# combination on top of the gate-epilogue reschedule: attention V-staging above the table wait, GEMM1 plain-tile trace (+local DCE), merge and gate epilogue loads above the alignment barrier, 64-bit acc
# speedup vs baseline: 1.0081x; 1.0044x over previous
;     __device__ bool next(int i, Unit& u) const { const bool ok = StaticOrder::next(i >> 2, u); u.sub = i & 3; return ok; }
; template <class Epi, class Sched, class Gemm, bool ALIGN_EPI = false, bool SP2 = false>
; __device__ __forceinline__ void gemm_phase(PG8_LAS unsigned char* lds, const Gemm g, const Sched& S, const Epi& E) {
;     ...
;         const bool has_next = S.next(ui + 1, nxt);
;         const char* nA = has_next ? (const char*)g.A + (size_t)nxt.pm * tstepA + (size_t)nxt.sub * g.a_sub : cA; const char* nB = has_next ? (const char*)g.Bt + (size_t)nxt.pn * tstepB + (size_t)nxt.sub * g.b_sub : cB;
;         for (int t = 0; t < nt; t += 2) {
;             const bool last = (t == nt - 2);
;             const char* a1 = cA + (size_t)(t + 1) * kstep;
;             const char* a2 = last ? nA : cA + (size_t)(t + 2) * kstep; const char* b2 = last ? nB : cB + (size_t)(t + 2) * kstep;
;     ...
;         if constexpr (!epi_chain<Epi>::value) {
; #pragma unroll
;         for (int a = 0; a < 2; ++a)
; #pragma unroll
;             for (int b = 0; b < 2; ++b)
; #pragma unroll
;                 for (int m = 0; m < 4; ++m)
; #pragma unroll
;                     for (int n = 0; n < 2; ++n) acc[a][b][m][n] = (f32x4){0.f, 0.f, 0.f, 0.f};
;         }
.LBB0_134:
	s_ashr_i32 s43, s42, 31
	s_lshl_b64 s[44:45], s[42:43], 18
	s_add_u32 s44, s60, s44
	s_addc_u32 s45, s61, s45
	s_and_b64 s[46:47], s[4:5], exec
	s_cselect_b32 s7, s45, s3
	s_cselect_b32 s43, s44, s2
	s_ashr_i32 s41, s40, 31
	s_lshl_b64 s[46:47], s[40:41], 18
	s_add_u32 s46, s62, s46
	s_addc_u32 s47, s63, s47
	s_and_b64 s[50:51], s[4:5], exec
	s_cselect_b32 s79, s47, s49
	s_cselect_b32 s80, s46, s48
	s_lshl_b32 s33, s0, 8
	s_lshl_b32 s41, s6, 8
	v_or_b32_e32 v18, s41, v252
	v_or_b32_e32 v20, s70, v1
	s_add_u32 s81, s48, 0x100
	v_ashrrev_i32_e32 v19, 31, v18
	v_add_u32_e32 v20, s33, v20
	s_addc_u32 s82, s49, 0
	v_ashrrev_i32_e32 v21, 31, v20
	v_lshl_add_u64 v[238:239], v[18:19], 2, s[34:35]
	s_add_u32 s48, s2, 0x20080
	v_mov_b32_e32 v18, 0
	v_lshl_add_u64 v[240:241], v[20:21], 2, s[30:31]
	s_addc_u32 s49, s3, 0
	s_mov_b32 s2, -2
	v_mov_b32_e32 v19, v18
	v_mov_b64_e32 v[20:21], 0
	v_mov_b64_e32 v[22:23], 0
	v_mov_b64_e32 v[24:25], 0
	v_mov_b64_e32 v[34:35], 0
	v_mov_b64_e32 v[36:37], 0
	v_mov_b64_e32 v[38:39], 0
	v_mov_b64_e32 v[40:41], 0
	v_mov_b64_e32 v[50:51], 0
	v_mov_b64_e32 v[52:53], 0
	v_mov_b64_e32 v[54:55], 0
	v_mov_b64_e32 v[56:57], 0
	v_mov_b64_e32 v[66:67], 0
	v_mov_b64_e32 v[68:69], 0
	v_mov_b64_e32 v[70:71], 0
	v_mov_b64_e32 v[72:73], 0
	v_mov_b64_e32 v[26:27], 0
	v_mov_b64_e32 v[28:29], 0
	v_mov_b64_e32 v[30:31], 0
	v_mov_b64_e32 v[32:33], 0
	v_mov_b64_e32 v[42:43], 0
	v_mov_b64_e32 v[44:45], 0
	v_mov_b64_e32 v[46:47], 0
	v_mov_b64_e32 v[48:49], 0
	v_mov_b64_e32 v[58:59], 0
	v_mov_b64_e32 v[60:61], 0
	v_mov_b64_e32 v[62:63], 0
	v_mov_b64_e32 v[64:65], 0
	v_mov_b64_e32 v[74:75], 0
	v_mov_b64_e32 v[76:77], 0
	v_mov_b64_e32 v[78:79], 0
	v_mov_b64_e32 v[80:81], 0
	v_mov_b64_e32 v[82:83], 0
	v_mov_b64_e32 v[84:85], 0
	v_mov_b64_e32 v[86:87], 0
	v_mov_b64_e32 v[88:89], 0
	v_mov_b64_e32 v[98:99], 0
	v_mov_b64_e32 v[100:101], 0
	v_mov_b64_e32 v[102:103], 0
	v_mov_b64_e32 v[104:105], 0
	v_mov_b64_e32 v[114:115], 0
	v_mov_b64_e32 v[116:117], 0
	v_mov_b64_e32 v[118:119], 0
	v_mov_b64_e32 v[120:121], 0
	v_mov_b64_e32 v[130:131], 0
	v_mov_b64_e32 v[132:133], 0
	v_mov_b64_e32 v[134:135], 0
	v_mov_b64_e32 v[136:137], 0
	v_mov_b64_e32 v[90:91], 0
	v_mov_b64_e32 v[92:93], 0
	v_mov_b64_e32 v[94:95], 0
	v_mov_b64_e32 v[96:97], 0
	v_mov_b64_e32 v[106:107], 0
	v_mov_b64_e32 v[108:109], 0
	v_mov_b64_e32 v[110:111], 0
	v_mov_b64_e32 v[112:113], 0
	v_mov_b64_e32 v[122:123], 0
	v_mov_b64_e32 v[124:125], 0
	v_mov_b64_e32 v[126:127], 0
	v_mov_b64_e32 v[128:129], 0
	v_mov_b64_e32 v[138:139], 0
	v_mov_b64_e32 v[140:141], 0
	v_mov_b64_e32 v[142:143], 0
	v_mov_b64_e32 v[144:145], 0
	s_nop 0
	s_branch .LBB0_136

; __device__ __forceinline__ unsigned cvt_pk_bf16(float lo, float hi) { return ::pk2(lo, hi); }
;     __device__ __forceinline__ void operator()(const f32x4 (&acc)[2][2][4][2], const Pre& p, const Unit& u, int wr, int wc, int fr, int fq) const {
;         asm volatile("" : "+v"(fr), "+v"(fq));
;         const int row0 = u.pm * BM + wr * 64 + fr, col0 = u.pn * BM + wc * 32 + 8 * fq;
;         const bool glu = (u.pn * BM >= ZB) && (u.pn * BM < ZQ);
; #pragma unroll
;         for (int ai = 0; ai < 2; ++ai)
; #pragma unroll
;             for (int m = 0; m < 4; ++m) { bf16_t* rowp = O + (size_t)(row0 + ai * HALF + m * 16) * ldc;
;                 const float rs = p.rs[ai * 4 + m];
; #pragma unroll
;                 for (int bj = 0; bj < 2; ++bj) {
;                     const f32x4 v0 = (__builtin_convertvector(__builtin_bit_cast(i32x4, acc[ai][bj][m][0]), f32x4) * p.wv[bj][0]) * rs, v1 = (__builtin_convertvector(__builtin_bit_cast(i32x4, acc[ai][bj][m][1]), f32x4) * p.wv[bj][1]) * rs;
;                     if (glu) {
;                         const float o0 = v0[0] * __builtin_amdgcn_rcpf(1.f + __builtin_amdgcn_exp2f(v0[1] * -1.44269504f)), o1 = v0[2] * __builtin_amdgcn_rcpf(1.f + __builtin_amdgcn_exp2f(v0[3] * -1.44269504f));
;                         const float o2 = v1[0] * __builtin_amdgcn_rcpf(1.f + __builtin_amdgcn_exp2f(v1[1] * -1.44269504f)), o3 = v1[2] * __builtin_amdgcn_rcpf(1.f + __builtin_amdgcn_exp2f(v1[3] * -1.44269504f));
;                         u32x2 w; w.x = cvt_pk_bf16(o0, o1); w.y = cvt_pk_bf16(o2, o3);
;                         *(u32x2*)(rowp + ZB + ((col0 + bj * HALF - ZB) >> 1)) = w;
;                     } else {
;                         u32x4 w; w.x = cvt_pk_bf16(v0[0], v0[1]); w.y = cvt_pk_bf16(v0[2], v0[3]); w.z = cvt_pk_bf16(v1[0], v1[1]); w.w = cvt_pk_bf16(v1[2], v1[3]);
;                         *(u32x4*)(rowp + col0 + bj * HALF) = w; } } }
;     }
.Lg1plain_0:
	v_cvt_pk_bf16_f32 v156, v148, v149
	v_cvt_pk_bf16_f32 v157, v140, v141
	v_cvt_pk_bf16_f32 v158, v150, v151
	v_cvt_pk_bf16_f32 v159, v152, v153
	global_store_dwordx4 v[144:145], v[156:159], off
	s_mov_b64 s[2:3], 0
	v_add_u32_e32 v138, 0xffffff00, v146
	v_ashrrev_i32_e32 v138, 1, v138
	v_ashrrev_i32_e32 v139, 31, v138
	v_cvt_f32_i32_e32 v135, v135
	v_cvt_f32_i32_e32 v134, v134
	v_cvt_f32_i32_e32 v137, v137
	v_cvt_f32_i32_e32 v136, v136
	v_cvt_f32_i32_e32 v151, v133
	v_cvt_f32_i32_e32 v150, v132
	v_cvt_f32_i32_e32 v149, v131
	v_cvt_f32_i32_e32 v148, v130
	v_mov_b32_e32 v227, v226
	v_pk_mul_f32 v[134:135], v[14:15], v[134:135]
	v_pk_mul_f32 v[136:137], v[16:17], v[136:137]
	v_mov_b32_e32 v140, v226
	v_mov_b32_e32 v141, v226
	v_pk_mul_f32 v[132:133], v[134:135], v[226:227]
	v_pk_mul_f32 v[134:135], v[12:13], v[150:151]
	v_pk_mul_f32 v[130:131], v[136:137], v[140:141]
	v_pk_mul_f32 v[148:149], v[10:11], v[148:149]
	v_pk_mul_f32 v[136:137], v[134:135], v[140:141]
	v_cndmask_b32_e64 v140, 0, 1, s[0:1]
	v_pk_mul_f32 v[134:135], v[148:149], v[226:227]
	v_cmp_ne_u32_e64 s[6:7], 1, v140
	v_cvt_pk_bf16_f32 v148, v132, v133
	v_cvt_pk_bf16_f32 v149, v130, v131
	v_cvt_pk_bf16_f32 v150, v134, v135
	v_cvt_pk_bf16_f32 v151, v136, v137
	global_store_dwordx4 v[144:145], v[148:151], off offset:256
	v_add_u32_e32 v140, 0xffffff80, v146
	v_cvt_f32_i32_e32 v135, v129
	v_cvt_f32_i32_e32 v134, v128
	v_add_u32_e32 v136, 16, v154
	v_mov_b64_e32 v[130:131], s[28:29]
	v_cvt_f32_i32_e32 v133, v127
	v_cvt_f32_i32_e32 v132, v126
	v_mad_i64_i32 v[126:127], s[0:1], v136, s78, v[130:131]
	v_pk_mul_f32 v[130:131], v[8:9], v[134:135]
	v_cvt_f32_i32_e32 v135, v123
	v_cvt_f32_i32_e32 v137, v125
	v_cvt_f32_i32_e32 v136, v124
	v_cvt_f32_i32_e32 v134, v122
	v_pk_mul_f32 v[132:133], v[6:7], v[132:133]
	v_pk_mul_f32 v[122:123], v[130:131], v[228:229] op_sel_hi:[1,0]
	v_pk_mul_f32 v[130:131], v[4:5], v[136:137]
	v_pk_mul_f32 v[134:135], v[2:3], v[134:135]
	v_lshl_add_u64 v[128:129], v[146:147], 1, v[126:127]
	v_pk_mul_f32 v[124:125], v[132:133], v[228:229] op_sel_hi:[1,0]
	v_pk_mul_f32 v[132:133], v[130:131], v[228:229] op_sel_hi:[1,0]
	v_pk_mul_f32 v[130:131], v[134:135], v[228:229] op_sel_hi:[1,0]
	v_cvt_pk_bf16_f32 v134, v124, v125
	v_cvt_pk_bf16_f32 v135, v122, v123
	v_cvt_pk_bf16_f32 v136, v130, v131
	v_cvt_pk_bf16_f32 v137, v132, v133
	global_store_dwordx4 v[128:129], v[134:137], off
	v_cvt_f32_i32_e32 v119, v119
	v_cvt_f32_i32_e32 v118, v118
	v_cvt_f32_i32_e32 v121, v121
	v_cvt_f32_i32_e32 v120, v120
	v_cvt_f32_i32_e32 v125, v115
	v_cvt_f32_i32_e32 v131, v117
	v_cvt_f32_i32_e32 v130, v116
	v_cvt_f32_i32_e32 v124, v114
	v_mov_b32_e32 v229, v228
	v_pk_mul_f32 v[118:119], v[14:15], v[118:119]
	v_pk_mul_f32 v[120:121], v[16:17], v[120:121]
	v_mov_b32_e32 v122, v228
	v_mov_b32_e32 v123, v228
	v_pk_mul_f32 v[116:117], v[118:119], v[228:229]
	v_pk_mul_f32 v[118:119], v[12:13], v[130:131]
	v_pk_mul_f32 v[124:125], v[10:11], v[124:125]
	v_pk_mul_f32 v[114:115], v[120:121], v[122:123]
	v_pk_mul_f32 v[120:121], v[118:119], v[122:123]
	v_pk_mul_f32 v[118:119], v[124:125], v[228:229]
	v_cvt_pk_bf16_f32 v122, v116, v117
	v_cvt_pk_bf16_f32 v123, v114, v115
	v_cvt_pk_bf16_f32 v124, v118, v119
	v_cvt_pk_bf16_f32 v125, v120, v121
	global_store_dwordx4 v[128:129], v[122:125], off offset:256
	v_cvt_f32_i32_e32 v119, v113
	v_cvt_f32_i32_e32 v118, v112
	v_add_u32_e32 v120, 32, v154
	v_mov_b64_e32 v[114:115], s[28:29]
	v_cvt_f32_i32_e32 v117, v111
	v_cvt_f32_i32_e32 v116, v110
	v_mad_i64_i32 v[110:111], s[0:1], v120, s78, v[114:115]
	v_pk_mul_f32 v[114:115], v[8:9], v[118:119]
	v_cvt_f32_i32_e32 v119, v107
	v_cvt_f32_i32_e32 v121, v109
	v_cvt_f32_i32_e32 v120, v108
	v_cvt_f32_i32_e32 v118, v106
	v_pk_mul_f32 v[116:117], v[6:7], v[116:117]
	v_pk_mul_f32 v[106:107], v[114:115], v[230:231] op_sel_hi:[1,0]
	v_pk_mul_f32 v[114:115], v[4:5], v[120:121]
	v_pk_mul_f32 v[118:119], v[2:3], v[118:119]
	v_lshl_add_u64 v[112:113], v[146:147], 1, v[110:111]
	v_pk_mul_f32 v[108:109], v[116:117], v[230:231] op_sel_hi:[1,0]
	v_pk_mul_f32 v[116:117], v[114:115], v[230:231] op_sel_hi:[1,0]
	v_pk_mul_f32 v[114:115], v[118:119], v[230:231] op_sel_hi:[1,0]
	v_cvt_pk_bf16_f32 v118, v108, v109
	v_cvt_pk_bf16_f32 v119, v106, v107
	v_cvt_pk_bf16_f32 v120, v114, v115
	v_cvt_pk_bf16_f32 v121, v116, v117
	global_store_dwordx4 v[112:113], v[118:121], off
	v_cvt_f32_i32_e32 v103, v103
	v_cvt_f32_i32_e32 v102, v102
	v_cvt_f32_i32_e32 v105, v105
	v_cvt_f32_i32_e32 v104, v104
	v_cvt_f32_i32_e32 v109, v99
	v_cvt_f32_i32_e32 v115, v101
	v_cvt_f32_i32_e32 v114, v100
	v_cvt_f32_i32_e32 v108, v98
	v_mov_b32_e32 v231, v230
	v_pk_mul_f32 v[102:103], v[14:15], v[102:103]
	v_pk_mul_f32 v[104:105], v[16:17], v[104:105]
	v_mov_b32_e32 v106, v230
	v_mov_b32_e32 v107, v230
	v_pk_mul_f32 v[100:101], v[102:103], v[230:231]
	v_pk_mul_f32 v[102:103], v[12:13], v[114:115]
	v_pk_mul_f32 v[108:109], v[10:11], v[108:109]
	v_pk_mul_f32 v[98:99], v[104:105], v[106:107]
	v_pk_mul_f32 v[104:105], v[102:103], v[106:107]
	v_pk_mul_f32 v[102:103], v[108:109], v[230:231]
	v_cvt_pk_bf16_f32 v106, v100, v101
	v_cvt_pk_bf16_f32 v107, v98, v99
	v_cvt_pk_bf16_f32 v108, v102, v103
	v_cvt_pk_bf16_f32 v109, v104, v105
	global_store_dwordx4 v[112:113], v[106:109], off offset:256
	v_cvt_f32_i32_e32 v103, v97
	v_cvt_f32_i32_e32 v102, v96
	v_add_u32_e32 v104, 48, v154
	v_mov_b64_e32 v[98:99], s[28:29]
	v_cvt_f32_i32_e32 v101, v95
	v_cvt_f32_i32_e32 v100, v94
	v_mad_i64_i32 v[94:95], s[0:1], v104, s78, v[98:99]
	v_pk_mul_f32 v[98:99], v[8:9], v[102:103]
	v_cvt_f32_i32_e32 v103, v91
	v_cvt_f32_i32_e32 v105, v93
	v_cvt_f32_i32_e32 v104, v92
	v_cvt_f32_i32_e32 v102, v90
; __device__ __forceinline__ unsigned cvt_pk_bf16(float lo, float hi) { return ::pk2(lo, hi); }
;     __device__ __forceinline__ void operator()(const f32x4 (&acc)[2][2][4][2], const Pre& p, const Unit& u, int wr, int wc, int fr, int fq) const {
;         asm volatile("" : "+v"(fr), "+v"(fq));
;         const int row0 = u.pm * BM + wr * 64 + fr, col0 = u.pn * BM + wc * 32 + 8 * fq;
;         const bool glu = (u.pn * BM >= ZB) && (u.pn * BM < ZQ);
; #pragma unroll
;         for (int ai = 0; ai < 2; ++ai)
; #pragma unroll
;             for (int m = 0; m < 4; ++m) { bf16_t* rowp = O + (size_t)(row0 + ai * HALF + m * 16) * ldc;
;                 const float rs = p.rs[ai * 4 + m];
; #pragma unroll
;                 for (int bj = 0; bj < 2; ++bj) {
;                     const f32x4 v0 = (__builtin_convertvector(__builtin_bit_cast(i32x4, acc[ai][bj][m][0]), f32x4) * p.wv[bj][0]) * rs, v1 = (__builtin_convertvector(__builtin_bit_cast(i32x4, acc[ai][bj][m][1]), f32x4) * p.wv[bj][1]) * rs;
;                     if (glu) {
;                         const float o0 = v0[0] * __builtin_amdgcn_rcpf(1.f + __builtin_amdgcn_exp2f(v0[1] * -1.44269504f)), o1 = v0[2] * __builtin_amdgcn_rcpf(1.f + __builtin_amdgcn_exp2f(v0[3] * -1.44269504f));
;                         const float o2 = v1[0] * __builtin_amdgcn_rcpf(1.f + __builtin_amdgcn_exp2f(v1[1] * -1.44269504f)), o3 = v1[2] * __builtin_amdgcn_rcpf(1.f + __builtin_amdgcn_exp2f(v1[3] * -1.44269504f));
;                         u32x2 w; w.x = cvt_pk_bf16(o0, o1); w.y = cvt_pk_bf16(o2, o3);
;                         *(u32x2*)(rowp + ZB + ((col0 + bj * HALF - ZB) >> 1)) = w;
;                     } else {
;                         u32x4 w; w.x = cvt_pk_bf16(v0[0], v0[1]); w.y = cvt_pk_bf16(v0[2], v0[3]); w.z = cvt_pk_bf16(v1[0], v1[1]); w.w = cvt_pk_bf16(v1[2], v1[3]);
;                         *(u32x4*)(rowp + col0 + bj * HALF) = w; } } }
;     }
	v_pk_mul_f32 v[100:101], v[6:7], v[100:101]
	v_pk_mul_f32 v[90:91], v[98:99], v[232:233] op_sel_hi:[1,0]
	v_pk_mul_f32 v[98:99], v[4:5], v[104:105]
	v_pk_mul_f32 v[102:103], v[2:3], v[102:103]
	v_lshl_add_u64 v[96:97], v[146:147], 1, v[94:95]
	v_pk_mul_f32 v[92:93], v[100:101], v[232:233] op_sel_hi:[1,0]
	v_pk_mul_f32 v[100:101], v[98:99], v[232:233] op_sel_hi:[1,0]
	v_pk_mul_f32 v[98:99], v[102:103], v[232:233] op_sel_hi:[1,0]
	v_cvt_pk_bf16_f32 v102, v92, v93
	v_cvt_pk_bf16_f32 v103, v90, v91
	v_cvt_pk_bf16_f32 v104, v98, v99
	v_cvt_pk_bf16_f32 v105, v100, v101
	global_store_dwordx4 v[96:97], v[102:105], off
	v_cvt_f32_i32_e32 v87, v87
	v_cvt_f32_i32_e32 v86, v86
	v_cvt_f32_i32_e32 v89, v89
	v_cvt_f32_i32_e32 v88, v88
	v_cvt_f32_i32_e32 v93, v83
	v_cvt_f32_i32_e32 v99, v85
	v_cvt_f32_i32_e32 v98, v84
	v_cvt_f32_i32_e32 v92, v82
	v_mov_b32_e32 v233, v232
	v_pk_mul_f32 v[86:87], v[14:15], v[86:87]
	v_pk_mul_f32 v[88:89], v[16:17], v[88:89]
	v_mov_b32_e32 v90, v232
	v_mov_b32_e32 v91, v232
	v_pk_mul_f32 v[84:85], v[86:87], v[232:233]
	v_pk_mul_f32 v[86:87], v[12:13], v[98:99]
	v_pk_mul_f32 v[92:93], v[10:11], v[92:93]
	v_pk_mul_f32 v[82:83], v[88:89], v[90:91]
	v_pk_mul_f32 v[88:89], v[86:87], v[90:91]
	v_pk_mul_f32 v[86:87], v[92:93], v[232:233]
	v_cvt_pk_bf16_f32 v90, v84, v85
	v_cvt_pk_bf16_f32 v91, v82, v83
	v_cvt_pk_bf16_f32 v92, v86, v87
	v_cvt_pk_bf16_f32 v93, v88, v89
	global_store_dwordx4 v[96:97], v[90:93], off offset:256
	v_cvt_f32_i32_e32 v87, v81
	v_cvt_f32_i32_e32 v86, v80
	v_add_u32_e32 v88, 0x80, v154
	v_mov_b64_e32 v[82:83], s[28:29]
	v_cvt_f32_i32_e32 v85, v79
	v_cvt_f32_i32_e32 v84, v78
	v_mad_i64_i32 v[78:79], s[0:1], v88, s78, v[82:83]
	v_pk_mul_f32 v[82:83], v[8:9], v[86:87]
	v_cvt_f32_i32_e32 v87, v75
	v_cvt_f32_i32_e32 v89, v77
	v_cvt_f32_i32_e32 v88, v76
	v_cvt_f32_i32_e32 v86, v74
	v_pk_mul_f32 v[84:85], v[6:7], v[84:85]
	v_pk_mul_f32 v[74:75], v[82:83], v[234:235] op_sel_hi:[1,0]
	v_pk_mul_f32 v[82:83], v[4:5], v[88:89]
	v_pk_mul_f32 v[86:87], v[2:3], v[86:87]
	v_lshl_add_u64 v[80:81], v[146:147], 1, v[78:79]
	v_pk_mul_f32 v[76:77], v[84:85], v[234:235] op_sel_hi:[1,0]
	v_pk_mul_f32 v[84:85], v[82:83], v[234:235] op_sel_hi:[1,0]
	v_pk_mul_f32 v[82:83], v[86:87], v[234:235] op_sel_hi:[1,0]
	v_cvt_pk_bf16_f32 v86, v76, v77
	v_cvt_pk_bf16_f32 v87, v74, v75
	v_cvt_pk_bf16_f32 v88, v82, v83
	v_cvt_pk_bf16_f32 v89, v84, v85
	global_store_dwordx4 v[80:81], v[86:89], off
	v_cvt_f32_i32_e32 v71, v71
	v_cvt_f32_i32_e32 v70, v70
	v_cvt_f32_i32_e32 v73, v73
	v_cvt_f32_i32_e32 v72, v72
	v_cvt_f32_i32_e32 v83, v67
	v_cvt_f32_i32_e32 v85, v69
	v_cvt_f32_i32_e32 v84, v68
	v_cvt_f32_i32_e32 v82, v66
	v_mov_b32_e32 v74, v234
	v_mov_b32_e32 v75, v234
	v_pk_mul_f32 v[70:71], v[14:15], v[70:71]
	v_pk_mul_f32 v[72:73], v[16:17], v[72:73]
	v_mov_b32_e32 v76, v234
	v_mov_b32_e32 v77, v234
	v_pk_mul_f32 v[68:69], v[70:71], v[74:75]
	v_pk_mul_f32 v[70:71], v[12:13], v[84:85]
	v_pk_mul_f32 v[82:83], v[10:11], v[82:83]
	v_pk_mul_f32 v[66:67], v[72:73], v[76:77]
	v_pk_mul_f32 v[72:73], v[70:71], v[76:77]
	v_pk_mul_f32 v[70:71], v[82:83], v[74:75]
	v_cvt_pk_bf16_f32 v74, v68, v69
	v_cvt_pk_bf16_f32 v75, v66, v67
	v_cvt_pk_bf16_f32 v76, v70, v71
	v_cvt_pk_bf16_f32 v77, v72, v73
	global_store_dwordx4 v[80:81], v[74:77], off offset:256
	v_cvt_f32_i32_e32 v71, v65
	v_cvt_f32_i32_e32 v70, v64
	v_add_u32_e32 v72, 0x90, v154
	v_mov_b64_e32 v[66:67], s[28:29]
	v_cvt_f32_i32_e32 v69, v63
	v_cvt_f32_i32_e32 v68, v62
	v_mad_i64_i32 v[62:63], s[0:1], v72, s78, v[66:67]
	v_pk_mul_f32 v[66:67], v[8:9], v[70:71]
	v_cvt_f32_i32_e32 v71, v59
	v_cvt_f32_i32_e32 v73, v61
	v_cvt_f32_i32_e32 v72, v60
	v_cvt_f32_i32_e32 v70, v58
	v_pk_mul_f32 v[68:69], v[6:7], v[68:69]
	v_pk_mul_f32 v[58:59], v[66:67], v[234:235] op_sel:[0,1]
	v_pk_mul_f32 v[66:67], v[4:5], v[72:73]
	v_pk_mul_f32 v[70:71], v[2:3], v[70:71]
	v_lshl_add_u64 v[64:65], v[146:147], 1, v[62:63]
	v_pk_mul_f32 v[60:61], v[68:69], v[234:235] op_sel:[0,1]
	v_pk_mul_f32 v[68:69], v[66:67], v[234:235] op_sel:[0,1]
	v_pk_mul_f32 v[66:67], v[70:71], v[234:235] op_sel:[0,1]
	v_cvt_pk_bf16_f32 v70, v60, v61
	v_cvt_pk_bf16_f32 v71, v58, v59
	v_cvt_pk_bf16_f32 v72, v66, v67
	v_cvt_pk_bf16_f32 v73, v68, v69
	global_store_dwordx4 v[64:65], v[70:73], off
	v_cvt_f32_i32_e32 v55, v55
	v_cvt_f32_i32_e32 v54, v54
	v_cvt_f32_i32_e32 v57, v57
	v_cvt_f32_i32_e32 v56, v56
	v_cvt_f32_i32_e32 v67, v51
	v_cvt_f32_i32_e32 v69, v53
	v_cvt_f32_i32_e32 v68, v52
; __device__ __forceinline__ unsigned cvt_pk_bf16(float lo, float hi) { return ::pk2(lo, hi); }
;     __device__ __forceinline__ void operator()(const f32x4 (&acc)[2][2][4][2], const Pre& p, const Unit& u, int wr, int wc, int fr, int fq) const {
;         asm volatile("" : "+v"(fr), "+v"(fq));
;         const int row0 = u.pm * BM + wr * 64 + fr, col0 = u.pn * BM + wc * 32 + 8 * fq;
;         const bool glu = (u.pn * BM >= ZB) && (u.pn * BM < ZQ);
; #pragma unroll
;         for (int ai = 0; ai < 2; ++ai)
; #pragma unroll
;             for (int m = 0; m < 4; ++m) { bf16_t* rowp = O + (size_t)(row0 + ai * HALF + m * 16) * ldc;
;                 const float rs = p.rs[ai * 4 + m];
; #pragma unroll
;                 for (int bj = 0; bj < 2; ++bj) {
;                     const f32x4 v0 = (__builtin_convertvector(__builtin_bit_cast(i32x4, acc[ai][bj][m][0]), f32x4) * p.wv[bj][0]) * rs, v1 = (__builtin_convertvector(__builtin_bit_cast(i32x4, acc[ai][bj][m][1]), f32x4) * p.wv[bj][1]) * rs;
;                     if (glu) {
;                         const float o0 = v0[0] * __builtin_amdgcn_rcpf(1.f + __builtin_amdgcn_exp2f(v0[1] * -1.44269504f)), o1 = v0[2] * __builtin_amdgcn_rcpf(1.f + __builtin_amdgcn_exp2f(v0[3] * -1.44269504f));
;                         const float o2 = v1[0] * __builtin_amdgcn_rcpf(1.f + __builtin_amdgcn_exp2f(v1[1] * -1.44269504f)), o3 = v1[2] * __builtin_amdgcn_rcpf(1.f + __builtin_amdgcn_exp2f(v1[3] * -1.44269504f));
;                         u32x2 w; w.x = cvt_pk_bf16(o0, o1); w.y = cvt_pk_bf16(o2, o3);
;                         *(u32x2*)(rowp + ZB + ((col0 + bj * HALF - ZB) >> 1)) = w;
;                     } else {
;                         u32x4 w; w.x = cvt_pk_bf16(v0[0], v0[1]); w.y = cvt_pk_bf16(v0[2], v0[3]); w.z = cvt_pk_bf16(v1[0], v1[1]); w.w = cvt_pk_bf16(v1[2], v1[3]);
;                         *(u32x4*)(rowp + col0 + bj * HALF) = w; } } }
;     }
	v_cvt_f32_i32_e32 v66, v50
	v_mov_b32_e32 v58, v235
	v_mov_b32_e32 v59, v235
	v_pk_mul_f32 v[54:55], v[14:15], v[54:55]
	v_pk_mul_f32 v[56:57], v[16:17], v[56:57]
	v_mov_b32_e32 v60, v235
	v_mov_b32_e32 v61, v235
	v_pk_mul_f32 v[52:53], v[54:55], v[58:59]
	v_pk_mul_f32 v[54:55], v[12:13], v[68:69]
	v_pk_mul_f32 v[66:67], v[10:11], v[66:67]
	v_pk_mul_f32 v[50:51], v[56:57], v[60:61]
	v_pk_mul_f32 v[56:57], v[54:55], v[60:61]
	v_pk_mul_f32 v[54:55], v[66:67], v[58:59]
	v_cvt_pk_bf16_f32 v58, v52, v53
	v_cvt_pk_bf16_f32 v59, v50, v51
	v_cvt_pk_bf16_f32 v60, v54, v55
	v_cvt_pk_bf16_f32 v61, v56, v57
	global_store_dwordx4 v[64:65], v[58:61], off offset:256
	v_cvt_f32_i32_e32 v55, v49
	v_cvt_f32_i32_e32 v54, v48
	v_add_u32_e32 v56, 0xa0, v154
	v_mov_b64_e32 v[50:51], s[28:29]
	v_cvt_f32_i32_e32 v53, v47
	v_cvt_f32_i32_e32 v52, v46
	v_mad_i64_i32 v[46:47], s[0:1], v56, s78, v[50:51]
	v_pk_mul_f32 v[50:51], v[8:9], v[54:55]
	v_cvt_f32_i32_e32 v55, v43
	v_cvt_f32_i32_e32 v57, v45
	v_cvt_f32_i32_e32 v56, v44
	v_cvt_f32_i32_e32 v54, v42
	v_pk_mul_f32 v[52:53], v[6:7], v[52:53]
	v_pk_mul_f32 v[42:43], v[50:51], v[236:237] op_sel_hi:[1,0]
	v_pk_mul_f32 v[50:51], v[4:5], v[56:57]
	v_pk_mul_f32 v[54:55], v[2:3], v[54:55]
	v_lshl_add_u64 v[48:49], v[146:147], 1, v[46:47]
	v_pk_mul_f32 v[44:45], v[52:53], v[236:237] op_sel_hi:[1,0]
	v_pk_mul_f32 v[52:53], v[50:51], v[236:237] op_sel_hi:[1,0]
	v_pk_mul_f32 v[50:51], v[54:55], v[236:237] op_sel_hi:[1,0]
	v_cvt_pk_bf16_f32 v54, v44, v45
	v_cvt_pk_bf16_f32 v55, v42, v43
	v_cvt_pk_bf16_f32 v56, v50, v51
	v_cvt_pk_bf16_f32 v57, v52, v53
	global_store_dwordx4 v[48:49], v[54:57], off
	v_cvt_f32_i32_e32 v39, v39
	v_cvt_f32_i32_e32 v38, v38
	v_cvt_f32_i32_e32 v41, v41
	v_cvt_f32_i32_e32 v40, v40
	v_cvt_f32_i32_e32 v51, v35
	v_cvt_f32_i32_e32 v53, v37
	v_cvt_f32_i32_e32 v52, v36
	v_cvt_f32_i32_e32 v50, v34
	v_mov_b32_e32 v42, v236
	v_mov_b32_e32 v43, v236
	v_pk_mul_f32 v[38:39], v[14:15], v[38:39]
	v_pk_mul_f32 v[40:41], v[16:17], v[40:41]
	v_mov_b32_e32 v44, v236
	v_mov_b32_e32 v45, v236
	v_pk_mul_f32 v[36:37], v[38:39], v[42:43]
	v_pk_mul_f32 v[38:39], v[12:13], v[52:53]
	v_pk_mul_f32 v[50:51], v[10:11], v[50:51]
	v_pk_mul_f32 v[34:35], v[40:41], v[44:45]
	v_pk_mul_f32 v[40:41], v[38:39], v[44:45]
	v_pk_mul_f32 v[38:39], v[50:51], v[42:43]
	v_cvt_pk_bf16_f32 v42, v36, v37
	v_cvt_pk_bf16_f32 v43, v34, v35
	v_cvt_pk_bf16_f32 v44, v38, v39
	v_cvt_pk_bf16_f32 v45, v40, v41
	global_store_dwordx4 v[48:49], v[42:45], off offset:256
	v_add_u32_e32 v40, 0xb0, v154
	v_mov_b64_e32 v[34:35], s[28:29]
	v_cvt_f32_i32_e32 v39, v33
	v_cvt_f32_i32_e32 v38, v32
	v_cvt_f32_i32_e32 v37, v31
	v_cvt_f32_i32_e32 v36, v30
	v_mad_i64_i32 v[30:31], s[0:1], v40, s78, v[34:35]
	v_cvt_f32_i32_e32 v41, v27
	v_cvt_f32_i32_e32 v43, v29
	v_cvt_f32_i32_e32 v42, v28
	v_cvt_f32_i32_e32 v40, v26
	v_pk_mul_f32 v[34:35], v[8:9], v[38:39]
	v_mov_b32_e32 v38, v237
	v_pk_mul_f32 v[36:37], v[6:7], v[36:37]
	v_pk_mul_f32 v[26:27], v[34:35], v[38:39] op_sel_hi:[1,0]
	v_pk_mul_f32 v[34:35], v[4:5], v[42:43]
	v_pk_mul_f32 v[40:41], v[2:3], v[40:41]
	v_lshl_add_u64 v[32:33], v[146:147], 1, v[30:31]
	v_pk_mul_f32 v[28:29], v[36:37], v[38:39] op_sel_hi:[1,0]
	v_pk_mul_f32 v[36:37], v[34:35], v[38:39] op_sel_hi:[1,0]
	v_pk_mul_f32 v[34:35], v[40:41], v[38:39] op_sel_hi:[1,0]
	v_cvt_pk_bf16_f32 v38, v28, v29
	v_cvt_pk_bf16_f32 v39, v26, v27
	v_cvt_pk_bf16_f32 v40, v34, v35
	v_cvt_pk_bf16_f32 v41, v36, v37
	global_store_dwordx4 v[32:33], v[38:41], off
	v_cvt_f32_i32_e32 v23, v23
	v_cvt_f32_i32_e32 v22, v22
	v_cvt_f32_i32_e32 v25, v25
	v_cvt_f32_i32_e32 v24, v24
	v_cvt_f32_i32_e32 v35, v19
	v_cvt_f32_i32_e32 v37, v21
	v_cvt_f32_i32_e32 v36, v20
	v_cvt_f32_i32_e32 v34, v18
	v_mov_b32_e32 v26, v237
	v_mov_b32_e32 v27, v237
	v_pk_mul_f32 v[22:23], v[14:15], v[22:23]
	v_pk_mul_f32 v[24:25], v[16:17], v[24:25]
	v_mov_b32_e32 v28, v237
	v_mov_b32_e32 v29, v237
	v_pk_mul_f32 v[20:21], v[22:23], v[26:27]
	v_pk_mul_f32 v[22:23], v[12:13], v[36:37]
	v_pk_mul_f32 v[34:35], v[10:11], v[34:35]
	v_pk_mul_f32 v[18:19], v[24:25], v[28:29]
	v_pk_mul_f32 v[24:25], v[22:23], v[28:29]
	v_pk_mul_f32 v[22:23], v[34:35], v[26:27]
	s_and_b64 vcc, exec, s[6:7]
	s_mov_b64 s[0:1], -1
	v_cvt_pk_bf16_f32 v26, v20, v21
	v_cvt_pk_bf16_f32 v27, v18, v19
	v_cvt_pk_bf16_f32 v28, v22, v23
	v_cvt_pk_bf16_f32 v29, v24, v25
	global_store_dwordx4 v[32:33], v[26:29], off offset:256
	s_nop 0
	s_branch .Lg1join_0

; __device__ __forceinline__ void attn_phase_mfma(const Ctx& c, unsigned char* lds_raw, bool do_store) {
;     ...
;     ATT_PREFETCH(u);
;     for (;;) {
;         ATT_TABLES(u);
;         asm volatile("" ::: "memory");
;         const AttnU A = attn_decode(u);
;     ...
;         const int iq = i0 + 32 * wave + rq, posq = r + d * iq;
;         const size_t tokq = (size_t)b * SEQ + posq;
;         bf16_t* qrow = c.Z + tokq * DIN + ZQ + hh * 64;
;         bf16x8 qf[4];
;         {
;             const u32x4 q0 = qn[0], q1 = qn[1], q2 = qn[2], q3 = qn[3];
;             const h16x8 cav = tq[0], cbv = tq[1], sav = tq[2], sbv = tq[3];
;             const float sc = 0.125f * 1.44269504f;
;             u32x4 o0, o1, o2, o3;
;     #pragma unroll
;             for (int e = 0; e < 4; ++e) {
;                 const float ca_0 = (float)cav[2 * e], ca_1 = (float)cav[2 * e + 1], sa_0 = (float)sav[2 * e], sa_1 = (float)sav[2 * e + 1];
;                 const float cb_0 = (float)cbv[2 * e], cb_1 = (float)cbv[2 * e + 1], sb_0 = (float)sbv[2 * e], sb_1 = (float)sbv[2 * e + 1];
;                 const float a0 = bflo(q0[e]), a1 = bfhi(q0[e]), b0 = bflo(q2[e]), b1 = bfhi(q2[e]);
;                 const float e0 = bflo(q1[e]), e1 = bfhi(q1[e]), f0 = bflo(q3[e]), f1 = bfhi(q3[e]);
;                 o0[e] = pk2((a0 * ca_0 - b0 * sa_0) * sc, (a1 * ca_1 - b1 * sa_1) * sc);
;                 o2[e] = pk2((b0 * ca_0 + a0 * sa_0) * sc, (b1 * ca_1 + a1 * sa_1) * sc);
;                 o1[e] = pk2((e0 * cb_0 - f0 * sb_0) * sc, (e1 * cb_1 - f1 * sb_1) * sc);
;                 o3[e] = pk2((f0 * cb_0 + e0 * sb_0) * sc, (f1 * cb_1 + e1 * sb_1) * sc);
;             }
;             qf[0] = __builtin_bit_cast(bf16x8, o0); qf[1] = __builtin_bit_cast(bf16x8, o1); qf[2] = __builtin_bit_cast(bf16x8, o2); qf[3] = __builtin_bit_cast(bf16x8, o3);
;         }
; #pragma unroll
;         for (int i = 0; i < 3; ++i) {
;             const int id = t + 512 * i, row = id >> 2, dc = id & 3;
;             const h16x8 kcv = tkc[i], ksv = tks[i];
;             u32x4 olo, ohi;
; #pragma unroll
;             for (int e = 0; e < 4; ++e) {
;                 const float l0 = bflo(ka[i][e]), l1 = bfhi(ka[i][e]), h0 = bflo(kb2[i][e]), h1 = bfhi(kb2[i][e]);
;                 const float cc0 = (float)kcv[2 * e], cc1 = (float)kcv[2 * e + 1], ss0 = (float)ksv[2 * e], ss1 = (float)ksv[2 * e + 1];
.LBB0_359:
	s_mul_hi_i32 s0, s33, 0x2aaaaaab
	s_lshr_b32 s1, s0, 31
	s_ashr_i32 s0, s0, 5
	s_add_i32 s90, s0, s1
	s_mul_i32 s0, s90, 0xffffff40
	s_add_i32 s91, s33, s0
	s_ashr_i32 s88, s91, 6
	s_lshl_b32 s96, s88, 1
	s_lshr_b32 s1, 16, s96
	s_and_b32 s0, s91, 15
	s_sub_i32 s2, 4, s96
	s_add_i32 s1, s1, -1
	s_lshr_b32 s2, s0, s2
	s_and_b32 s0, s1, s0
	s_lshl_b32 s9, s0, 8
	s_sub_i32 s89, s9, 64
	v_add_u32_e32 v18, s9, v180
	v_add_u32_e32 v34, s89, v1
	v_lshlrev_b32_e32 v18, s96, v18
	v_lshlrev_b32_e32 v34, s96, v34
	v_add_u32_e32 v58, s2, v18
	v_add_u32_e32 v34, s2, v34
	v_lshlrev_b32_e32 v18, 6, v58
	v_med3_i32 v34, v34, 0, v221
	v_ashrrev_i32_e32 v19, 31, v18
	v_lshlrev_b32_e32 v34, 7, v34
	v_mov_b32_e32 v35, v106
	v_lshl_add_u64 v[18:19], v[18:19], 1, v[170:171]
	v_lshl_add_u64 v[34:35], v[172:173], 0, v[34:35]
	global_load_dwordx4 v[30:33], v[18:19], off
	global_load_dwordx4 v[22:25], v[18:19], off offset:32
	global_load_dwordx4 v[26:29], v[18:19], off offset:64
	s_nop 0
	global_load_dwordx4 v[18:21], v[18:19], off offset:96
	s_nop 0
	global_load_dwordx4 v[54:57], v[34:35], off
	global_load_dwordx4 v[50:53], v[34:35], off offset:64
	v_add_u32_e32 v34, s89, v176
	v_lshlrev_b32_e32 v34, s96, v34
	v_add_u32_e32 v34, s2, v34
	v_med3_i32 v34, v34, 0, v221
	v_lshlrev_b32_e32 v34, 7, v34
	v_mov_b32_e32 v35, v106
	v_lshl_add_u64 v[34:35], v[172:173], 0, v[34:35]
	global_load_dwordx4 v[46:49], v[34:35], off
	global_load_dwordx4 v[42:45], v[34:35], off offset:64
	v_add_u32_e32 v34, s89, v178
	v_lshlrev_b32_e32 v34, s96, v34
	v_add_u32_e32 v34, s2, v34
	v_med3_i32 v34, v34, 0, v221
	v_lshlrev_b32_e32 v34, 7, v34
	v_mov_b32_e32 v35, v106
	v_lshl_add_u64 v[34:35], v[172:173], 0, v[34:35]
	global_load_dwordx4 v[38:41], v[34:35], off
	s_nop 0
	global_load_dwordx4 v[34:37], v[34:35], off offset:64
	v_lshlrev_b32_e32 v62, 16, v86
	v_and_b32_e32 v63, 0xffff0000, v86
	v_lshlrev_b32_e32 v60, 16, v90
	v_and_b32_e32 v61, 0xffff0000, v90
	v_readlane_b32 s0, v255, 12
	s_add_i32 s33, s33, s0
	s_cmpk_gt_i32 s33, 0x5ff
	v_perm_b32 v250, v94, v82, s6
	v_perm_b32 v251, v94, v82, s7
	v_add_u32_e32 v252, 0xc000, v181
	ds_write2_b32 v252, v250, v251 offset1:194
	v_perm_b32 v250, v95, v83, s6
	v_perm_b32 v251, v95, v83, s7
	v_add_u32_e32 v252, 0xc600, v181
	ds_write2_b32 v252, v250, v251 offset0:4 offset1:198
	v_perm_b32 v250, v96, v84, s6
	v_perm_b32 v251, v96, v84, s7
	v_add_u32_e32 v252, 0xcc00, v181
	ds_write2_b32 v252, v250, v251 offset0:8 offset1:202
	v_perm_b32 v250, v97, v85, s6
	v_perm_b32 v251, v97, v85, s7
	v_add_u32_e32 v252, 0xd200, v181
	ds_write2_b32 v252, v250, v251 offset0:12 offset1:206
	v_perm_b32 v250, v114, v110, s6
	v_perm_b32 v251, v114, v110, s7
	v_add_u32_e32 v252, 0xc800, v182
	ds_write2_b32 v252, v250, v251 offset1:194
	v_perm_b32 v250, v115, v111, s6
	v_perm_b32 v251, v115, v111, s7
	v_add_u32_e32 v252, 0xce00, v182
	ds_write2_b32 v252, v250, v251 offset0:4 offset1:198
	v_perm_b32 v250, v116, v112, s6
	v_perm_b32 v251, v116, v112, s7
	v_add_u32_e32 v252, 0xd400, v182
	ds_write2_b32 v252, v250, v251 offset0:8 offset1:202
	v_perm_b32 v250, v117, v113, s6
	v_perm_b32 v251, v117, v113, s7
	v_add_u32_e32 v252, 0xda00, v182
	ds_write2_b32 v252, v250, v251 offset0:12 offset1:206
	v_perm_b32 v250, v146, v126, s6
	v_perm_b32 v251, v146, v126, s7
	v_add_u32_e32 v252, 0xd000, v183
	ds_write2_b32 v252, v250, v251 offset1:194
	v_perm_b32 v250, v147, v127, s6
	v_perm_b32 v251, v147, v127, s7
	v_add_u32_e32 v252, 0xd600, v183
	ds_write2_b32 v252, v250, v251 offset0:4 offset1:198
	v_perm_b32 v250, v148, v128, s6
	v_perm_b32 v251, v148, v128, s7
	v_add_u32_e32 v252, 0xdc00, v183
	ds_write2_b32 v252, v250, v251 offset0:8 offset1:202
	v_perm_b32 v250, v149, v129, s6
	v_perm_b32 v251, v149, v129, s7
	v_add_u32_e32 v252, 0xe200, v183
	ds_write2_b32 v252, v250, v251 offset0:12 offset1:206
	s_waitcnt vmcnt(5)
	v_cvt_f32_f16_e32 v64, v54
	s_waitcnt vmcnt(4)
	v_cvt_f32_f16_e32 v66, v50
	v_cvt_f32_f16_sdwa v67, v50 dst_sel:DWORD dst_unused:UNUSED_PAD src0_sel:WORD_1
	v_cvt_f32_f16_sdwa v65, v54 dst_sel:DWORD dst_unused:UNUSED_PAD src0_sel:WORD_1
	v_pk_mul_f32 v[68:69], v[62:63], v[66:67]
	s_nop 0
	v_pk_fma_f32 v[68:69], v[60:61], v[64:65], v[68:69] neg_lo:[0,0,1] neg_hi:[0,0,1]
	v_pk_mul_f32 v[60:61], v[60:61], v[66:67]
	v_cvt_f32_f16_e32 v66, v51
	v_cvt_f32_f16_sdwa v67, v51 dst_sel:DWORD dst_unused:UNUSED_PAD src0_sel:WORD_1
	v_pk_fma_f32 v[60:61], v[62:63], v[64:65], v[60:61]
	v_cvt_f32_f16_e32 v64, v55
	v_cvt_f32_f16_sdwa v65, v55 dst_sel:DWORD dst_unused:UNUSED_PAD src0_sel:WORD_1
	v_lshlrev_b32_e32 v62, 16, v87
	v_and_b32_e32 v63, 0xffff0000, v87
	v_cvt_pk_bf16_f32 v50, v68, v69
	v_cvt_pk_bf16_f32 v54, v60, v61
	v_lshlrev_b32_e32 v60, 16, v91
	v_and_b32_e32 v61, 0xffff0000, v91
	v_pk_mul_f32 v[68:69], v[62:63], v[66:67]
	s_nop 0
	v_pk_fma_f32 v[68:69], v[60:61], v[64:65], v[68:69] neg_lo:[0,0,1] neg_hi:[0,0,1]
	v_pk_mul_f32 v[60:61], v[60:61], v[66:67]
	v_cvt_f32_f16_e32 v66, v52
	v_cvt_f32_f16_sdwa v67, v52 dst_sel:DWORD dst_unused:UNUSED_PAD src0_sel:WORD_1
	v_pk_fma_f32 v[60:61], v[62:63], v[64:65], v[60:61]
	v_cvt_f32_f16_e32 v64, v56
	v_cvt_f32_f16_sdwa v65, v56 dst_sel:DWORD dst_unused:UNUSED_PAD src0_sel:WORD_1
	v_lshlrev_b32_e32 v62, 16, v88
	v_and_b32_e32 v63, 0xffff0000, v88
	v_cvt_pk_bf16_f32 v51, v68, v69
	v_cvt_pk_bf16_f32 v55, v60, v61
	v_lshlrev_b32_e32 v60, 16, v92
	v_and_b32_e32 v61, 0xffff0000, v92
	v_pk_mul_f32 v[68:69], v[62:63], v[66:67]
	s_nop 0
	v_pk_fma_f32 v[68:69], v[60:61], v[64:65], v[68:69] neg_lo:[0,0,1] neg_hi:[0,0,1]
	v_pk_mul_f32 v[60:61], v[60:61], v[66:67]
	v_cvt_f32_f16_e32 v66, v53
	v_cvt_f32_f16_sdwa v67, v53 dst_sel:DWORD dst_unused:UNUSED_PAD src0_sel:WORD_1
	v_pk_fma_f32 v[60:61], v[62:63], v[64:65], v[60:61]
	v_cvt_f32_f16_e32 v64, v57
	v_cvt_f32_f16_sdwa v65, v57 dst_sel:DWORD dst_unused:UNUSED_PAD src0_sel:WORD_1
	v_lshlrev_b32_e32 v62, 16, v89
	v_and_b32_e32 v63, 0xffff0000, v89
	v_cvt_pk_bf16_f32 v52, v68, v69
	v_cvt_pk_bf16_f32 v56, v60, v61
	v_lshlrev_b32_e32 v60, 16, v93
	v_and_b32_e32 v61, 0xffff0000, v93
	v_pk_mul_f32 v[68:69], v[62:63], v[66:67]
	s_nop 0
	v_pk_fma_f32 v[68:69], v[60:61], v[64:65], v[68:69] neg_lo:[0,0,1] neg_hi:[0,0,1]
	v_pk_mul_f32 v[60:61], v[60:61], v[66:67]
	v_cvt_pk_bf16_f32 v53, v68, v69
	v_pk_fma_f32 v[60:61], v[62:63], v[64:65], v[60:61]
	s_nop 0
	v_cvt_pk_bf16_f32 v57, v60, v61
	ds_write_b128 v210, v[50:53]
	ds_write_b128 v211, v[54:57]
	s_waitcnt vmcnt(2)
; __device__ __forceinline__ float bflo(unsigned w) { return __uint_as_float(w << 16); }
; __device__ __forceinline__ float bfhi(unsigned w) { return __uint_as_float(w & 0xffff0000u); }
; __device__ __forceinline__ unsigned pk2(float lo, float hi) { const f32x2n v = {lo, hi}; return __builtin_bit_cast(unsigned, __builtin_convertvector(v, bf16x2n)); }
; #define LASP __attribute__((address_space(3)))
; __device__ __forceinline__ void attn_phase_mfma(const Ctx& c, unsigned char* lds_raw, bool do_store) {
;     ...
; #pragma unroll
;         for (int i = 0; i < 3; ++i) {
;             const int id = t + 512 * i, row = id >> 2, dc = id & 3;
;             const h16x8 kcv = tkc[i], ksv = tks[i];
;             u32x4 olo, ohi;
; #pragma unroll
;             for (int e = 0; e < 4; ++e) {
;                 const float l0 = bflo(ka[i][e]), l1 = bfhi(ka[i][e]), h0 = bflo(kb2[i][e]), h1 = bfhi(kb2[i][e]);
;                 const float cc0 = (float)kcv[2 * e], cc1 = (float)kcv[2 * e + 1], ss0 = (float)ksv[2 * e], ss1 = (float)ksv[2 * e + 1];
;                 olo[e] = pk2(l0 * cc0 - h0 * ss0, l1 * cc1 - h1 * ss1);
;                 ohi[e] = pk2(h0 * cc0 + l0 * ss0, h1 * cc1 + l1 * ss1);
;             }
;             *(LASP u32x4*)(Kt + row * 128 + ((dc ^ (row & 7)) << 4)) = olo;
;             *(LASP u32x4*)(Kt + row * 128 + (((4 + dc) ^ (row & 7)) << 4)) = ohi;
;             const int rp = id % 192, dc8 = id / 192;
; #pragma unroll
;             for (int e = 0; e < 4; ++e) {
;                 Vt[(8 * dc8 + 2 * e) * 194 + rp] = __builtin_amdgcn_perm(vb[i][e], va[i][e], 0x05040100u);
;                 Vt[(8 * dc8 + 2 * e + 1) * 194 + rp] = __builtin_amdgcn_perm(vb[i][e], va[i][e], 0x07060302u);
;             }
;         }
;         __syncthreads();
	v_cvt_f32_f16_e32 v56, v42
	v_cvt_f32_f16_sdwa v57, v42 dst_sel:DWORD dst_unused:UNUSED_PAD src0_sel:WORD_1
	v_cvt_f32_f16_e32 v54, v46
	v_cvt_f32_f16_sdwa v55, v46 dst_sel:DWORD dst_unused:UNUSED_PAD src0_sel:WORD_1
	v_lshlrev_b32_e32 v52, 16, v98
	v_and_b32_e32 v53, 0xffff0000, v98
	v_lshlrev_b32_e32 v50, 16, v102
	v_and_b32_e32 v51, 0xffff0000, v102
	v_pk_mul_f32 v[60:61], v[52:53], v[56:57]
	s_nop 0
	v_pk_fma_f32 v[60:61], v[50:51], v[54:55], v[60:61] neg_lo:[0,0,1] neg_hi:[0,0,1]
	v_pk_mul_f32 v[50:51], v[50:51], v[56:57]
	v_cvt_f32_f16_e32 v56, v43
	v_cvt_f32_f16_sdwa v57, v43 dst_sel:DWORD dst_unused:UNUSED_PAD src0_sel:WORD_1
	v_pk_fma_f32 v[50:51], v[52:53], v[54:55], v[50:51]
	v_cvt_f32_f16_e32 v54, v47
	v_cvt_f32_f16_sdwa v55, v47 dst_sel:DWORD dst_unused:UNUSED_PAD src0_sel:WORD_1
	v_lshlrev_b32_e32 v52, 16, v99
	v_and_b32_e32 v53, 0xffff0000, v99
	v_cvt_pk_bf16_f32 v42, v60, v61
	v_cvt_pk_bf16_f32 v46, v50, v51
	v_lshlrev_b32_e32 v50, 16, v103
	v_and_b32_e32 v51, 0xffff0000, v103
	v_pk_mul_f32 v[60:61], v[52:53], v[56:57]
	s_nop 0
	v_pk_fma_f32 v[60:61], v[50:51], v[54:55], v[60:61] neg_lo:[0,0,1] neg_hi:[0,0,1]
	v_pk_mul_f32 v[50:51], v[50:51], v[56:57]
	v_cvt_f32_f16_e32 v56, v44
	v_cvt_f32_f16_sdwa v57, v44 dst_sel:DWORD dst_unused:UNUSED_PAD src0_sel:WORD_1
	v_pk_fma_f32 v[50:51], v[52:53], v[54:55], v[50:51]
	v_cvt_f32_f16_e32 v54, v48
	v_cvt_f32_f16_sdwa v55, v48 dst_sel:DWORD dst_unused:UNUSED_PAD src0_sel:WORD_1
	v_lshlrev_b32_e32 v52, 16, v100
	v_and_b32_e32 v53, 0xffff0000, v100
	v_cvt_pk_bf16_f32 v43, v60, v61
	v_cvt_pk_bf16_f32 v47, v50, v51
	v_lshlrev_b32_e32 v50, 16, v104
	v_and_b32_e32 v51, 0xffff0000, v104
	v_pk_mul_f32 v[60:61], v[52:53], v[56:57]
	s_nop 0
	v_pk_fma_f32 v[60:61], v[50:51], v[54:55], v[60:61] neg_lo:[0,0,1] neg_hi:[0,0,1]
	v_pk_mul_f32 v[50:51], v[50:51], v[56:57]
	v_cvt_f32_f16_e32 v56, v45
	v_cvt_f32_f16_sdwa v57, v45 dst_sel:DWORD dst_unused:UNUSED_PAD src0_sel:WORD_1
	v_pk_fma_f32 v[50:51], v[52:53], v[54:55], v[50:51]
	v_cvt_f32_f16_e32 v54, v49
	v_cvt_f32_f16_sdwa v55, v49 dst_sel:DWORD dst_unused:UNUSED_PAD src0_sel:WORD_1
	v_lshlrev_b32_e32 v52, 16, v101
	v_and_b32_e32 v53, 0xffff0000, v101
	v_cvt_pk_bf16_f32 v44, v60, v61
	v_cvt_pk_bf16_f32 v48, v50, v51
	v_lshlrev_b32_e32 v50, 16, v105
	v_and_b32_e32 v51, 0xffff0000, v105
	v_pk_mul_f32 v[60:61], v[52:53], v[56:57]
	s_nop 0
	v_pk_fma_f32 v[60:61], v[50:51], v[54:55], v[60:61] neg_lo:[0,0,1] neg_hi:[0,0,1]
	v_pk_mul_f32 v[50:51], v[50:51], v[56:57]
	v_cvt_pk_bf16_f32 v45, v60, v61
	v_pk_fma_f32 v[50:51], v[52:53], v[54:55], v[50:51]
	s_nop 0
	v_cvt_pk_bf16_f32 v49, v50, v51
	ds_write_b128 v212, v[42:45]
	ds_write_b128 v213, v[46:49]
	s_waitcnt vmcnt(0)
	v_cvt_f32_f16_e32 v48, v34
	v_cvt_f32_f16_sdwa v49, v34 dst_sel:DWORD dst_unused:UNUSED_PAD src0_sel:WORD_1
	v_cvt_f32_f16_e32 v46, v38
	v_cvt_f32_f16_sdwa v47, v38 dst_sel:DWORD dst_unused:UNUSED_PAD src0_sel:WORD_1
	v_lshlrev_b32_e32 v44, 16, v118
	v_and_b32_e32 v45, 0xffff0000, v118
	v_lshlrev_b32_e32 v42, 16, v122
	v_and_b32_e32 v43, 0xffff0000, v122
	v_pk_mul_f32 v[50:51], v[44:45], v[48:49]
	s_nop 0
	v_pk_fma_f32 v[50:51], v[42:43], v[46:47], v[50:51] neg_lo:[0,0,1] neg_hi:[0,0,1]
	v_pk_mul_f32 v[42:43], v[42:43], v[48:49]
	v_cvt_f32_f16_e32 v48, v35
	v_cvt_f32_f16_sdwa v49, v35 dst_sel:DWORD dst_unused:UNUSED_PAD src0_sel:WORD_1
	v_pk_fma_f32 v[42:43], v[44:45], v[46:47], v[42:43]
	v_cvt_f32_f16_e32 v46, v39
	v_cvt_f32_f16_sdwa v47, v39 dst_sel:DWORD dst_unused:UNUSED_PAD src0_sel:WORD_1
	v_lshlrev_b32_e32 v44, 16, v119
	v_and_b32_e32 v45, 0xffff0000, v119
	v_cvt_pk_bf16_f32 v34, v50, v51
	v_cvt_pk_bf16_f32 v38, v42, v43
	v_lshlrev_b32_e32 v42, 16, v123
	v_and_b32_e32 v43, 0xffff0000, v123
	v_pk_mul_f32 v[50:51], v[44:45], v[48:49]
	s_nop 0
	v_pk_fma_f32 v[50:51], v[42:43], v[46:47], v[50:51] neg_lo:[0,0,1] neg_hi:[0,0,1]
	v_pk_mul_f32 v[42:43], v[42:43], v[48:49]
	v_cvt_f32_f16_e32 v48, v36
	v_cvt_f32_f16_sdwa v49, v36 dst_sel:DWORD dst_unused:UNUSED_PAD src0_sel:WORD_1
	v_pk_fma_f32 v[42:43], v[44:45], v[46:47], v[42:43]
	v_cvt_f32_f16_e32 v46, v40
	v_cvt_f32_f16_sdwa v47, v40 dst_sel:DWORD dst_unused:UNUSED_PAD src0_sel:WORD_1
	v_lshlrev_b32_e32 v44, 16, v120
	v_and_b32_e32 v45, 0xffff0000, v120
	v_cvt_pk_bf16_f32 v35, v50, v51
	v_cvt_pk_bf16_f32 v39, v42, v43
	v_lshlrev_b32_e32 v42, 16, v124
	v_and_b32_e32 v43, 0xffff0000, v124
	v_pk_mul_f32 v[50:51], v[44:45], v[48:49]
	s_nop 0
	v_pk_fma_f32 v[50:51], v[42:43], v[46:47], v[50:51] neg_lo:[0,0,1] neg_hi:[0,0,1]
	v_pk_mul_f32 v[42:43], v[42:43], v[48:49]
	v_cvt_f32_f16_e32 v48, v37
	v_cvt_f32_f16_sdwa v49, v37 dst_sel:DWORD dst_unused:UNUSED_PAD src0_sel:WORD_1
	v_pk_fma_f32 v[42:43], v[44:45], v[46:47], v[42:43]
	v_cvt_f32_f16_e32 v46, v41
	v_cvt_f32_f16_sdwa v47, v41 dst_sel:DWORD dst_unused:UNUSED_PAD src0_sel:WORD_1
	v_lshlrev_b32_e32 v44, 16, v121
	v_and_b32_e32 v45, 0xffff0000, v121
	v_cvt_pk_bf16_f32 v36, v50, v51
	v_cvt_pk_bf16_f32 v40, v42, v43
	v_lshlrev_b32_e32 v42, 16, v125
	v_and_b32_e32 v43, 0xffff0000, v125
	v_pk_mul_f32 v[50:51], v[44:45], v[48:49]
	s_nop 0
	v_pk_fma_f32 v[50:51], v[42:43], v[46:47], v[50:51] neg_lo:[0,0,1] neg_hi:[0,0,1]
	v_pk_mul_f32 v[42:43], v[42:43], v[48:49]
	v_cvt_pk_bf16_f32 v37, v50, v51
	v_pk_fma_f32 v[42:43], v[44:45], v[46:47], v[42:43]
	s_nop 0
	v_cvt_pk_bf16_f32 v41, v42, v43
	ds_write_b128 v214, v[34:37]
	ds_write_b128 v215, v[38:41]
	s_waitcnt lgkmcnt(0)
	s_barrier
; __device__ __forceinline__ void attn_phase_mfma(const Ctx& c, unsigned char* lds_raw, bool do_store) {
;     ...
;         const int un = u + G;
;         if (un < NAT) ATT_PREFETCH(un);
	s_cbranch_scc1 .LBB0_379
	s_mul_hi_i32 s0, s33, 0x2aaaaaab
	s_lshr_b32 s1, s0, 31
	s_ashr_i32 s0, s0, 5
	s_add_i32 s0, s0, s1
	s_mul_i32 s1, s0, 0xffffff40
	s_add_i32 s1, s33, s1
	s_ashr_i32 s11, s1, 6
	s_lshl_b32 s10, s11, 1
	s_lshr_b32 s2, 16, s10
	s_and_b32 s1, s1, 15
	s_sub_i32 s3, 4, s10
	s_add_i32 s2, s2, -1
	s_lshr_b32 s12, s1, s3
	s_and_b32 s1, s2, s1
	s_lshl_b32 s13, s1, 8
	s_ashr_i32 s1, s0, 31
	v_add_u32_e32 v34, s13, v180
	s_lshl_b64 s[2:3], s[0:1], 12
	v_lshlrev_b32_e32 v34, s10, v34
	s_or_b32 s0, s2, s12
	s_mov_b32 s1, s3
	v_ashrrev_i32_e32 v35, 31, v34
	v_lshl_add_u64 v[34:35], s[0:1], 0, v[34:35]
	v_mov_b64_e32 v[36:37], s[92:93]
	v_mad_u64_u32 v[36:37], s[74:75], v34, s8, v[36:37]
	s_lshl_b32 s11, s11, 8
	s_and_b32 s74, s4, 0xc0
	s_or_b32 s94, s11, s74
	v_mad_i32_i24 v37, v35, s8, v37
	s_ashr_i32 s95, s94, 31
	v_lshl_add_u64 v[34:35], s[94:95], 1, v[36:37]
	v_mov_b32_e32 v169, v106
	v_lshl_add_u64 v[34:35], v[34:35], 0, v[168:169]
	global_load_dwordx4 v[142:145], v[34:35], off offset:1536
	global_load_dwordx4 v[138:141], v[34:35], off offset:1568
	global_load_dwordx4 v[134:137], v[34:35], off offset:1600
	global_load_dwordx4 v[130:133], v[34:35], off offset:1632
	s_sub_i32 s13, s13, 64
	s_lshr_b32 s11, 0x1000, s10
	v_add_u32_e32 v34, s13, v1
	v_mov_b32_e32 v84, v106
	v_mov_b32_e32 v85, v106
	v_cmp_lt_i32_e32 vcc, -1, v34
	v_cmp_gt_i32_e64 s[74:75], s11, v34
	v_mov_b32_e32 v82, v106
	v_mov_b32_e32 v83, v106
	v_mov_b64_e32 v[88:89], v[84:85]
	v_mov_b64_e32 v[92:93], v[84:85]
	s_and_b64 vcc, vcc, s[74:75]
	v_mov_b64_e32 v[86:87], v[82:83]
	v_mov_b64_e32 v[90:91], v[82:83]
	s_and_saveexec_b64 s[74:75], vcc
	s_cbranch_execz .LBB0_362
	v_lshlrev_b32_e32 v34, s10, v34
	v_add_u32_e32 v34, s12, v34
	v_mov_b32_e32 v35, v106
	v_lshl_add_u64 v[34:35], s[2:3], 0, v[34:35]
	v_mov_b64_e32 v[36:37], s[92:93]
	v_mad_u64_u32 v[36:37], vcc, v34, s8, v[36:37]
	v_mad_i32_i24 v37, v35, s8, v37
	v_lshl_add_u64 v[34:35], s[94:95], 1, v[36:37]
	v_mov_b32_e32 v159, v106
	v_lshl_add_u64 v[34:35], v[34:35], 0, v[158:159]
	global_load_dwordx4 v[90:93], v[34:35], off offset:3072
	global_load_dwordx4 v[86:89], v[34:35], off offset:3136

; template <class Epi, class Sched, class Gemm, bool ALIGN_EPI = false, bool SP2 = false>
; __device__ __forceinline__ void gemm_phase(PG8_LAS unsigned char* lds, const Gemm g, const Sched& S, const Epi& E) {
;     ...
; #pragma unroll
;     for (int a = 0; a < 2; ++a)
; #pragma unroll
;         for (int b = 0; b < 2; ++b)
; #pragma unroll
;             for (int m = 0; m < 4; ++m)
; #pragma unroll
;                 for (int n = 0; n < 2; ++n) acc[a][b][m][n] = (f32x4){0.f, 0.f, 0.f, 0.f};
;     bf16x8 At[4][2], B0[2][2], B1[2][2];
;     const char* cA = (const char*)g.A + (size_t)cur.pm * tstepA + (size_t)cur.sub * g.a_sub; const char* cB = (const char*)g.Bt + (size_t)cur.pn * tstepB + (size_t)cur.sub * g.b_sub;
;     S.a_ready(cur);
;     if constexpr (SP2) {
;         PG8_STAGE(PG8_SB(0, 0), cB, voffB); PG8_STAGE(PG8_SB(0, 1), cB + hB1, voffB1); PG8_STAGE(PG8_SA(0, 0), cA, voffA); PG8_STAGE(PG8_SA(0, 1), cA + hstepA, voffA);
;         if (wr == 1) PG8_BAR;
;         PG8_WAIT_V(2); PG8_BAR;
;         PG8_STAGE(PG8_SB(1, 0), cB + kstep, voffB); PG8_STAGE(PG8_SA(1, 0), cA + kstep, voffA); PG8_STAGE(PG8_SB(1, 1), cB + hB1 + kstep, voffB1);
;         PG8_WAIT_V(6); PG8_BAR;
;     } else {
;         PG8_STAGE(PG8_SB(0, 0), cB, voffB); PG8_STAGE(PG8_SA(0, 0), cA, voffA); PG8_STAGE(PG8_SB(0, 1), cB + hB1, voffB1); PG8_STAGE(PG8_SA(0, 1), cA + hstepA, voffA);
;         if (wr == 1) PG8_BAR;
;         PG8_WAIT_V(4); PG8_BAR;
;         PG8_STAGE(PG8_SB(1, 0), cB + kstep, voffB); PG8_STAGE(PG8_SA(1, 0), cA + kstep, voffA); PG8_STAGE(PG8_SB(1, 1), cB + hB1 + kstep, voffB1);
;         PG8_WAIT_V(6); PG8_BAR;
;     }
;     for (;;) {
;         const bool has_next = S.next(ui + 1, nxt);
;         const char* nA = has_next ? (const char*)g.A + (size_t)nxt.pm * tstepA + (size_t)nxt.sub * g.a_sub : cA; const char* nB = has_next ? (const char*)g.Bt + (size_t)nxt.pn * tstepB + (size_t)nxt.sub * g.b_sub : cB;
;         for (int t = 0; t < nt; t += 2) {
;             const bool last = (t == nt - 2);
;             const char* a1 = cA + (size_t)(t + 1) * kstep;
;             const char* a2 = last ? nA : cA + (size_t)(t + 2) * kstep; const char* b2 = last ? nB : cB + (size_t)(t + 2) * kstep;
;             const char* a3 = a2 + kstep; const char* b3 = b2 + kstep;
;             if (last && has_next) S.a_ready(nxt);
;             if constexpr (SP2) {
.LBB0_1191:
	s_ashr_i32 s31, s30, 31
	s_lshl_b64 s[34:35], s[30:31], 18
	s_add_u32 s34, s44, s34
	s_addc_u32 s35, s45, s35
	s_and_b64 s[36:37], s[4:5], exec
	s_cselect_b32 s31, s35, s3
	s_cselect_b32 s60, s34, s2
	s_ashr_i32 s29, s28, 31
	s_lshl_b64 s[36:37], s[28:29], 18
	s_add_u32 s36, s42, s36
	s_addc_u32 s37, s43, s37
	s_and_b64 s[40:41], s[4:5], exec
	s_cselect_b32 s29, s37, s1
	s_cselect_b32 s61, s36, s0
	s_add_u32 s62, s0, 0x100
	s_addc_u32 s63, s1, 0
	s_add_u32 s0, s2, 0x20080
	v_mov_b32_e32 v2, 0
	s_addc_u32 s1, s3, 0
	s_mov_b32 s64, -2
	v_mov_b32_e32 v3, v2
	v_mov_b32_e32 v4, v2
	v_mov_b32_e32 v5, v2
	v_mov_b32_e32 v6, v2
	v_mov_b32_e32 v7, v2
	v_mov_b32_e32 v8, v2
	v_mov_b32_e32 v9, v2
	s_waitcnt vmcnt(0)
	v_mov_b64_e32 v[18:19], 0
	v_mov_b64_e32 v[20:21], 0
	v_mov_b64_e32 v[22:23], 0
	v_mov_b64_e32 v[24:25], 0
	v_mov_b64_e32 v[34:35], 0
	v_mov_b64_e32 v[36:37], 0
	v_mov_b64_e32 v[38:39], 0
	v_mov_b64_e32 v[40:41], 0
	v_mov_b64_e32 v[50:51], 0
	v_mov_b64_e32 v[52:53], 0
	v_mov_b64_e32 v[54:55], 0
	v_mov_b64_e32 v[56:57], 0
	v_mov_b64_e32 v[10:11], 0
	v_mov_b64_e32 v[12:13], 0
	v_mov_b64_e32 v[14:15], 0
	v_mov_b64_e32 v[16:17], 0
	v_mov_b64_e32 v[26:27], 0
	v_mov_b64_e32 v[28:29], 0
	v_mov_b64_e32 v[30:31], 0
	v_mov_b64_e32 v[32:33], 0
	v_mov_b64_e32 v[42:43], 0
	v_mov_b64_e32 v[44:45], 0
	v_mov_b64_e32 v[46:47], 0
	v_mov_b64_e32 v[48:49], 0
	v_mov_b64_e32 v[58:59], 0
	v_mov_b64_e32 v[60:61], 0
	v_mov_b64_e32 v[62:63], 0
	v_mov_b64_e32 v[64:65], 0
	v_mov_b64_e32 v[66:67], 0
	v_mov_b64_e32 v[68:69], 0
	v_mov_b64_e32 v[70:71], 0
	v_mov_b64_e32 v[72:73], 0
	v_mov_b64_e32 v[82:83], 0
	v_mov_b64_e32 v[84:85], 0
	v_mov_b64_e32 v[86:87], 0
	v_mov_b64_e32 v[88:89], 0
	v_mov_b64_e32 v[98:99], 0
	v_mov_b64_e32 v[100:101], 0
	v_mov_b64_e32 v[102:103], 0
	v_mov_b64_e32 v[104:105], 0
	v_mov_b64_e32 v[114:115], 0
	v_mov_b64_e32 v[116:117], 0
	v_mov_b64_e32 v[118:119], 0
	v_mov_b64_e32 v[120:121], 0
	v_mov_b64_e32 v[74:75], 0
	v_mov_b64_e32 v[76:77], 0
	v_mov_b64_e32 v[78:79], 0
	v_mov_b64_e32 v[80:81], 0
	v_mov_b64_e32 v[90:91], 0
	v_mov_b64_e32 v[92:93], 0
	v_mov_b64_e32 v[94:95], 0
	v_mov_b64_e32 v[96:97], 0
	v_mov_b64_e32 v[106:107], 0
	v_mov_b64_e32 v[108:109], 0
	v_mov_b64_e32 v[110:111], 0
	v_mov_b64_e32 v[112:113], 0
	v_mov_b64_e32 v[122:123], 0
	v_mov_b64_e32 v[124:125], 0
	v_mov_b64_e32 v[126:127], 0
	v_mov_b64_e32 v[128:129], 0
.LBB0_1192:
	ds_read_b128 v[172:175], v183
	ds_read_b128 v[188:191], v183 offset:1024
	ds_read_b128 v[192:195], v183 offset:2048
	ds_read_b128 v[196:199], v183 offset:3072
	ds_read_b128 v[134:137], v185
	ds_read_b128 v[138:141], v185 offset:1024
	ds_read_b128 v[142:145], v185 offset:2048
	ds_read_b128 v[130:133], v185 offset:3072
	s_add_u32 s2, s0, 0xfffe0080
	s_addc_u32 s3, s1, -1
	s_cmp_eq_u32 s64, 4
	s_cselect_b32 s3, s31, s3
	s_cselect_b32 s2, s60, s2
	s_cselect_b32 s41, s29, s63
	s_cselect_b32 s40, s61, s62
	v_lshl_add_u64 v[160:161], s[0:1], 0, v[158:159]
	s_add_i32 m0, s39, 0xc000
	ds_read_b128 v[164:167], v187
	ds_read_b128 v[168:171], v187 offset:1024
	ds_read_b128 v[200:203], v187 offset:2048
	ds_read_b128 v[204:207], v187 offset:3072
	ds_read_b128 v[208:211], v187 offset:4096
	ds_read_b128 v[212:215], v187 offset:5120
	ds_read_b128 v[216:219], v187 offset:6144
	ds_read_b128 v[220:223], v187 offset:7168
	global_load_lds_dwordx4 v[160:161], off
	v_lshl_add_u64 v[160:161], s[0:1], 0, v[156:157]
	s_add_i32 m0, s39, 0xe000
	s_nop 0
	global_load_lds_dwordx4 v[160:161], off
	s_waitcnt vmcnt(8)
	s_waitcnt lgkmcnt(0)
	s_barrier
	s_setprio 1
	s_waitcnt lgkmcnt(0)
	v_mfma_i32_16x16x64_i8 v[224:227], v[172:175], v[164:167], v[126:129]
	v_mfma_i32_16x16x64_i8 v[126:129], v[188:191], v[168:171], v[224:227]
	v_mfma_i32_16x16x64_i8 v[228:231], v[192:195], v[164:167], v[122:125]
	v_mfma_i32_16x16x64_i8 v[232:235], v[172:175], v[200:203], v[110:113]
	v_mfma_i32_16x16x64_i8 v[236:239], v[192:195], v[200:203], v[106:109]
	v_mfma_i32_16x16x64_i8 v[240:243], v[172:175], v[208:211], v[94:97]
	v_mfma_i32_16x16x64_i8 v[244:247], v[192:195], v[208:211], v[90:93]
	v_mfma_i32_16x16x64_i8 v[224:227], v[172:175], v[216:219], v[78:81]
	v_mfma_i32_16x16x64_i8 v[74:77], v[192:195], v[216:219], v[74:77]
	v_mfma_i32_16x16x64_i8 v[122:125], v[196:199], v[168:171], v[228:231]
	v_mfma_i32_16x16x64_i8 v[110:113], v[188:191], v[204:207], v[232:235]
	v_mfma_i32_16x16x64_i8 v[106:109], v[196:199], v[204:207], v[236:239]
	v_mfma_i32_16x16x64_i8 v[94:97], v[188:191], v[212:215], v[240:243]
	v_mfma_i32_16x16x64_i8 v[90:93], v[196:199], v[212:215], v[244:247]
	v_mfma_i32_16x16x64_i8 v[78:81], v[188:191], v[220:223], v[224:227]
	v_mfma_i32_16x16x64_i8 v[74:77], v[196:199], v[220:223], v[74:77]
	s_setprio 0
	s_setprio 1
	v_mfma_i32_16x16x64_i8 v[224:227], v[134:137], v[164:167], v[118:121]
	v_mfma_i32_16x16x64_i8 v[118:121], v[138:141], v[168:171], v[224:227]
	v_mfma_i32_16x16x64_i8 v[228:231], v[142:145], v[164:167], v[114:117]
	v_mfma_i32_16x16x64_i8 v[232:235], v[134:137], v[200:203], v[102:105]
	v_mfma_i32_16x16x64_i8 v[236:239], v[142:145], v[200:203], v[98:101]
	v_mfma_i32_16x16x64_i8 v[240:243], v[134:137], v[208:211], v[86:89]
	v_mfma_i32_16x16x64_i8 v[244:247], v[142:145], v[208:211], v[82:85]
	v_mfma_i32_16x16x64_i8 v[164:167], v[134:137], v[216:219], v[70:73]
	v_mfma_i32_16x16x64_i8 v[66:69], v[142:145], v[216:219], v[66:69]
	v_mfma_i32_16x16x64_i8 v[114:117], v[130:133], v[168:171], v[228:231]
	v_mfma_i32_16x16x64_i8 v[102:105], v[138:141], v[204:207], v[232:235]
	v_mfma_i32_16x16x64_i8 v[98:101], v[130:133], v[204:207], v[236:239]
	v_mfma_i32_16x16x64_i8 v[86:89], v[138:141], v[212:215], v[240:243]
	v_mfma_i32_16x16x64_i8 v[82:85], v[130:133], v[212:215], v[244:247]
	v_mfma_i32_16x16x64_i8 v[70:73], v[138:141], v[220:223], v[164:167]
	v_mfma_i32_16x16x64_i8 v[66:69], v[130:133], v[220:223], v[66:69]
	s_setprio 0
	s_barrier
; #define PG8_STAGE(bufoff, gbase, voff) do { _Pragma("unroll") for (int _i = 0; _i < 2; ++_i) \
;         __builtin_amdgcn_global_load_lds((const unsigned*)((const char*)(gbase) + (voff)[_i]), (PG8_LAS unsigned*)(lds + (bufoff) + ldsw + _i * 8192), 16, 0, 0); } while (0)
; #define PG8_LDA(dst, b, h) do { _Pragma("unroll") for (int m = 0; m < 4; ++m) _Pragma("unroll") for (int k = 0; k < 2; ++k) dst[m][k] = *(const PG8_LAS bf16x8*)(lds + PG8_SA(b, h) + aoff + m * 2048 + k * 1024); } while (0)
; #define PG8_LDB(dst, b, h) do { _Pragma("unroll") for (int n = 0; n < 2; ++n) _Pragma("unroll") for (int k = 0; k < 2; ++k) dst[n][k] = *(const PG8_LAS bf16x8*)(lds + PG8_SB(b, h) + boff + n * 2048 + k * 1024); } while (0)
; #define PG8_MMA(ai, bj, At, Bt) do { __builtin_amdgcn_s_setprio(1); _Pragma("unroll") for (int m = 0; m < 4; ++m) _Pragma("unroll") for (int n = 0; n < 2; ++n) _Pragma("unroll") for (int k = 0; k < 2; ++k) \
;         acc[ai][bj][m][n] = Gemm::i8 ? ::mfma16i8_g(Bt[n][k], At[m][k], acc[ai][bj][m][n]) : ::mfma16_g(Bt[n][k], At[m][k], acc[ai][bj][m][n]); __builtin_amdgcn_s_setprio(0); } while (0)
; #define PG8_WAIT_V(n) asm volatile("s_waitcnt vmcnt(" #n ")" ::: "memory")
; #define PG8_BAR __builtin_amdgcn_s_barrier()
; template <class Epi, class Sched, class Gemm, bool ALIGN_EPI = false, bool SP2 = false>
; __device__ __forceinline__ void gemm_phase(PG8_LAS unsigned char* lds, const Gemm g, const Sched& S, const Epi& E) {
;     ...
;             if constexpr (SP2) {
;             PG8_LDB(B0, 0, 0); PG8_LDB(B1, 0, 1); PG8_SCHED; PG8_LDA(At, 0, 0); PG8_STAGE(PG8_SA(1, 1), a1 + hstepA, voffA);
;             PG8_WAIT_V(8); PG8_WAIT_L(0); PG8_BAR; PG8_MMA(0, 0, At, B0); PG8_MMA(0, 1, At, B1); PG8_BAR; PG8_SCHED;
;             PG8_LDA(At, 0, 1); PG8_STAGE(PG8_SB(0, 0), b2, voffB); PG8_STAGE(PG8_SB(0, 1), b2 + hB1, voffB1); PG8_STAGE(PG8_SA(0, 0), a2, voffA);
;             PG8_WAIT_V(8); PG8_WAIT_L(0); PG8_BAR; PG8_MMA(1, 0, At, B0); PG8_MMA(1, 1, At, B1); PG8_BAR; PG8_SCHED;
;             PG8_LDB(B0, 1, 0); PG8_LDB(B1, 1, 1); PG8_SCHED; PG8_LDA(At, 1, 0); PG8_STAGE(PG8_SA(0, 1), a2 + hstepA, voffA);
;             PG8_WAIT_V(8); PG8_WAIT_L(0); PG8_BAR; PG8_MMA(0, 0, At, B0); PG8_MMA(0, 1, At, B1); PG8_BAR; PG8_SCHED;
;             PG8_LDA(At, 1, 1); PG8_STAGE(PG8_SB(1, 0), b3, voffB); PG8_STAGE(PG8_SB(1, 1), b3 + hB1, voffB1); PG8_STAGE(PG8_SA(1, 0), a3, voffA);
	s_add_i32 s65, s55, s33
	v_lshl_add_u64 v[164:165], s[40:41], 0, v[148:149]
	s_mov_b32 m0, s65
	ds_read_b128 v[200:203], v187 offset:16384
	ds_read_b128 v[204:207], v187 offset:17408
	ds_read_b128 v[208:211], v187 offset:18432
	ds_read_b128 v[212:215], v187 offset:19456
	ds_read_b128 v[216:219], v187 offset:20480
	ds_read_b128 v[220:223], v187 offset:21504
	ds_read_b128 v[224:227], v187 offset:22528
	ds_read_b128 v[228:231], v187 offset:23552
	global_load_lds_dwordx4 v[164:165], off
	s_add_i32 m0, s65, 0x2000
	s_add_u32 s66, s40, 0x2000
	v_lshl_add_u64 v[166:167], s[40:41], 0, v[152:153]
	s_addc_u32 s67, s41, 0
	s_add_i32 s65, s56, s33
	global_load_lds_dwordx4 v[166:167], off
	v_lshl_add_u64 v[160:161], s[66:67], 0, v[148:149]
	s_mov_b32 m0, s65
	v_lshl_add_u64 v[168:169], s[2:3], 0, v[146:147]
	global_load_lds_dwordx4 v[160:161], off
	v_lshl_add_u64 v[160:161], s[66:67], 0, v[152:153]
	s_add_i32 m0, s65, 0x2000
	v_lshl_add_u64 v[170:171], s[2:3], 0, v[150:151]
	global_load_lds_dwordx4 v[160:161], off
	s_mov_b32 m0, s39
	s_nop 0
	global_load_lds_dwordx4 v[168:169], off
	s_mov_b32 m0, s46
	s_nop 0
	global_load_lds_dwordx4 v[170:171], off
	s_waitcnt vmcnt(8)
	s_waitcnt lgkmcnt(0)
	s_barrier
	s_setprio 1
	s_waitcnt lgkmcnt(0)
	v_mfma_i32_16x16x64_i8 v[232:235], v[172:175], v[200:203], v[62:65]
	v_mfma_i32_16x16x64_i8 v[62:65], v[188:191], v[204:207], v[232:235]
	v_mfma_i32_16x16x64_i8 v[236:239], v[192:195], v[200:203], v[58:61]
	v_mfma_i32_16x16x64_i8 v[240:243], v[172:175], v[208:211], v[46:49]
	v_mfma_i32_16x16x64_i8 v[244:247], v[192:195], v[208:211], v[42:45]
	v_mfma_i32_16x16x64_i8 v[248:251], v[172:175], v[216:219], v[30:33]
	v_mfma_i32_16x16x64_i8 v[160:163], v[192:195], v[216:219], v[26:29]
	v_mfma_i32_16x16x64_i8 v[232:235], v[172:175], v[224:227], v[14:17]
	v_mfma_i32_16x16x64_i8 v[10:13], v[192:195], v[224:227], v[10:13]
	v_mfma_i32_16x16x64_i8 v[58:61], v[196:199], v[204:207], v[236:239]
	v_mfma_i32_16x16x64_i8 v[46:49], v[188:191], v[212:215], v[240:243]
	v_mfma_i32_16x16x64_i8 v[42:45], v[196:199], v[212:215], v[244:247]
	v_mfma_i32_16x16x64_i8 v[30:33], v[188:191], v[220:223], v[248:251]
	v_mfma_i32_16x16x64_i8 v[26:29], v[196:199], v[220:223], v[160:163]
	v_mfma_i32_16x16x64_i8 v[14:17], v[188:191], v[228:231], v[232:235]
	v_mfma_i32_16x16x64_i8 v[10:13], v[196:199], v[228:231], v[10:13]
	s_setprio 0
	s_setprio 1
	v_mfma_i32_16x16x64_i8 v[160:163], v[134:137], v[200:203], v[54:57]
	v_mfma_i32_16x16x64_i8 v[54:57], v[138:141], v[204:207], v[160:163]
	v_mfma_i32_16x16x64_i8 v[172:175], v[142:145], v[200:203], v[50:53]
	v_mfma_i32_16x16x64_i8 v[188:191], v[134:137], v[208:211], v[38:41]
	v_mfma_i32_16x16x64_i8 v[192:195], v[142:145], v[208:211], v[34:37]
	v_mfma_i32_16x16x64_i8 v[196:199], v[134:137], v[216:219], v[22:25]
	v_mfma_i32_16x16x64_i8 v[232:235], v[142:145], v[216:219], v[18:21]
	v_mfma_i32_16x16x64_i8 v[160:163], v[134:137], v[224:227], v[6:9]
	v_mfma_i32_16x16x64_i8 v[2:5], v[142:145], v[224:227], v[2:5]
	v_mfma_i32_16x16x64_i8 v[50:53], v[130:133], v[204:207], v[172:175]
	v_mfma_i32_16x16x64_i8 v[38:41], v[138:141], v[212:215], v[188:191]
	v_mfma_i32_16x16x64_i8 v[34:37], v[130:133], v[212:215], v[192:195]
	v_mfma_i32_16x16x64_i8 v[22:25], v[138:141], v[220:223], v[196:199]
	v_mfma_i32_16x16x64_i8 v[18:21], v[130:133], v[220:223], v[232:235]
	v_mfma_i32_16x16x64_i8 v[6:9], v[138:141], v[228:231], v[160:163]
	v_mfma_i32_16x16x64_i8 v[2:5], v[130:133], v[228:231], v[2:5]
	s_setprio 0
	s_barrier
	s_add_i32 s65, 0, 0x18000
	s_add_i32 s66, 0, 0x1c000
	v_add_u32_e32 v130, s65, v181
	v_add_u32_e32 v131, s66, v181
	ds_read_b128 v[160:163], v130
	ds_read_b128 v[172:175], v130 offset:1024
	ds_read_b128 v[188:191], v130 offset:2048
	ds_read_b128 v[192:195], v130 offset:3072
	ds_read_b128 v[134:137], v131
	ds_read_b128 v[138:141], v131 offset:1024
	ds_read_b128 v[142:145], v131 offset:2048
	ds_read_b128 v[130:133], v131 offset:3072
	s_add_u32 s2, s2, 0x20000
	s_addc_u32 s3, s3, 0
	s_mov_b32 m0, s47
	v_lshl_add_u64 v[176:177], s[2:3], 0, v[146:147]
	ds_read_b128 v[196:199], v187 offset:32768
	ds_read_b128 v[200:203], v187 offset:33792
	ds_read_b128 v[204:207], v187 offset:34816
	ds_read_b128 v[208:211], v187 offset:35840
	ds_read_b128 v[212:215], v187 offset:36864
	ds_read_b128 v[216:219], v187 offset:37888
	ds_read_b128 v[220:223], v187 offset:38912
	ds_read_b128 v[224:227], v187 offset:39936
	global_load_lds_dwordx4 v[176:177], off
	v_lshl_add_u64 v[176:177], s[2:3], 0, v[150:151]
	s_mov_b32 m0, s48
	s_nop 0
	global_load_lds_dwordx4 v[176:177], off
	s_waitcnt vmcnt(8)
	s_waitcnt lgkmcnt(0)
	s_barrier
; #define PG8_STAGE(bufoff, gbase, voff) do { _Pragma("unroll") for (int _i = 0; _i < 2; ++_i) \
;         __builtin_amdgcn_global_load_lds((const unsigned*)((const char*)(gbase) + (voff)[_i]), (PG8_LAS unsigned*)(lds + (bufoff) + ldsw + _i * 8192), 16, 0, 0); } while (0)
; #define PG8_LDA(dst, b, h) do { _Pragma("unroll") for (int m = 0; m < 4; ++m) _Pragma("unroll") for (int k = 0; k < 2; ++k) dst[m][k] = *(const PG8_LAS bf16x8*)(lds + PG8_SA(b, h) + aoff + m * 2048 + k * 1024); } while (0)
; #define PG8_LDB(dst, b, h) do { _Pragma("unroll") for (int n = 0; n < 2; ++n) _Pragma("unroll") for (int k = 0; k < 2; ++k) dst[n][k] = *(const PG8_LAS bf16x8*)(lds + PG8_SB(b, h) + boff + n * 2048 + k * 1024); } while (0)
; #define PG8_MMA(ai, bj, At, Bt) do { __builtin_amdgcn_s_setprio(1); _Pragma("unroll") for (int m = 0; m < 4; ++m) _Pragma("unroll") for (int n = 0; n < 2; ++n) _Pragma("unroll") for (int k = 0; k < 2; ++k) \
;         acc[ai][bj][m][n] = Gemm::i8 ? ::mfma16i8_g(Bt[n][k], At[m][k], acc[ai][bj][m][n]) : ::mfma16_g(Bt[n][k], At[m][k], acc[ai][bj][m][n]); __builtin_amdgcn_s_setprio(0); } while (0)
; #define PG8_WAIT_V(n) asm volatile("s_waitcnt vmcnt(" #n ")" ::: "memory")
; #define PG8_WAIT_L(n) asm volatile("s_waitcnt lgkmcnt(" #n ")" ::: "memory")
; template <class Epi, class Sched, class Gemm, bool ALIGN_EPI = false, bool SP2 = false>
; __device__ __forceinline__ void gemm_phase(PG8_LAS unsigned char* lds, const Gemm g, const Sched& S, const Epi& E) {
;     ...
;             PG8_LDA(At, 0, 1); PG8_STAGE(PG8_SB(0, 0), b2, voffB); PG8_STAGE(PG8_SB(0, 1), b2 + hB1, voffB1); PG8_STAGE(PG8_SA(0, 0), a2, voffA);
;             PG8_WAIT_V(8); PG8_WAIT_L(0); PG8_BAR; PG8_MMA(1, 0, At, B0); PG8_MMA(1, 1, At, B1); PG8_BAR; PG8_SCHED;
;             PG8_LDB(B0, 1, 0); PG8_LDB(B1, 1, 1); PG8_SCHED; PG8_LDA(At, 1, 0); PG8_STAGE(PG8_SA(0, 1), a2 + hstepA, voffA);
;             PG8_WAIT_V(8); PG8_WAIT_L(0); PG8_BAR; PG8_MMA(0, 0, At, B0); PG8_MMA(0, 1, At, B1); PG8_BAR; PG8_SCHED;
;             PG8_LDA(At, 1, 1); PG8_STAGE(PG8_SB(1, 0), b3, voffB); PG8_STAGE(PG8_SB(1, 1), b3 + hB1, voffB1); PG8_STAGE(PG8_SA(1, 0), a3, voffA);
;             PG8_WAIT_V(8);
;             if constexpr (epi_pre<Epi>::value) { if (last) E.pre(pre, cur, wr, wc, lane); }
;             PG8_WAIT_L(0); PG8_BAR; PG8_MMA(1, 0, At, B0); PG8_MMA(1, 1, At, B1); PG8_BAR; PG8_SCHED;
	s_setprio 1
	s_waitcnt lgkmcnt(0)
	v_mfma_i32_16x16x64_i8 v[228:231], v[160:163], v[196:199], v[126:129]
	v_mfma_i32_16x16x64_i8 v[126:129], v[172:175], v[200:203], v[228:231]
	v_mfma_i32_16x16x64_i8 v[232:235], v[188:191], v[196:199], v[122:125]
	v_mfma_i32_16x16x64_i8 v[236:239], v[160:163], v[204:207], v[110:113]
	v_mfma_i32_16x16x64_i8 v[240:243], v[188:191], v[204:207], v[106:109]
	v_mfma_i32_16x16x64_i8 v[244:247], v[160:163], v[212:215], v[94:97]
	v_mfma_i32_16x16x64_i8 v[248:251], v[188:191], v[212:215], v[90:93]
	v_mfma_i32_16x16x64_i8 v[228:231], v[160:163], v[220:223], v[78:81]
	v_mfma_i32_16x16x64_i8 v[74:77], v[188:191], v[220:223], v[74:77]
	v_mfma_i32_16x16x64_i8 v[122:125], v[192:195], v[200:203], v[232:235]
	v_mfma_i32_16x16x64_i8 v[110:113], v[172:175], v[208:211], v[236:239]
	v_mfma_i32_16x16x64_i8 v[106:109], v[192:195], v[208:211], v[240:243]
	v_mfma_i32_16x16x64_i8 v[94:97], v[172:175], v[216:219], v[244:247]
	v_mfma_i32_16x16x64_i8 v[90:93], v[192:195], v[216:219], v[248:251]
	v_mfma_i32_16x16x64_i8 v[78:81], v[172:175], v[224:227], v[228:231]
	v_mfma_i32_16x16x64_i8 v[74:77], v[192:195], v[224:227], v[74:77]
	s_setprio 0
	s_setprio 1
	v_mfma_i32_16x16x64_i8 v[228:231], v[134:137], v[196:199], v[118:121]
	v_mfma_i32_16x16x64_i8 v[118:121], v[138:141], v[200:203], v[228:231]
	v_mfma_i32_16x16x64_i8 v[232:235], v[142:145], v[196:199], v[114:117]
	v_mfma_i32_16x16x64_i8 v[236:239], v[134:137], v[204:207], v[102:105]
	v_mfma_i32_16x16x64_i8 v[240:243], v[142:145], v[204:207], v[98:101]
	v_mfma_i32_16x16x64_i8 v[244:247], v[134:137], v[212:215], v[86:89]
	v_mfma_i32_16x16x64_i8 v[248:251], v[142:145], v[212:215], v[82:85]
	v_mfma_i32_16x16x64_i8 v[196:199], v[134:137], v[220:223], v[70:73]
	v_mfma_i32_16x16x64_i8 v[66:69], v[142:145], v[220:223], v[66:69]
	v_mfma_i32_16x16x64_i8 v[114:117], v[130:133], v[200:203], v[232:235]
	v_mfma_i32_16x16x64_i8 v[102:105], v[138:141], v[208:211], v[236:239]
	v_mfma_i32_16x16x64_i8 v[98:101], v[130:133], v[208:211], v[240:243]
	v_mfma_i32_16x16x64_i8 v[86:89], v[138:141], v[216:219], v[244:247]
	v_mfma_i32_16x16x64_i8 v[82:85], v[130:133], v[216:219], v[248:251]
	v_mfma_i32_16x16x64_i8 v[70:73], v[138:141], v[224:227], v[196:199]
	v_mfma_i32_16x16x64_i8 v[66:69], v[130:133], v[224:227], v[66:69]
	s_setprio 0
	s_barrier
	s_add_i32 s2, s65, s33
	v_lshl_add_u64 v[164:165], v[164:165], 0, s[18:19]
	s_mov_b32 m0, s2
	ds_read_b128 v[196:199], v187 offset:49152
	ds_read_b128 v[200:203], v187 offset:50176
	ds_read_b128 v[204:207], v187 offset:51200
	ds_read_b128 v[208:211], v187 offset:52224
	ds_read_b128 v[212:215], v187 offset:53248
	ds_read_b128 v[216:219], v187 offset:54272
	ds_read_b128 v[220:223], v187 offset:55296
	ds_read_b128 v[224:227], v187 offset:56320
	global_load_lds_dwordx4 v[164:165], off
	s_add_i32 m0, s2, 0x2000
	s_add_u32 s2, s40, 0x2080
	v_lshl_add_u64 v[164:165], v[166:167], 0, s[18:19]
	s_addc_u32 s3, s41, 0
	s_add_i32 s40, s66, s33
	global_load_lds_dwordx4 v[164:165], off
	v_lshl_add_u64 v[164:165], s[2:3], 0, v[148:149]
	s_mov_b32 m0, s40
	s_nop 0
	global_load_lds_dwordx4 v[164:165], off
	v_lshl_add_u64 v[164:165], s[2:3], 0, v[152:153]
	s_add_i32 m0, s40, 0x2000
	s_nop 0
	global_load_lds_dwordx4 v[164:165], off
	v_lshl_add_u64 v[164:165], v[168:169], 0, s[18:19]
	s_mov_b32 m0, s51
	s_nop 0
	global_load_lds_dwordx4 v[164:165], off
	v_lshl_add_u64 v[164:165], v[170:171], 0, s[18:19]
	s_mov_b32 m0, s52
	s_nop 0
	global_load_lds_dwordx4 v[164:165], off
	s_waitcnt vmcnt(8)
	s_waitcnt lgkmcnt(0)
	s_barrier
	s_setprio 1
	s_waitcnt lgkmcnt(0)
	v_mfma_i32_16x16x64_i8 v[164:167], v[160:163], v[196:199], v[62:65]
	v_mfma_i32_16x16x64_i8 v[62:65], v[172:175], v[200:203], v[164:167]
	v_mfma_i32_16x16x64_i8 v[168:171], v[188:191], v[196:199], v[58:61]
	v_mfma_i32_16x16x64_i8 v[228:231], v[160:163], v[204:207], v[46:49]
	v_mfma_i32_16x16x64_i8 v[232:235], v[188:191], v[204:207], v[42:45]
	v_mfma_i32_16x16x64_i8 v[236:239], v[160:163], v[212:215], v[30:33]
	v_mfma_i32_16x16x64_i8 v[240:243], v[188:191], v[212:215], v[26:29]
	v_mfma_i32_16x16x64_i8 v[164:167], v[160:163], v[220:223], v[14:17]
	v_mfma_i32_16x16x64_i8 v[10:13], v[188:191], v[220:223], v[10:13]
	v_mfma_i32_16x16x64_i8 v[58:61], v[192:195], v[200:203], v[168:171]
	v_mfma_i32_16x16x64_i8 v[46:49], v[172:175], v[208:211], v[228:231]
	v_mfma_i32_16x16x64_i8 v[42:45], v[192:195], v[208:211], v[232:235]
	v_mfma_i32_16x16x64_i8 v[30:33], v[172:175], v[216:219], v[236:239]
	v_mfma_i32_16x16x64_i8 v[26:29], v[192:195], v[216:219], v[240:243]
	v_mfma_i32_16x16x64_i8 v[14:17], v[172:175], v[224:227], v[164:167]
	v_mfma_i32_16x16x64_i8 v[10:13], v[192:195], v[224:227], v[10:13]
	s_setprio 0
	s_setprio 1
	v_mfma_i32_16x16x64_i8 v[160:163], v[134:137], v[196:199], v[54:57]
	v_mfma_i32_16x16x64_i8 v[54:57], v[138:141], v[200:203], v[160:163]
	v_mfma_i32_16x16x64_i8 v[164:167], v[142:145], v[196:199], v[50:53]
	v_mfma_i32_16x16x64_i8 v[168:171], v[134:137], v[204:207], v[38:41]
	v_mfma_i32_16x16x64_i8 v[172:175], v[142:145], v[204:207], v[34:37]
	v_mfma_i32_16x16x64_i8 v[188:191], v[134:137], v[212:215], v[22:25]
	v_mfma_i32_16x16x64_i8 v[192:195], v[142:145], v[212:215], v[18:21]
	v_mfma_i32_16x16x64_i8 v[160:163], v[134:137], v[220:223], v[6:9]
	v_mfma_i32_16x16x64_i8 v[2:5], v[142:145], v[220:223], v[2:5]
	v_mfma_i32_16x16x64_i8 v[50:53], v[130:133], v[200:203], v[164:167]
	v_mfma_i32_16x16x64_i8 v[38:41], v[138:141], v[208:211], v[168:171]
	v_mfma_i32_16x16x64_i8 v[34:37], v[130:133], v[208:211], v[172:175]
	v_mfma_i32_16x16x64_i8 v[22:25], v[138:141], v[216:219], v[188:191]
	v_mfma_i32_16x16x64_i8 v[18:21], v[130:133], v[216:219], v[192:195]
	v_mfma_i32_16x16x64_i8 v[6:9], v[138:141], v[224:227], v[160:163]
	v_mfma_i32_16x16x64_i8 v[2:5], v[130:133], v[224:227], v[2:5]
	s_setprio 0
	s_barrier
; #define PG8_BAR __builtin_amdgcn_s_barrier()
;     __device__ __forceinline__ void operator()(const f32x4 (&acc)[2][2][4][2], const Unit& u, int wr, int wc, int fr, int fq) const {
;         asm volatile("" : "+v"(fr), "+v"(fq));
;         const int row0 = u.pm * BM + wr * 64 + fr, col0 = u.pn * BM + wc * 64 + 16 * fq;
;         const int gn = u.pn >> 2, gbase = (gn < 3) ? 3072 + 1024 * gn : 0;
;         f32x4 bv[2][2];
; #pragma unroll
;         for (int bj = 0; bj < 2; ++bj)
; #pragma unroll
;             for (int n = 0; n < 2; ++n) bv[bj][n] = *(const f32x4*)(bias + col0 + 8 * bj + 4 * n) * -1.44269504f;
;         f32x4 wv[2][2];
; #pragma unroll
;         for (int bj = 0; bj < 2; ++bj)
; #pragma unroll
;             for (int n = 0; n < 2; ++n) wv[bj][n] = *(const f32x4*)(SW + col0 + 8 * bj + 4 * n) * -1.44269504f;
;         float rsv[8];
; #pragma unroll
;         for (int i = 0; i < 8; ++i) rsv[i] = SH[row0 + (i >> 2) * HALF + (i & 3) * 16];
; template <class Epi, class Sched, class Gemm, bool ALIGN_EPI = false, bool SP2 = false>
; __device__ __forceinline__ void gemm_phase(PG8_LAS unsigned char* lds, const Gemm g, const Sched& S, const Epi& E) {
;     ...
;         if constexpr (ALIGN_EPI) { if (wr == 0) PG8_BAR; }
	s_add_i32 s64, s64, 2
	s_add_u32 s62, s62, 0x100
	s_addc_u32 s63, s63, 0
	s_add_u32 s0, s0, 0x100
	s_addc_u32 s1, s1, 0
	s_cmp_gt_u32 s64, 5
	s_cbranch_scc0 .LBB0_1192
	s_lshl_b32 s0, s59, 8
	v_mov_b32_e32 v130, v179
	v_mov_b32_e32 v154, v1
	s_or_b32 s0, s0, s53
	v_cvt_f32_i32_e32 v212, v122
	v_lshl_add_u32 v144, v130, 4, s0
	s_lshl_b32 s0, s38, 8
	v_ashrrev_i32_e32 v145, 31, v144
	s_add_i32 s0, s0, s50
	v_lshlrev_b64 v[142:143], 2, v[144:145]
	v_add_u32_e32 v164, s0, v154
	v_lshl_add_u64 v[160:161], s[10:11], 0, v[142:143]
	v_ashrrev_i32_e32 v165, 31, v164
	global_load_dwordx4 v[130:133], v[160:161], off
	global_load_dwordx4 v[134:137], v[160:161], off offset:16
	global_load_dwordx4 v[138:141], v[160:161], off offset:32
	s_nop 0
	global_load_dwordx4 v[160:163], v[160:161], off offset:48
	v_lshl_add_u64 v[142:143], s[14:15], 0, v[142:143]
	v_lshl_add_u64 v[170:171], v[164:165], 2, s[16:17]
	global_load_dwordx4 v[166:169], v[142:143], off
	global_load_dwordx4 v[194:197], v[142:143], off offset:16
	global_load_dwordx4 v[198:201], v[142:143], off offset:32
	global_load_dwordx4 v[202:205], v[142:143], off offset:48
	global_load_dword v206, v[170:171], off
	global_load_dword v188, v[170:171], off offset:64
	global_load_dword v186, v[170:171], off offset:128
	global_load_dword v184, v[170:171], off offset:192
	global_load_dword v182, v[170:171], off offset:512
	global_load_dword v180, v[170:171], off offset:576
	global_load_dword v178, v[170:171], off offset:640
	global_load_dword v122, v[170:171], off offset:704
	s_ashr_i32 s0, s59, 2
	s_lshl_b32 s1, s0, 10
	v_mov_b64_e32 v[142:143], s[12:13]
	s_add_i32 s2, s1, 0xc00
	v_cvt_f32_i32_e32 v209, v127
	v_cvt_f32_i32_e32 v208, v126
	v_cvt_f32_i32_e32 v215, v125
	v_cvt_f32_i32_e32 v214, v124
	s_cmp_lt_i32 s0, 3
	v_mad_i64_i32 v[124:125], s[0:1], v164, s57, v[142:143]
	s_cselect_b32 s0, s2, 0
	v_cvt_f32_i32_e32 v211, v129
	v_cvt_f32_i32_e32 v210, v128
	s_ashr_i32 s1, s0, 31
	v_cvt_f32_i32_e32 v115, v115
	v_cvt_f32_i32_e32 v114, v114
	v_cvt_f32_i32_e32 v99, v99
	v_cvt_f32_i32_e32 v98, v98
	v_cvt_f32_i32_e32 v83, v83
	v_cvt_f32_i32_e32 v82, v82
	v_cvt_f32_i32_e32 v67, v67
	v_cvt_f32_i32_e32 v66, v66
	v_cvt_f32_i32_e32 v51, v51
	v_cvt_f32_i32_e32 v50, v50
	v_cvt_f32_i32_e32 v35, v35
	v_cvt_f32_i32_e32 v34, v34
	v_cvt_f32_i32_e32 v19, v19
	v_cvt_f32_i32_e32 v18, v18
	v_and_b32_e32 v154, 0x3f0, v144
	v_lshl_add_u64 v[124:125], v[124:125], 0, s[0:1]
	v_cvt_f32_i32_e32 v117, v117
	v_cvt_f32_i32_e32 v116, v116
	v_cvt_f32_i32_e32 v111, v111
	v_cvt_f32_i32_e32 v110, v110
	v_cvt_f32_i32_e32 v101, v101
	v_cvt_f32_i32_e32 v100, v100
	v_cvt_f32_i32_e32 v95, v95
	v_cvt_f32_i32_e32 v94, v94
	v_cvt_f32_i32_e32 v85, v85
	v_cvt_f32_i32_e32 v84, v84
	v_cvt_f32_i32_e32 v79, v79
	v_cvt_f32_i32_e32 v78, v78
	v_cvt_f32_i32_e32 v69, v69
	v_cvt_f32_i32_e32 v68, v68
	v_cvt_f32_i32_e32 v63, v63
	v_cvt_f32_i32_e32 v62, v62
	v_cvt_f32_i32_e32 v53, v53
	v_cvt_f32_i32_e32 v52, v52
	v_cvt_f32_i32_e32 v47, v47
	v_cvt_f32_i32_e32 v46, v46
	v_cvt_f32_i32_e32 v37, v37
	v_cvt_f32_i32_e32 v36, v36
	v_cvt_f32_i32_e32 v31, v31
	v_cvt_f32_i32_e32 v30, v30
	v_cvt_f32_i32_e32 v21, v21
	v_cvt_f32_i32_e32 v20, v20
	v_cvt_f32_i32_e32 v15, v15
	v_cvt_f32_i32_e32 v14, v14
	v_add_u32_e32 v207, 32, v164
	v_lshl_add_u64 v[216:217], v[124:125], 0, v[154:155]
	v_add_u32_e32 v189, 0xa0, v164
	v_cvt_f32_i32_e32 v213, v123
	v_add_u32_e32 v123, 0xb0, v164
	v_cvt_f32_i32_e32 v119, v119
	v_cvt_f32_i32_e32 v118, v118
	v_cvt_f32_i32_e32 v109, v109
	v_cvt_f32_i32_e32 v108, v108
	v_cvt_f32_i32_e32 v103, v103
	v_cvt_f32_i32_e32 v102, v102
	v_cvt_f32_i32_e32 v93, v93
	v_cvt_f32_i32_e32 v121, v121
	v_cvt_f32_i32_e32 v120, v120
	v_cvt_f32_i32_e32 v113, v113
	v_cvt_f32_i32_e32 v112, v112
	v_cvt_f32_i32_e32 v107, v107
	v_cvt_f32_i32_e32 v106, v106
	v_cvt_f32_i32_e32 v105, v105
	v_cvt_f32_i32_e32 v104, v104
	v_cvt_f32_i32_e32 v92, v92
	v_cvt_f32_i32_e32 v87, v87
	v_cvt_f32_i32_e32 v86, v86
	v_cvt_f32_i32_e32 v97, v97
	v_cvt_f32_i32_e32 v96, v96
	v_cvt_f32_i32_e32 v91, v91
	v_cvt_f32_i32_e32 v90, v90
	v_cvt_f32_i32_e32 v89, v89
	v_cvt_f32_i32_e32 v88, v88
	v_cvt_f32_i32_e32 v77, v77
	v_cvt_f32_i32_e32 v76, v76
	v_cvt_f32_i32_e32 v71, v71
	v_cvt_f32_i32_e32 v70, v70
	v_cvt_f32_i32_e32 v81, v81
	v_cvt_f32_i32_e32 v80, v80
	v_cvt_f32_i32_e32 v75, v75
	v_cvt_f32_i32_e32 v74, v74
	v_cvt_f32_i32_e32 v73, v73
	v_cvt_f32_i32_e32 v72, v72
	v_cvt_f32_i32_e32 v61, v61
	v_cvt_f32_i32_e32 v60, v60
	v_cvt_f32_i32_e32 v55, v55
	v_cvt_f32_i32_e32 v54, v54
	v_cvt_f32_i32_e32 v65, v65
	v_cvt_f32_i32_e32 v64, v64
	v_cvt_f32_i32_e32 v59, v59
	v_cvt_f32_i32_e32 v58, v58
	v_cvt_f32_i32_e32 v57, v57
	v_cvt_f32_i32_e32 v56, v56
	v_cvt_f32_i32_e32 v45, v45
	v_cvt_f32_i32_e32 v44, v44
	v_cvt_f32_i32_e32 v39, v39
	v_cvt_f32_i32_e32 v38, v38
	v_cvt_f32_i32_e32 v49, v49
	v_cvt_f32_i32_e32 v48, v48
	v_cvt_f32_i32_e32 v43, v43
	v_cvt_f32_i32_e32 v42, v42
	v_cvt_f32_i32_e32 v41, v41
	v_cvt_f32_i32_e32 v40, v40
	v_cvt_f32_i32_e32 v29, v29
	v_cvt_f32_i32_e32 v28, v28
	v_cvt_f32_i32_e32 v23, v23
	v_cvt_f32_i32_e32 v22, v22
	v_cvt_f32_i32_e32 v33, v33
	v_cvt_f32_i32_e32 v32, v32
	v_cvt_f32_i32_e32 v27, v27
	v_cvt_f32_i32_e32 v26, v26
	v_cvt_f32_i32_e32 v25, v25
	v_cvt_f32_i32_e32 v24, v24
	v_cvt_f32_i32_e32 v7, v7
	v_cvt_f32_i32_e32 v6, v6
	v_cvt_f32_i32_e32 v3, v3
	v_cvt_f32_i32_e32 v2, v2
	v_cvt_f32_i32_e32 v17, v17
	v_cvt_f32_i32_e32 v16, v16
	v_cvt_f32_i32_e32 v11, v11
	v_cvt_f32_i32_e32 v13, v13
	v_cvt_f32_i32_e32 v12, v12
	v_cvt_f32_i32_e32 v10, v10
	v_cvt_f32_i32_e32 v9, v9
	v_cvt_f32_i32_e32 v8, v8
	v_cvt_f32_i32_e32 v5, v5
	v_cvt_f32_i32_e32 v4, v4
	s_and_b64 vcc, exec, s[20:21]
	s_cbranch_vccz .LBB0_1195
	s_barrier
;     __device__ __forceinline__ void operator()(const f32x4 (&acc)[2][2][4][2], const Unit& u, int wr, int wc, int fr, int fq) const {
;     ...
; #pragma unroll
;         for (int ai = 0; ai < 2; ++ai)
; #pragma unroll
;             for (int m = 0; m < 4; ++m) { unsigned char* rowp = O + (size_t)(row0 + ai * HALF + m * 16) * 8704 + gbase + (col0 & 1023);
;                 const float rs = rsv[ai * 4 + m];
;                 u32x4 w; EPG_Q4(w.x, acc[ai][0][m][0], wv[0][0], rs, bv[0][0]); EPG_Q4(w.y, acc[ai][0][m][1], wv[0][1], rs, bv[0][1]);
;                 EPG_Q4(w.z, acc[ai][1][m][0], wv[1][0], rs, bv[1][0]); EPG_Q4(w.w, acc[ai][1][m][1], wv[1][1], rs, bv[1][1]);
;                 *(u32x4*)rowp = w; }
.LBB0_1195:
	s_waitcnt vmcnt(0)
	v_pk_mul_f32 v[172:173], v[130:131], s[22:23] op_sel_hi:[1,0]
	v_pk_mul_f32 v[170:171], v[132:133], s[22:23] op_sel_hi:[1,0]
	v_pk_mul_f32 v[174:175], v[166:167], s[22:23] op_sel_hi:[1,0]
	v_pk_mul_f32 v[124:125], v[162:163], s[22:23] op_sel_hi:[1,0]
	v_pk_mul_f32 v[162:163], v[174:175], v[208:209]
	v_pk_mul_f32 v[176:177], v[168:169], s[22:23] op_sel_hi:[1,0]
	v_pk_mul_f32 v[130:131], v[202:203], s[22:23] op_sel_hi:[1,0]
	v_pk_fma_f32 v[162:163], v[162:163], v[206:207], v[172:173] op_sel_hi:[1,0,1]
	v_pk_mul_f32 v[128:129], v[160:161], s[22:23] op_sel_hi:[1,0]
	v_pk_mul_f32 v[132:133], v[204:205], s[22:23] op_sel_hi:[1,0]
	v_pk_mul_f32 v[160:161], v[176:177], v[210:211]
	v_exp_f32_e32 v162, v162
	v_exp_f32_e32 v163, v163
	v_pk_mul_f32 v[114:115], v[130:131], v[114:115]
	v_pk_fma_f32 v[160:161], v[160:161], v[206:207], v[170:171] op_sel_hi:[1,0,1]
	v_pk_mul_f32 v[116:117], v[132:133], v[116:117]
	v_pk_fma_f32 v[114:115], v[114:115], v[206:207], v[128:129] op_sel_hi:[1,0,1]
	v_exp_f32_e32 v160, v160
	v_exp_f32_e32 v161, v161
	v_pk_fma_f32 v[116:117], v[116:117], v[206:207], v[124:125] op_sel_hi:[1,0,1]
	v_exp_f32_e32 v114, v114
	v_exp_f32_e32 v115, v115
	v_exp_f32_e32 v116, v116
	v_exp_f32_e32 v117, v117
	v_pk_mul_f32 v[166:167], v[194:195], s[22:23] op_sel_hi:[1,0]
	v_pk_add_f32 v[162:163], v[162:163], 1.0 op_sel_hi:[1,0]
	v_add_u32_e32 v193, 16, v164
	v_add_u32_e32 v192, 48, v164
	v_add_u32_e32 v191, 0x80, v164
	v_add_u32_e32 v190, 0x90, v164
	v_pk_mul_f32 v[144:145], v[136:137], s[22:23] op_sel_hi:[1,0]
	v_pk_mul_f32 v[164:165], v[134:135], s[22:23] op_sel_hi:[1,0]
	v_pk_mul_f32 v[136:137], v[138:139], s[22:23] op_sel_hi:[1,0]
	v_pk_mul_f32 v[168:169], v[196:197], s[22:23] op_sel_hi:[1,0]
	v_pk_mul_f32 v[138:139], v[198:199], s[22:23] op_sel_hi:[1,0]
	v_pk_mul_f32 v[196:197], v[166:167], v[212:213]
	v_rcp_f32_e32 v162, v162
	v_rcp_f32_e32 v163, v163
	v_pk_mul_f32 v[134:135], v[140:141], s[22:23] op_sel_hi:[1,0]
	v_pk_mul_f32 v[140:141], v[200:201], s[22:23] op_sel_hi:[1,0]
	v_pk_mul_f32 v[194:195], v[168:169], v[214:215]
	v_pk_fma_f32 v[196:197], v[196:197], v[206:207], v[164:165] op_sel_hi:[1,0,1]
	v_pk_add_f32 v[160:161], v[160:161], 1.0 op_sel_hi:[1,0]
	v_pk_mul_f32 v[118:119], v[138:139], v[118:119]
	v_pk_add_f32 v[114:115], v[114:115], 1.0 op_sel_hi:[1,0]
	v_pk_fma_f32 v[194:195], v[194:195], v[206:207], v[144:145] op_sel_hi:[1,0,1]
	v_exp_f32_e32 v196, v196
	v_rcp_f32_e32 v160, v160
	v_rcp_f32_e32 v161, v161
	v_exp_f32_e32 v197, v197
	v_pk_mul_f32 v[120:121], v[140:141], v[120:121]
	v_pk_fma_f32 v[118:119], v[118:119], v[206:207], v[136:137] op_sel_hi:[1,0,1]
	v_pk_add_f32 v[116:117], v[116:117], 1.0 op_sel_hi:[1,0]
	v_rcp_f32_e32 v114, v114
	v_rcp_f32_e32 v115, v115
	v_mov_b64_e32 v[126:127], s[24:25]
	v_exp_f32_e32 v194, v194
	v_exp_f32_e32 v195, v195
	v_pk_fma_f32 v[120:121], v[120:121], v[206:207], v[134:135] op_sel_hi:[1,0,1]
	v_exp_f32_e32 v118, v118
	v_exp_f32_e32 v119, v119
	v_rcp_f32_e32 v116, v116
	v_rcp_f32_e32 v117, v117
	v_pk_fma_f32 v[162:163], v[162:163], s[26:27], v[126:127] op_sel_hi:[1,0,0]
	v_exp_f32_e32 v120, v120
	v_exp_f32_e32 v121, v121
	v_max_f32_e32 v163, 0x4b000001, v163
	v_max_f32_e32 v162, 0x4b000001, v162
	v_pk_fma_f32 v[160:161], v[160:161], s[26:27], v[126:127] op_sel_hi:[1,0,0]
	v_perm_b32 v198, v163, v162, s58
	v_pk_add_f32 v[162:163], v[196:197], 1.0 op_sel_hi:[1,0]
	v_pk_fma_f32 v[114:115], v[114:115], s[26:27], v[126:127] op_sel_hi:[1,0,0]
	v_max_f32_e32 v199, 0x4b000001, v161
	v_max_f32_e32 v200, 0x4b000001, v160
	v_pk_add_f32 v[160:161], v[194:195], 1.0 op_sel_hi:[1,0]
	v_rcp_f32_e32 v162, v162
	v_rcp_f32_e32 v163, v163
	v_pk_add_f32 v[118:119], v[118:119], 1.0 op_sel_hi:[1,0]
	v_pk_fma_f32 v[116:117], v[116:117], s[26:27], v[126:127] op_sel_hi:[1,0,0]
	v_max_f32_e32 v115, 0x4b000001, v115
	v_max_f32_e32 v114, 0x4b000001, v114
	v_rcp_f32_e32 v194, v160
	v_rcp_f32_e32 v195, v161
	v_pk_add_f32 v[120:121], v[120:121], 1.0 op_sel_hi:[1,0]
	v_rcp_f32_e32 v118, v118
	v_rcp_f32_e32 v119, v119
	v_perm_b32 v114, v115, v114, s58
	v_max_f32_e32 v115, 0x4b000001, v117
	v_max_f32_e32 v116, 0x4b000001, v116
	v_rcp_f32_e32 v120, v120
	v_rcp_f32_e32 v121, v121
	v_perm_b32 v115, v115, v116, s58
	v_pk_fma_f32 v[162:163], v[162:163], s[26:27], v[126:127] op_sel_hi:[1,0,0]
	v_pk_fma_f32 v[194:195], v[194:195], s[26:27], v[126:127] op_sel_hi:[1,0,0]
	v_max_f32_e32 v161, 0x4b000001, v163
	v_max_f32_e32 v162, 0x4b000001, v162
	v_pk_fma_f32 v[118:119], v[118:119], s[26:27], v[126:127] op_sel_hi:[1,0,0]
	v_perm_b32 v161, v161, v162, s58
	v_max_f32_e32 v162, 0x4b000001, v195
	v_max_f32_e32 v163, 0x4b000001, v194
	v_pk_fma_f32 v[120:121], v[120:121], s[26:27], v[126:127] op_sel_hi:[1,0,0]
	v_max_f32_e32 v119, 0x4b000001, v119
	v_max_f32_e32 v118, 0x4b000001, v118
	v_perm_b32 v162, v162, v163, s58
	v_perm_b32 v118, v119, v118, s58
	v_max_f32_e32 v119, 0x4b000001, v121
	v_max_f32_e32 v120, 0x4b000001, v120
	v_lshl_or_b32 v163, v115, 16, v114
	v_perm_b32 v160, v199, v200, s58
	v_perm_b32 v119, v119, v120, s58
	v_lshl_or_b32 v160, v160, 16, v198
	v_lshl_or_b32 v161, v162, 16, v161
	v_lshl_or_b32 v162, v119, 16, v118
	global_store_dwordx4 v[216:217], v[160:163], off
	v_pk_mul_f32 v[98:99], v[130:131], v[98:99]
	v_pk_mul_f32 v[110:111], v[174:175], v[110:111]
	v_pk_mul_f32 v[100:101], v[132:133], v[100:101]
	v_pk_fma_f32 v[98:99], v[98:99], v[188:189], v[128:129] op_sel_hi:[1,0,1]
	v_pk_fma_f32 v[110:111], v[110:111], v[188:189], v[172:173] op_sel_hi:[1,0,1]
	v_pk_fma_f32 v[100:101], v[100:101], v[188:189], v[124:125] op_sel_hi:[1,0,1]
	v_exp_f32_e32 v98, v98
	v_exp_f32_e32 v99, v99
;     __device__ __forceinline__ void operator()(const f32x4 (&acc)[2][2][4][2], const Unit& u, int wr, int wc, int fr, int fq) const {
;     ...
; #pragma unroll
;         for (int ai = 0; ai < 2; ++ai)
; #pragma unroll
;             for (int m = 0; m < 4; ++m) { unsigned char* rowp = O + (size_t)(row0 + ai * HALF + m * 16) * 8704 + gbase + (col0 & 1023);
;                 const float rs = rsv[ai * 4 + m];
;                 u32x4 w; EPG_Q4(w.x, acc[ai][0][m][0], wv[0][0], rs, bv[0][0]); EPG_Q4(w.y, acc[ai][0][m][1], wv[0][1], rs, bv[0][1]);
;                 EPG_Q4(w.z, acc[ai][1][m][0], wv[1][0], rs, bv[1][0]); EPG_Q4(w.w, acc[ai][1][m][1], wv[1][1], rs, bv[1][1]);
;                 *(u32x4*)rowp = w; }
	v_exp_f32_e32 v110, v110
	v_exp_f32_e32 v111, v111
	v_exp_f32_e32 v100, v100
	v_exp_f32_e32 v101, v101
	v_pk_mul_f32 v[108:109], v[168:169], v[108:109]
	v_pk_mul_f32 v[102:103], v[138:139], v[102:103]
	v_pk_add_f32 v[98:99], v[98:99], 1.0 op_sel_hi:[1,0]
	v_pk_mul_f32 v[112:113], v[176:177], v[112:113]
	v_pk_add_f32 v[110:111], v[110:111], 1.0 op_sel_hi:[1,0]
	v_pk_mul_f32 v[106:107], v[166:167], v[106:107]
	v_pk_fma_f32 v[108:109], v[108:109], v[188:189], v[144:145] op_sel_hi:[1,0,1]
	v_pk_mul_f32 v[104:105], v[140:141], v[104:105]
	v_pk_fma_f32 v[102:103], v[102:103], v[188:189], v[136:137] op_sel_hi:[1,0,1]
	v_pk_add_f32 v[100:101], v[100:101], 1.0 op_sel_hi:[1,0]
	v_rcp_f32_e32 v98, v98
	v_rcp_f32_e32 v99, v99
	v_pk_fma_f32 v[112:113], v[112:113], v[188:189], v[170:171] op_sel_hi:[1,0,1]
	v_rcp_f32_e32 v110, v110
	v_rcp_f32_e32 v111, v111
	v_pk_fma_f32 v[106:107], v[106:107], v[188:189], v[164:165] op_sel_hi:[1,0,1]
	v_exp_f32_e32 v108, v108
	v_exp_f32_e32 v109, v109
	v_pk_fma_f32 v[104:105], v[104:105], v[188:189], v[134:135] op_sel_hi:[1,0,1]
	v_exp_f32_e32 v102, v102
	v_exp_f32_e32 v103, v103
	v_rcp_f32_e32 v100, v100
	v_rcp_f32_e32 v101, v101
	v_exp_f32_e32 v112, v112
	v_exp_f32_e32 v113, v113
	v_exp_f32_e32 v106, v106
	v_exp_f32_e32 v107, v107
	v_exp_f32_e32 v104, v104
	v_exp_f32_e32 v105, v105
	v_pk_fma_f32 v[98:99], v[98:99], s[26:27], v[126:127] op_sel_hi:[1,0,0]
	v_pk_fma_f32 v[110:111], v[110:111], s[26:27], v[126:127] op_sel_hi:[1,0,0]
	v_pk_add_f32 v[108:109], v[108:109], 1.0 op_sel_hi:[1,0]
	v_pk_add_f32 v[102:103], v[102:103], 1.0 op_sel_hi:[1,0]
	v_pk_fma_f32 v[100:101], v[100:101], s[26:27], v[126:127] op_sel_hi:[1,0,0]
	v_max_f32_e32 v99, 0x4b000001, v99
	v_max_f32_e32 v98, 0x4b000001, v98
	v_pk_add_f32 v[112:113], v[112:113], 1.0 op_sel_hi:[1,0]
	v_max_f32_e32 v111, 0x4b000001, v111
	v_max_f32_e32 v110, 0x4b000001, v110
	v_pk_add_f32 v[106:107], v[106:107], 1.0 op_sel_hi:[1,0]
	v_rcp_f32_e32 v108, v108
	v_rcp_f32_e32 v109, v109
	v_pk_add_f32 v[104:105], v[104:105], 1.0 op_sel_hi:[1,0]
	v_rcp_f32_e32 v102, v102
	v_rcp_f32_e32 v103, v103
	v_perm_b32 v98, v99, v98, s58
	v_max_f32_e32 v99, 0x4b000001, v101
	v_max_f32_e32 v100, 0x4b000001, v100
	v_rcp_f32_e32 v112, v112
	v_rcp_f32_e32 v113, v113
	v_perm_b32 v116, v111, v110, s58
	v_rcp_f32_e32 v110, v106
	v_rcp_f32_e32 v111, v107
	v_rcp_f32_e32 v104, v104
	v_rcp_f32_e32 v105, v105
	v_perm_b32 v99, v99, v100, s58
	v_pk_fma_f32 v[108:109], v[108:109], s[26:27], v[126:127] op_sel_hi:[1,0,0]
	v_pk_fma_f32 v[102:103], v[102:103], s[26:27], v[126:127] op_sel_hi:[1,0,0]
	v_pk_fma_f32 v[112:113], v[112:113], s[26:27], v[126:127] op_sel_hi:[1,0,0]
	v_pk_fma_f32 v[110:111], v[110:111], s[26:27], v[126:127] op_sel_hi:[1,0,0]
	v_max_f32_e32 v109, 0x4b000001, v109
	v_max_f32_e32 v108, 0x4b000001, v108
	v_pk_fma_f32 v[104:105], v[104:105], s[26:27], v[126:127] op_sel_hi:[1,0,0]
	v_max_f32_e32 v103, 0x4b000001, v103
	v_max_f32_e32 v102, 0x4b000001, v102
	v_mad_i64_i32 v[114:115], s[2:3], v193, s57, v[142:143]
	v_max_f32_e32 v113, 0x4b000001, v113
	v_max_f32_e32 v112, 0x4b000001, v112
	v_max_f32_e32 v107, 0x4b000001, v111
	v_max_f32_e32 v110, 0x4b000001, v110
	v_perm_b32 v108, v109, v108, s58
	v_perm_b32 v102, v103, v102, s58
	v_max_f32_e32 v103, 0x4b000001, v105
	v_max_f32_e32 v104, 0x4b000001, v104
	v_lshl_or_b32 v109, v99, 16, v98
	v_lshl_add_u64 v[114:115], v[114:115], 0, s[0:1]
	v_perm_b32 v106, v113, v112, s58
	v_perm_b32 v107, v107, v110, s58
	v_perm_b32 v103, v103, v104, s58
	v_lshl_add_u64 v[114:115], v[114:115], 0, v[154:155]
	v_lshl_or_b32 v106, v106, 16, v116
	v_lshl_or_b32 v107, v108, 16, v107
	v_lshl_or_b32 v108, v103, 16, v102
	global_store_dwordx4 v[114:115], v[106:109], off
	v_pk_mul_f32 v[82:83], v[130:131], v[82:83]
	v_pk_mul_f32 v[94:95], v[174:175], v[94:95]
	v_pk_mul_f32 v[84:85], v[132:133], v[84:85]
	v_pk_fma_f32 v[82:83], v[82:83], v[186:187], v[128:129] op_sel_hi:[1,0,1]
	v_pk_fma_f32 v[94:95], v[94:95], v[186:187], v[172:173] op_sel_hi:[1,0,1]
	v_pk_fma_f32 v[84:85], v[84:85], v[186:187], v[124:125] op_sel_hi:[1,0,1]
	v_exp_f32_e32 v82, v82
	v_exp_f32_e32 v83, v83
	v_exp_f32_e32 v94, v94
	v_exp_f32_e32 v95, v95
	v_exp_f32_e32 v84, v84
	v_exp_f32_e32 v85, v85
	v_pk_mul_f32 v[92:93], v[168:169], v[92:93]
	v_pk_mul_f32 v[86:87], v[138:139], v[86:87]
	v_pk_add_f32 v[82:83], v[82:83], 1.0 op_sel_hi:[1,0]
	v_pk_mul_f32 v[96:97], v[176:177], v[96:97]
	v_pk_add_f32 v[94:95], v[94:95], 1.0 op_sel_hi:[1,0]
	v_pk_mul_f32 v[90:91], v[166:167], v[90:91]
	v_pk_fma_f32 v[92:93], v[92:93], v[186:187], v[144:145] op_sel_hi:[1,0,1]
	v_pk_mul_f32 v[88:89], v[140:141], v[88:89]
	v_pk_fma_f32 v[86:87], v[86:87], v[186:187], v[136:137] op_sel_hi:[1,0,1]
	v_pk_add_f32 v[84:85], v[84:85], 1.0 op_sel_hi:[1,0]
	v_rcp_f32_e32 v82, v82
	v_rcp_f32_e32 v83, v83
	v_pk_fma_f32 v[96:97], v[96:97], v[186:187], v[170:171] op_sel_hi:[1,0,1]
	v_rcp_f32_e32 v94, v94
	v_rcp_f32_e32 v95, v95
	v_pk_fma_f32 v[90:91], v[90:91], v[186:187], v[164:165] op_sel_hi:[1,0,1]
	v_exp_f32_e32 v92, v92
	v_exp_f32_e32 v93, v93
	v_pk_fma_f32 v[88:89], v[88:89], v[186:187], v[134:135] op_sel_hi:[1,0,1]
	v_exp_f32_e32 v86, v86
	v_exp_f32_e32 v87, v87
	v_rcp_f32_e32 v84, v84
	v_rcp_f32_e32 v85, v85
	v_exp_f32_e32 v96, v96
	v_exp_f32_e32 v97, v97
	v_exp_f32_e32 v90, v90
	v_exp_f32_e32 v91, v91
	v_exp_f32_e32 v88, v88
	v_exp_f32_e32 v89, v89
	v_pk_fma_f32 v[82:83], v[82:83], s[26:27], v[126:127] op_sel_hi:[1,0,0]
	v_pk_fma_f32 v[94:95], v[94:95], s[26:27], v[126:127] op_sel_hi:[1,0,0]
	v_pk_add_f32 v[92:93], v[92:93], 1.0 op_sel_hi:[1,0]
	v_pk_add_f32 v[86:87], v[86:87], 1.0 op_sel_hi:[1,0]
;     __device__ __forceinline__ void operator()(const f32x4 (&acc)[2][2][4][2], const Unit& u, int wr, int wc, int fr, int fq) const {
;     ...
; #pragma unroll
;         for (int ai = 0; ai < 2; ++ai)
; #pragma unroll
;             for (int m = 0; m < 4; ++m) { unsigned char* rowp = O + (size_t)(row0 + ai * HALF + m * 16) * 8704 + gbase + (col0 & 1023);
;                 const float rs = rsv[ai * 4 + m];
;                 u32x4 w; EPG_Q4(w.x, acc[ai][0][m][0], wv[0][0], rs, bv[0][0]); EPG_Q4(w.y, acc[ai][0][m][1], wv[0][1], rs, bv[0][1]);
;                 EPG_Q4(w.z, acc[ai][1][m][0], wv[1][0], rs, bv[1][0]); EPG_Q4(w.w, acc[ai][1][m][1], wv[1][1], rs, bv[1][1]);
;                 *(u32x4*)rowp = w; }
	v_pk_fma_f32 v[84:85], v[84:85], s[26:27], v[126:127] op_sel_hi:[1,0,0]
	v_max_f32_e32 v83, 0x4b000001, v83
	v_max_f32_e32 v82, 0x4b000001, v82
	v_pk_add_f32 v[96:97], v[96:97], 1.0 op_sel_hi:[1,0]
	v_max_f32_e32 v95, 0x4b000001, v95
	v_max_f32_e32 v94, 0x4b000001, v94
	v_pk_add_f32 v[90:91], v[90:91], 1.0 op_sel_hi:[1,0]
	v_rcp_f32_e32 v92, v92
	v_rcp_f32_e32 v93, v93
	v_pk_add_f32 v[88:89], v[88:89], 1.0 op_sel_hi:[1,0]
	v_rcp_f32_e32 v86, v86
	v_rcp_f32_e32 v87, v87
	v_perm_b32 v82, v83, v82, s58
	v_max_f32_e32 v83, 0x4b000001, v85
	v_max_f32_e32 v84, 0x4b000001, v84
	v_rcp_f32_e32 v96, v96
	v_rcp_f32_e32 v97, v97
	v_perm_b32 v100, v95, v94, s58
	v_rcp_f32_e32 v94, v90
	v_rcp_f32_e32 v95, v91
	v_rcp_f32_e32 v88, v88
	v_rcp_f32_e32 v89, v89
	v_perm_b32 v83, v83, v84, s58
	v_pk_fma_f32 v[92:93], v[92:93], s[26:27], v[126:127] op_sel_hi:[1,0,0]
	v_pk_fma_f32 v[86:87], v[86:87], s[26:27], v[126:127] op_sel_hi:[1,0,0]
	v_pk_fma_f32 v[96:97], v[96:97], s[26:27], v[126:127] op_sel_hi:[1,0,0]
	v_pk_fma_f32 v[94:95], v[94:95], s[26:27], v[126:127] op_sel_hi:[1,0,0]
	v_max_f32_e32 v93, 0x4b000001, v93
	v_max_f32_e32 v92, 0x4b000001, v92
	v_pk_fma_f32 v[88:89], v[88:89], s[26:27], v[126:127] op_sel_hi:[1,0,0]
	v_max_f32_e32 v87, 0x4b000001, v87
	v_max_f32_e32 v86, 0x4b000001, v86
	v_mad_i64_i32 v[98:99], s[2:3], v207, s57, v[142:143]
	v_max_f32_e32 v97, 0x4b000001, v97
	v_max_f32_e32 v96, 0x4b000001, v96
	v_max_f32_e32 v91, 0x4b000001, v95
	v_max_f32_e32 v94, 0x4b000001, v94
	v_perm_b32 v92, v93, v92, s58
	v_perm_b32 v86, v87, v86, s58
	v_max_f32_e32 v87, 0x4b000001, v89
	v_max_f32_e32 v88, 0x4b000001, v88
	v_lshl_or_b32 v93, v83, 16, v82
	v_lshl_add_u64 v[98:99], v[98:99], 0, s[0:1]
	v_perm_b32 v90, v97, v96, s58
	v_perm_b32 v91, v91, v94, s58
	v_perm_b32 v87, v87, v88, s58
	v_lshl_add_u64 v[98:99], v[98:99], 0, v[154:155]
	v_lshl_or_b32 v90, v90, 16, v100
	v_lshl_or_b32 v91, v92, 16, v91
	v_lshl_or_b32 v92, v87, 16, v86
	global_store_dwordx4 v[98:99], v[90:93], off
	v_pk_mul_f32 v[66:67], v[130:131], v[66:67]
	v_pk_mul_f32 v[78:79], v[174:175], v[78:79]
	v_pk_mul_f32 v[68:69], v[132:133], v[68:69]
	v_pk_fma_f32 v[66:67], v[66:67], v[184:185], v[128:129] op_sel_hi:[1,0,1]
	v_pk_fma_f32 v[78:79], v[78:79], v[184:185], v[172:173] op_sel_hi:[1,0,1]
	v_pk_fma_f32 v[68:69], v[68:69], v[184:185], v[124:125] op_sel_hi:[1,0,1]
	v_exp_f32_e32 v66, v66
	v_exp_f32_e32 v67, v67
	v_exp_f32_e32 v78, v78
	v_exp_f32_e32 v79, v79
	v_exp_f32_e32 v68, v68
	v_exp_f32_e32 v69, v69
	v_pk_mul_f32 v[76:77], v[168:169], v[76:77]
	v_pk_mul_f32 v[70:71], v[138:139], v[70:71]
	v_pk_add_f32 v[66:67], v[66:67], 1.0 op_sel_hi:[1,0]
	v_pk_mul_f32 v[80:81], v[176:177], v[80:81]
	v_pk_add_f32 v[78:79], v[78:79], 1.0 op_sel_hi:[1,0]
	v_pk_mul_f32 v[74:75], v[166:167], v[74:75]
	v_pk_fma_f32 v[76:77], v[76:77], v[184:185], v[144:145] op_sel_hi:[1,0,1]
	v_pk_mul_f32 v[72:73], v[140:141], v[72:73]
	v_pk_fma_f32 v[70:71], v[70:71], v[184:185], v[136:137] op_sel_hi:[1,0,1]
	v_pk_add_f32 v[68:69], v[68:69], 1.0 op_sel_hi:[1,0]
	v_rcp_f32_e32 v66, v66
	v_rcp_f32_e32 v67, v67
	v_pk_fma_f32 v[80:81], v[80:81], v[184:185], v[170:171] op_sel_hi:[1,0,1]
	v_rcp_f32_e32 v78, v78
	v_rcp_f32_e32 v79, v79
	v_pk_fma_f32 v[74:75], v[74:75], v[184:185], v[164:165] op_sel_hi:[1,0,1]
	v_exp_f32_e32 v76, v76
	v_exp_f32_e32 v77, v77
	v_pk_fma_f32 v[72:73], v[72:73], v[184:185], v[134:135] op_sel_hi:[1,0,1]
	v_exp_f32_e32 v70, v70
	v_exp_f32_e32 v71, v71
	v_rcp_f32_e32 v68, v68
	v_rcp_f32_e32 v69, v69
	v_exp_f32_e32 v80, v80
	v_exp_f32_e32 v81, v81
	v_exp_f32_e32 v74, v74
	v_exp_f32_e32 v75, v75
	v_exp_f32_e32 v72, v72
	v_exp_f32_e32 v73, v73
	v_pk_fma_f32 v[66:67], v[66:67], s[26:27], v[126:127] op_sel_hi:[1,0,0]
	v_pk_fma_f32 v[78:79], v[78:79], s[26:27], v[126:127] op_sel_hi:[1,0,0]
	v_pk_add_f32 v[76:77], v[76:77], 1.0 op_sel_hi:[1,0]
	v_pk_add_f32 v[70:71], v[70:71], 1.0 op_sel_hi:[1,0]
	v_pk_fma_f32 v[68:69], v[68:69], s[26:27], v[126:127] op_sel_hi:[1,0,0]
	v_max_f32_e32 v67, 0x4b000001, v67
	v_max_f32_e32 v66, 0x4b000001, v66
	v_pk_add_f32 v[80:81], v[80:81], 1.0 op_sel_hi:[1,0]
	v_max_f32_e32 v79, 0x4b000001, v79
	v_max_f32_e32 v78, 0x4b000001, v78
	v_pk_add_f32 v[74:75], v[74:75], 1.0 op_sel_hi:[1,0]
	v_rcp_f32_e32 v76, v76
	v_rcp_f32_e32 v77, v77
	v_pk_add_f32 v[72:73], v[72:73], 1.0 op_sel_hi:[1,0]
	v_rcp_f32_e32 v70, v70
	v_rcp_f32_e32 v71, v71
	v_perm_b32 v66, v67, v66, s58
	v_max_f32_e32 v67, 0x4b000001, v69
	v_max_f32_e32 v68, 0x4b000001, v68
	v_rcp_f32_e32 v80, v80
	v_rcp_f32_e32 v81, v81
	v_perm_b32 v84, v79, v78, s58
	v_rcp_f32_e32 v78, v74
	v_rcp_f32_e32 v79, v75
	v_rcp_f32_e32 v72, v72
	v_rcp_f32_e32 v73, v73
	v_perm_b32 v67, v67, v68, s58
	v_pk_fma_f32 v[76:77], v[76:77], s[26:27], v[126:127] op_sel_hi:[1,0,0]
	v_pk_fma_f32 v[70:71], v[70:71], s[26:27], v[126:127] op_sel_hi:[1,0,0]
	v_pk_fma_f32 v[80:81], v[80:81], s[26:27], v[126:127] op_sel_hi:[1,0,0]
	v_pk_fma_f32 v[78:79], v[78:79], s[26:27], v[126:127] op_sel_hi:[1,0,0]
	v_max_f32_e32 v77, 0x4b000001, v77
	v_max_f32_e32 v76, 0x4b000001, v76
	v_pk_fma_f32 v[72:73], v[72:73], s[26:27], v[126:127] op_sel_hi:[1,0,0]
	v_max_f32_e32 v71, 0x4b000001, v71
	v_max_f32_e32 v70, 0x4b000001, v70
	v_mad_i64_i32 v[82:83], s[2:3], v192, s57, v[142:143]
	v_max_f32_e32 v81, 0x4b000001, v81
	v_max_f32_e32 v80, 0x4b000001, v80
	v_max_f32_e32 v75, 0x4b000001, v79
	v_max_f32_e32 v78, 0x4b000001, v78
	v_perm_b32 v76, v77, v76, s58
	v_perm_b32 v70, v71, v70, s58
	v_max_f32_e32 v71, 0x4b000001, v73
	v_max_f32_e32 v72, 0x4b000001, v72
	v_lshl_or_b32 v77, v67, 16, v66
	v_lshl_add_u64 v[82:83], v[82:83], 0, s[0:1]
	v_perm_b32 v74, v81, v80, s58
;     __device__ __forceinline__ void operator()(const f32x4 (&acc)[2][2][4][2], const Unit& u, int wr, int wc, int fr, int fq) const {
;     ...
; #pragma unroll
;         for (int ai = 0; ai < 2; ++ai)
; #pragma unroll
;             for (int m = 0; m < 4; ++m) { unsigned char* rowp = O + (size_t)(row0 + ai * HALF + m * 16) * 8704 + gbase + (col0 & 1023);
;                 const float rs = rsv[ai * 4 + m];
;                 u32x4 w; EPG_Q4(w.x, acc[ai][0][m][0], wv[0][0], rs, bv[0][0]); EPG_Q4(w.y, acc[ai][0][m][1], wv[0][1], rs, bv[0][1]);
;                 EPG_Q4(w.z, acc[ai][1][m][0], wv[1][0], rs, bv[1][0]); EPG_Q4(w.w, acc[ai][1][m][1], wv[1][1], rs, bv[1][1]);
;                 *(u32x4*)rowp = w; }
	v_perm_b32 v75, v75, v78, s58
	v_perm_b32 v71, v71, v72, s58
	v_lshl_add_u64 v[82:83], v[82:83], 0, v[154:155]
	v_lshl_or_b32 v74, v74, 16, v84
	v_lshl_or_b32 v75, v76, 16, v75
	v_lshl_or_b32 v76, v71, 16, v70
	global_store_dwordx4 v[82:83], v[74:77], off
	v_pk_mul_f32 v[50:51], v[130:131], v[50:51]
	v_pk_mul_f32 v[62:63], v[174:175], v[62:63]
	v_pk_mul_f32 v[52:53], v[132:133], v[52:53]
	v_pk_fma_f32 v[50:51], v[50:51], v[182:183], v[128:129] op_sel_hi:[1,0,1]
	v_pk_fma_f32 v[62:63], v[62:63], v[182:183], v[172:173] op_sel_hi:[1,0,1]
	v_pk_fma_f32 v[52:53], v[52:53], v[182:183], v[124:125] op_sel_hi:[1,0,1]
	v_exp_f32_e32 v50, v50
	v_exp_f32_e32 v51, v51
	v_exp_f32_e32 v62, v62
	v_exp_f32_e32 v63, v63
	v_exp_f32_e32 v52, v52
	v_exp_f32_e32 v53, v53
	v_pk_mul_f32 v[60:61], v[168:169], v[60:61]
	v_pk_mul_f32 v[54:55], v[138:139], v[54:55]
	v_pk_add_f32 v[50:51], v[50:51], 1.0 op_sel_hi:[1,0]
	v_pk_mul_f32 v[64:65], v[176:177], v[64:65]
	v_pk_add_f32 v[62:63], v[62:63], 1.0 op_sel_hi:[1,0]
	v_pk_mul_f32 v[58:59], v[166:167], v[58:59]
	v_pk_fma_f32 v[60:61], v[60:61], v[182:183], v[144:145] op_sel_hi:[1,0,1]
	v_pk_mul_f32 v[56:57], v[140:141], v[56:57]
	v_pk_fma_f32 v[54:55], v[54:55], v[182:183], v[136:137] op_sel_hi:[1,0,1]
	v_pk_add_f32 v[52:53], v[52:53], 1.0 op_sel_hi:[1,0]
	v_rcp_f32_e32 v50, v50
	v_rcp_f32_e32 v51, v51
	v_pk_fma_f32 v[64:65], v[64:65], v[182:183], v[170:171] op_sel_hi:[1,0,1]
	v_rcp_f32_e32 v62, v62
	v_rcp_f32_e32 v63, v63
	v_pk_fma_f32 v[58:59], v[58:59], v[182:183], v[164:165] op_sel_hi:[1,0,1]
	v_exp_f32_e32 v60, v60
	v_exp_f32_e32 v61, v61
	v_pk_fma_f32 v[56:57], v[56:57], v[182:183], v[134:135] op_sel_hi:[1,0,1]
	v_exp_f32_e32 v54, v54
	v_exp_f32_e32 v55, v55
	v_rcp_f32_e32 v52, v52
	v_rcp_f32_e32 v53, v53
	v_exp_f32_e32 v64, v64
	v_exp_f32_e32 v65, v65
	v_exp_f32_e32 v58, v58
	v_exp_f32_e32 v59, v59
	v_exp_f32_e32 v56, v56
	v_exp_f32_e32 v57, v57
	v_pk_fma_f32 v[50:51], v[50:51], s[26:27], v[126:127] op_sel_hi:[1,0,0]
	v_pk_fma_f32 v[62:63], v[62:63], s[26:27], v[126:127] op_sel_hi:[1,0,0]
	v_pk_add_f32 v[60:61], v[60:61], 1.0 op_sel_hi:[1,0]
	v_pk_add_f32 v[54:55], v[54:55], 1.0 op_sel_hi:[1,0]
	v_pk_fma_f32 v[52:53], v[52:53], s[26:27], v[126:127] op_sel_hi:[1,0,0]
	v_max_f32_e32 v51, 0x4b000001, v51
	v_max_f32_e32 v50, 0x4b000001, v50
	v_pk_add_f32 v[64:65], v[64:65], 1.0 op_sel_hi:[1,0]
	v_max_f32_e32 v63, 0x4b000001, v63
	v_max_f32_e32 v62, 0x4b000001, v62
	v_pk_add_f32 v[58:59], v[58:59], 1.0 op_sel_hi:[1,0]
	v_rcp_f32_e32 v60, v60
	v_rcp_f32_e32 v61, v61
	v_pk_add_f32 v[56:57], v[56:57], 1.0 op_sel_hi:[1,0]
	v_rcp_f32_e32 v54, v54
	v_rcp_f32_e32 v55, v55
	v_perm_b32 v50, v51, v50, s58
	v_max_f32_e32 v51, 0x4b000001, v53
	v_max_f32_e32 v52, 0x4b000001, v52
	v_rcp_f32_e32 v64, v64
	v_rcp_f32_e32 v65, v65
	v_perm_b32 v68, v63, v62, s58
	v_rcp_f32_e32 v62, v58
	v_rcp_f32_e32 v63, v59
	v_rcp_f32_e32 v56, v56
	v_rcp_f32_e32 v57, v57
	v_perm_b32 v51, v51, v52, s58
	v_pk_fma_f32 v[60:61], v[60:61], s[26:27], v[126:127] op_sel_hi:[1,0,0]
	v_pk_fma_f32 v[54:55], v[54:55], s[26:27], v[126:127] op_sel_hi:[1,0,0]
	v_pk_fma_f32 v[64:65], v[64:65], s[26:27], v[126:127] op_sel_hi:[1,0,0]
	v_pk_fma_f32 v[62:63], v[62:63], s[26:27], v[126:127] op_sel_hi:[1,0,0]
	v_max_f32_e32 v61, 0x4b000001, v61
	v_max_f32_e32 v60, 0x4b000001, v60
	v_pk_fma_f32 v[56:57], v[56:57], s[26:27], v[126:127] op_sel_hi:[1,0,0]
	v_max_f32_e32 v55, 0x4b000001, v55
	v_max_f32_e32 v54, 0x4b000001, v54
	v_mad_i64_i32 v[66:67], s[2:3], v191, s57, v[142:143]
	v_max_f32_e32 v65, 0x4b000001, v65
	v_max_f32_e32 v64, 0x4b000001, v64
	v_max_f32_e32 v59, 0x4b000001, v63
	v_max_f32_e32 v62, 0x4b000001, v62
	v_perm_b32 v60, v61, v60, s58
	v_perm_b32 v54, v55, v54, s58
	v_max_f32_e32 v55, 0x4b000001, v57
	v_max_f32_e32 v56, 0x4b000001, v56
	v_lshl_or_b32 v61, v51, 16, v50
	v_lshl_add_u64 v[66:67], v[66:67], 0, s[0:1]
	v_perm_b32 v58, v65, v64, s58
	v_perm_b32 v59, v59, v62, s58
	v_perm_b32 v55, v55, v56, s58
	v_lshl_add_u64 v[66:67], v[66:67], 0, v[154:155]
	v_lshl_or_b32 v58, v58, 16, v68
	v_lshl_or_b32 v59, v60, 16, v59
	v_lshl_or_b32 v60, v55, 16, v54
	global_store_dwordx4 v[66:67], v[58:61], off
	v_pk_mul_f32 v[34:35], v[130:131], v[34:35]
	v_pk_mul_f32 v[46:47], v[174:175], v[46:47]
	v_pk_mul_f32 v[36:37], v[132:133], v[36:37]
	v_pk_fma_f32 v[34:35], v[34:35], v[180:181], v[128:129] op_sel_hi:[1,0,1]
	v_pk_fma_f32 v[46:47], v[46:47], v[180:181], v[172:173] op_sel_hi:[1,0,1]
	v_pk_fma_f32 v[36:37], v[36:37], v[180:181], v[124:125] op_sel_hi:[1,0,1]
	v_exp_f32_e32 v34, v34
	v_exp_f32_e32 v35, v35
	v_exp_f32_e32 v46, v46
	v_exp_f32_e32 v47, v47
	v_exp_f32_e32 v36, v36
	v_exp_f32_e32 v37, v37
	v_pk_mul_f32 v[44:45], v[168:169], v[44:45]
	v_pk_mul_f32 v[38:39], v[138:139], v[38:39]
	v_pk_add_f32 v[34:35], v[34:35], 1.0 op_sel_hi:[1,0]
	v_pk_mul_f32 v[48:49], v[176:177], v[48:49]
	v_pk_add_f32 v[46:47], v[46:47], 1.0 op_sel_hi:[1,0]
	v_pk_mul_f32 v[42:43], v[166:167], v[42:43]
	v_pk_fma_f32 v[44:45], v[44:45], v[180:181], v[144:145] op_sel_hi:[1,0,1]
	v_pk_mul_f32 v[40:41], v[140:141], v[40:41]
	v_pk_fma_f32 v[38:39], v[38:39], v[180:181], v[136:137] op_sel_hi:[1,0,1]
	v_pk_add_f32 v[36:37], v[36:37], 1.0 op_sel_hi:[1,0]
	v_rcp_f32_e32 v34, v34
	v_rcp_f32_e32 v35, v35
	v_pk_fma_f32 v[48:49], v[48:49], v[180:181], v[170:171] op_sel_hi:[1,0,1]
	v_rcp_f32_e32 v46, v46
	v_rcp_f32_e32 v47, v47
	v_pk_fma_f32 v[42:43], v[42:43], v[180:181], v[164:165] op_sel_hi:[1,0,1]
	v_exp_f32_e32 v44, v44
	v_exp_f32_e32 v45, v45
	v_pk_fma_f32 v[40:41], v[40:41], v[180:181], v[134:135] op_sel_hi:[1,0,1]
	v_exp_f32_e32 v38, v38
	v_exp_f32_e32 v39, v39
	v_rcp_f32_e32 v36, v36
;     __device__ __forceinline__ void operator()(const f32x4 (&acc)[2][2][4][2], const Unit& u, int wr, int wc, int fr, int fq) const {
;     ...
; #pragma unroll
;         for (int ai = 0; ai < 2; ++ai)
; #pragma unroll
;             for (int m = 0; m < 4; ++m) { unsigned char* rowp = O + (size_t)(row0 + ai * HALF + m * 16) * 8704 + gbase + (col0 & 1023);
;                 const float rs = rsv[ai * 4 + m];
;                 u32x4 w; EPG_Q4(w.x, acc[ai][0][m][0], wv[0][0], rs, bv[0][0]); EPG_Q4(w.y, acc[ai][0][m][1], wv[0][1], rs, bv[0][1]);
;                 EPG_Q4(w.z, acc[ai][1][m][0], wv[1][0], rs, bv[1][0]); EPG_Q4(w.w, acc[ai][1][m][1], wv[1][1], rs, bv[1][1]);
;                 *(u32x4*)rowp = w; }
	v_rcp_f32_e32 v37, v37
	v_exp_f32_e32 v48, v48
	v_exp_f32_e32 v49, v49
	v_exp_f32_e32 v42, v42
	v_exp_f32_e32 v43, v43
	v_exp_f32_e32 v40, v40
	v_exp_f32_e32 v41, v41
	v_pk_fma_f32 v[34:35], v[34:35], s[26:27], v[126:127] op_sel_hi:[1,0,0]
	v_pk_fma_f32 v[46:47], v[46:47], s[26:27], v[126:127] op_sel_hi:[1,0,0]
	v_pk_add_f32 v[44:45], v[44:45], 1.0 op_sel_hi:[1,0]
	v_pk_add_f32 v[38:39], v[38:39], 1.0 op_sel_hi:[1,0]
	v_pk_fma_f32 v[36:37], v[36:37], s[26:27], v[126:127] op_sel_hi:[1,0,0]
	v_max_f32_e32 v35, 0x4b000001, v35
	v_max_f32_e32 v34, 0x4b000001, v34
	v_pk_add_f32 v[48:49], v[48:49], 1.0 op_sel_hi:[1,0]
	v_max_f32_e32 v47, 0x4b000001, v47
	v_max_f32_e32 v46, 0x4b000001, v46
	v_pk_add_f32 v[42:43], v[42:43], 1.0 op_sel_hi:[1,0]
	v_rcp_f32_e32 v44, v44
	v_rcp_f32_e32 v45, v45
	v_pk_add_f32 v[40:41], v[40:41], 1.0 op_sel_hi:[1,0]
	v_rcp_f32_e32 v38, v38
	v_rcp_f32_e32 v39, v39
	v_perm_b32 v34, v35, v34, s58
	v_max_f32_e32 v35, 0x4b000001, v37
	v_max_f32_e32 v36, 0x4b000001, v36
	v_rcp_f32_e32 v48, v48
	v_rcp_f32_e32 v49, v49
	v_perm_b32 v52, v47, v46, s58
	v_rcp_f32_e32 v46, v42
	v_rcp_f32_e32 v47, v43
	v_rcp_f32_e32 v40, v40
	v_rcp_f32_e32 v41, v41
	v_perm_b32 v35, v35, v36, s58
	v_pk_fma_f32 v[44:45], v[44:45], s[26:27], v[126:127] op_sel_hi:[1,0,0]
	v_pk_fma_f32 v[38:39], v[38:39], s[26:27], v[126:127] op_sel_hi:[1,0,0]
	v_pk_fma_f32 v[48:49], v[48:49], s[26:27], v[126:127] op_sel_hi:[1,0,0]
	v_pk_fma_f32 v[46:47], v[46:47], s[26:27], v[126:127] op_sel_hi:[1,0,0]
	v_max_f32_e32 v45, 0x4b000001, v45
	v_max_f32_e32 v44, 0x4b000001, v44
	v_pk_fma_f32 v[40:41], v[40:41], s[26:27], v[126:127] op_sel_hi:[1,0,0]
	v_max_f32_e32 v39, 0x4b000001, v39
	v_max_f32_e32 v38, 0x4b000001, v38
	v_mad_i64_i32 v[50:51], s[2:3], v190, s57, v[142:143]
	v_max_f32_e32 v49, 0x4b000001, v49
	v_max_f32_e32 v48, 0x4b000001, v48
	v_max_f32_e32 v43, 0x4b000001, v47
	v_max_f32_e32 v46, 0x4b000001, v46
	v_perm_b32 v44, v45, v44, s58
	v_perm_b32 v38, v39, v38, s58
	v_max_f32_e32 v39, 0x4b000001, v41
	v_max_f32_e32 v40, 0x4b000001, v40
	v_lshl_or_b32 v45, v35, 16, v34
	v_lshl_add_u64 v[50:51], v[50:51], 0, s[0:1]
	v_perm_b32 v42, v49, v48, s58
	v_perm_b32 v43, v43, v46, s58
	v_perm_b32 v39, v39, v40, s58
	v_lshl_add_u64 v[50:51], v[50:51], 0, v[154:155]
	v_lshl_or_b32 v42, v42, 16, v52
	v_lshl_or_b32 v43, v44, 16, v43
	v_lshl_or_b32 v44, v39, 16, v38
	global_store_dwordx4 v[50:51], v[42:45], off
	v_pk_mul_f32 v[18:19], v[130:131], v[18:19]
	v_pk_mul_f32 v[30:31], v[174:175], v[30:31]
	v_pk_mul_f32 v[20:21], v[132:133], v[20:21]
	v_pk_fma_f32 v[18:19], v[18:19], v[178:179], v[128:129] op_sel_hi:[1,0,1]
	v_pk_fma_f32 v[30:31], v[30:31], v[178:179], v[172:173] op_sel_hi:[1,0,1]
	v_pk_fma_f32 v[20:21], v[20:21], v[178:179], v[124:125] op_sel_hi:[1,0,1]
	v_exp_f32_e32 v18, v18
	v_exp_f32_e32 v19, v19
	v_exp_f32_e32 v30, v30
	v_exp_f32_e32 v31, v31
	v_exp_f32_e32 v20, v20
	v_exp_f32_e32 v21, v21
	v_pk_mul_f32 v[28:29], v[168:169], v[28:29]
	v_pk_mul_f32 v[22:23], v[138:139], v[22:23]
	v_pk_add_f32 v[18:19], v[18:19], 1.0 op_sel_hi:[1,0]
	v_pk_mul_f32 v[32:33], v[176:177], v[32:33]
	v_pk_add_f32 v[30:31], v[30:31], 1.0 op_sel_hi:[1,0]
	v_pk_mul_f32 v[26:27], v[166:167], v[26:27]
	v_pk_fma_f32 v[28:29], v[28:29], v[178:179], v[144:145] op_sel_hi:[1,0,1]
	v_pk_mul_f32 v[24:25], v[140:141], v[24:25]
	v_pk_fma_f32 v[22:23], v[22:23], v[178:179], v[136:137] op_sel_hi:[1,0,1]
	v_pk_add_f32 v[20:21], v[20:21], 1.0 op_sel_hi:[1,0]
	v_rcp_f32_e32 v18, v18
	v_rcp_f32_e32 v19, v19
	v_pk_fma_f32 v[32:33], v[32:33], v[178:179], v[170:171] op_sel_hi:[1,0,1]
	v_rcp_f32_e32 v30, v30
	v_rcp_f32_e32 v31, v31
	v_pk_fma_f32 v[26:27], v[26:27], v[178:179], v[164:165] op_sel_hi:[1,0,1]
	v_exp_f32_e32 v28, v28
	v_exp_f32_e32 v29, v29
	v_pk_fma_f32 v[24:25], v[24:25], v[178:179], v[134:135] op_sel_hi:[1,0,1]
	v_exp_f32_e32 v22, v22
	v_exp_f32_e32 v23, v23
	v_rcp_f32_e32 v20, v20
	v_rcp_f32_e32 v21, v21
	v_exp_f32_e32 v32, v32
	v_exp_f32_e32 v33, v33
	v_exp_f32_e32 v26, v26
	v_exp_f32_e32 v27, v27
	v_exp_f32_e32 v24, v24
	v_exp_f32_e32 v25, v25
	v_pk_fma_f32 v[18:19], v[18:19], s[26:27], v[126:127] op_sel_hi:[1,0,0]
	v_pk_fma_f32 v[30:31], v[30:31], s[26:27], v[126:127] op_sel_hi:[1,0,0]
	v_pk_add_f32 v[28:29], v[28:29], 1.0 op_sel_hi:[1,0]
	v_pk_add_f32 v[22:23], v[22:23], 1.0 op_sel_hi:[1,0]
	v_pk_fma_f32 v[20:21], v[20:21], s[26:27], v[126:127] op_sel_hi:[1,0,0]
	v_max_f32_e32 v19, 0x4b000001, v19
	v_max_f32_e32 v18, 0x4b000001, v18
	v_pk_add_f32 v[32:33], v[32:33], 1.0 op_sel_hi:[1,0]
	v_max_f32_e32 v31, 0x4b000001, v31
	v_max_f32_e32 v30, 0x4b000001, v30
	v_pk_add_f32 v[26:27], v[26:27], 1.0 op_sel_hi:[1,0]
	v_rcp_f32_e32 v28, v28
	v_rcp_f32_e32 v29, v29
	v_pk_add_f32 v[24:25], v[24:25], 1.0 op_sel_hi:[1,0]
	v_rcp_f32_e32 v22, v22
	v_rcp_f32_e32 v23, v23
	v_perm_b32 v18, v19, v18, s58
	v_max_f32_e32 v19, 0x4b000001, v21
	v_max_f32_e32 v20, 0x4b000001, v20
	v_rcp_f32_e32 v32, v32
	v_rcp_f32_e32 v33, v33
	v_perm_b32 v36, v31, v30, s58
	v_rcp_f32_e32 v30, v26
	v_rcp_f32_e32 v31, v27
	v_rcp_f32_e32 v24, v24
	v_rcp_f32_e32 v25, v25
	v_perm_b32 v19, v19, v20, s58
; #define PG8_BAR __builtin_amdgcn_s_barrier()
;     __device__ __forceinline__ void operator()(const f32x4 (&acc)[2][2][4][2], const Unit& u, int wr, int wc, int fr, int fq) const {
;     ...
; #pragma unroll
;         for (int ai = 0; ai < 2; ++ai)
; #pragma unroll
;             for (int m = 0; m < 4; ++m) { unsigned char* rowp = O + (size_t)(row0 + ai * HALF + m * 16) * 8704 + gbase + (col0 & 1023);
;                 const float rs = rsv[ai * 4 + m];
;                 u32x4 w; EPG_Q4(w.x, acc[ai][0][m][0], wv[0][0], rs, bv[0][0]); EPG_Q4(w.y, acc[ai][0][m][1], wv[0][1], rs, bv[0][1]);
;                 EPG_Q4(w.z, acc[ai][1][m][0], wv[1][0], rs, bv[1][0]); EPG_Q4(w.w, acc[ai][1][m][1], wv[1][1], rs, bv[1][1]);
;                 *(u32x4*)rowp = w; }
; template <class Epi, class Sched, class Gemm, bool ALIGN_EPI = false, bool SP2 = false>
; __device__ __forceinline__ void gemm_phase(PG8_LAS unsigned char* lds, const Gemm g, const Sched& S, const Epi& E) {
;     ...
;         if (!has_next) break;
;         if constexpr (!epi_chain<Epi>::value) {
; #pragma unroll
;         for (int a = 0; a < 2; ++a)
; #pragma unroll
;             for (int b = 0; b < 2; ++b)
; #pragma unroll
;                 for (int m = 0; m < 4; ++m)
; #pragma unroll
;                     for (int n = 0; n < 2; ++n) acc[a][b][m][n] = (f32x4){0.f, 0.f, 0.f, 0.f};
;         }
;         cur = nxt; cA = nA; cB = nB; ++ui;
;         if constexpr (ALIGN_EPI) { if (wr == 1) PG8_BAR; }
	v_pk_fma_f32 v[28:29], v[28:29], s[26:27], v[126:127] op_sel_hi:[1,0,0]
	v_pk_fma_f32 v[22:23], v[22:23], s[26:27], v[126:127] op_sel_hi:[1,0,0]
	v_pk_fma_f32 v[32:33], v[32:33], s[26:27], v[126:127] op_sel_hi:[1,0,0]
	v_pk_fma_f32 v[30:31], v[30:31], s[26:27], v[126:127] op_sel_hi:[1,0,0]
	v_max_f32_e32 v29, 0x4b000001, v29
	v_max_f32_e32 v28, 0x4b000001, v28
	v_pk_fma_f32 v[24:25], v[24:25], s[26:27], v[126:127] op_sel_hi:[1,0,0]
	v_max_f32_e32 v23, 0x4b000001, v23
	v_max_f32_e32 v22, 0x4b000001, v22
	v_mad_i64_i32 v[34:35], s[2:3], v189, s57, v[142:143]
	v_max_f32_e32 v33, 0x4b000001, v33
	v_max_f32_e32 v32, 0x4b000001, v32
	v_max_f32_e32 v27, 0x4b000001, v31
	v_max_f32_e32 v30, 0x4b000001, v30
	v_perm_b32 v28, v29, v28, s58
	v_perm_b32 v22, v23, v22, s58
	v_max_f32_e32 v23, 0x4b000001, v25
	v_max_f32_e32 v24, 0x4b000001, v24
	v_lshl_or_b32 v29, v19, 16, v18
	v_lshl_add_u64 v[34:35], v[34:35], 0, s[0:1]
	v_perm_b32 v26, v33, v32, s58
	v_perm_b32 v27, v27, v30, s58
	v_perm_b32 v23, v23, v24, s58
	v_lshl_add_u64 v[34:35], v[34:35], 0, v[154:155]
	v_lshl_or_b32 v26, v26, 16, v36
	v_lshl_or_b32 v27, v28, 16, v27
	v_lshl_or_b32 v28, v23, 16, v22
	global_store_dwordx4 v[34:35], v[26:29], off
	v_pk_mul_f32 v[14:15], v[174:175], v[14:15]
	v_pk_fma_f32 v[14:15], v[14:15], v[122:123], v[172:173] op_sel_hi:[1,0,1]
	v_exp_f32_e32 v14, v14
	v_exp_f32_e32 v15, v15
	v_pk_mul_f32 v[6:7], v[138:139], v[6:7]
	v_pk_mul_f32 v[2:3], v[130:131], v[2:3]
	v_pk_mul_f32 v[16:17], v[176:177], v[16:17]
	v_pk_add_f32 v[14:15], v[14:15], 1.0 op_sel_hi:[1,0]
	v_pk_mul_f32 v[12:13], v[168:169], v[12:13]
	v_pk_mul_f32 v[10:11], v[166:167], v[10:11]
	v_pk_mul_f32 v[8:9], v[140:141], v[8:9]
	v_pk_fma_f32 v[6:7], v[6:7], v[122:123], v[136:137] op_sel_hi:[1,0,1]
	v_pk_mul_f32 v[4:5], v[132:133], v[4:5]
	v_pk_fma_f32 v[2:3], v[2:3], v[122:123], v[128:129] op_sel_hi:[1,0,1]
	v_pk_fma_f32 v[16:17], v[16:17], v[122:123], v[170:171] op_sel_hi:[1,0,1]
	v_rcp_f32_e32 v14, v14
	v_rcp_f32_e32 v15, v15
	v_pk_fma_f32 v[12:13], v[12:13], v[122:123], v[144:145] op_sel_hi:[1,0,1]
	v_pk_fma_f32 v[10:11], v[10:11], v[122:123], v[164:165] op_sel_hi:[1,0,1]
	v_pk_fma_f32 v[8:9], v[8:9], v[122:123], v[134:135] op_sel_hi:[1,0,1]
	v_exp_f32_e32 v6, v6
	v_exp_f32_e32 v7, v7
	v_pk_fma_f32 v[4:5], v[4:5], v[122:123], v[124:125] op_sel_hi:[1,0,1]
	v_exp_f32_e32 v2, v2
	v_exp_f32_e32 v3, v3
	v_exp_f32_e32 v16, v16
	v_exp_f32_e32 v17, v17
	v_exp_f32_e32 v10, v10
	v_exp_f32_e32 v12, v12
	v_exp_f32_e32 v13, v13
	v_exp_f32_e32 v11, v11
	v_exp_f32_e32 v8, v8
	v_exp_f32_e32 v9, v9
	v_exp_f32_e32 v4, v4
	v_exp_f32_e32 v5, v5
	v_pk_fma_f32 v[14:15], v[14:15], s[26:27], v[126:127] op_sel_hi:[1,0,0]
	v_pk_add_f32 v[6:7], v[6:7], 1.0 op_sel_hi:[1,0]
	v_pk_add_f32 v[2:3], v[2:3], 1.0 op_sel_hi:[1,0]
	v_pk_add_f32 v[16:17], v[16:17], 1.0 op_sel_hi:[1,0]
	v_max_f32_e32 v15, 0x4b000001, v15
	v_max_f32_e32 v14, 0x4b000001, v14
	v_pk_add_f32 v[12:13], v[12:13], 1.0 op_sel_hi:[1,0]
	v_pk_add_f32 v[10:11], v[10:11], 1.0 op_sel_hi:[1,0]
	v_pk_add_f32 v[8:9], v[8:9], 1.0 op_sel_hi:[1,0]
	v_rcp_f32_e32 v6, v6
	v_rcp_f32_e32 v7, v7
	v_pk_add_f32 v[4:5], v[4:5], 1.0 op_sel_hi:[1,0]
	v_rcp_f32_e32 v2, v2
	v_rcp_f32_e32 v3, v3
	v_rcp_f32_e32 v16, v16
	v_rcp_f32_e32 v17, v17
	v_perm_b32 v20, v15, v14, s58
	v_rcp_f32_e32 v14, v10
	v_rcp_f32_e32 v12, v12
	v_rcp_f32_e32 v13, v13
	v_rcp_f32_e32 v15, v11
	v_rcp_f32_e32 v8, v8
	v_rcp_f32_e32 v9, v9
	v_rcp_f32_e32 v4, v4
	v_rcp_f32_e32 v5, v5
	v_pk_fma_f32 v[6:7], v[6:7], s[26:27], v[126:127] op_sel_hi:[1,0,0]
	v_pk_fma_f32 v[2:3], v[2:3], s[26:27], v[126:127] op_sel_hi:[1,0,0]
	v_pk_fma_f32 v[16:17], v[16:17], s[26:27], v[126:127] op_sel_hi:[1,0,0]
	v_pk_fma_f32 v[12:13], v[12:13], s[26:27], v[126:127] op_sel_hi:[1,0,0]
	v_pk_fma_f32 v[14:15], v[14:15], s[26:27], v[126:127] op_sel_hi:[1,0,0]
	v_pk_fma_f32 v[8:9], v[8:9], s[26:27], v[126:127] op_sel_hi:[1,0,0]
	v_max_f32_e32 v7, 0x4b000001, v7
	v_max_f32_e32 v6, 0x4b000001, v6
	v_pk_fma_f32 v[4:5], v[4:5], s[26:27], v[126:127] op_sel_hi:[1,0,0]
	v_max_f32_e32 v3, 0x4b000001, v3
	v_max_f32_e32 v2, 0x4b000001, v2
	v_mad_i64_i32 v[18:19], s[2:3], v123, s57, v[142:143]
	v_max_f32_e32 v17, 0x4b000001, v17
	v_max_f32_e32 v16, 0x4b000001, v16
	v_max_f32_e32 v11, 0x4b000001, v15
	v_max_f32_e32 v14, 0x4b000001, v14
	v_max_f32_e32 v13, 0x4b000001, v13
	v_max_f32_e32 v12, 0x4b000001, v12
	v_perm_b32 v6, v7, v6, s58
	v_max_f32_e32 v7, 0x4b000001, v9
	v_max_f32_e32 v8, 0x4b000001, v8
	v_perm_b32 v2, v3, v2, s58
	v_max_f32_e32 v3, 0x4b000001, v5
	v_max_f32_e32 v4, 0x4b000001, v4
	v_lshl_add_u64 v[18:19], v[18:19], 0, s[0:1]
	v_perm_b32 v10, v17, v16, s58
	v_perm_b32 v11, v11, v14, s58
	v_perm_b32 v12, v13, v12, s58
	v_perm_b32 v7, v7, v8, s58
	v_perm_b32 v3, v3, v4, s58
	v_lshl_add_u64 v[18:19], v[18:19], 0, v[154:155]
	v_lshl_or_b32 v10, v10, 16, v20
	v_lshl_or_b32 v11, v12, 16, v11
	v_lshl_or_b32 v12, v7, 16, v6
	v_lshl_or_b32 v13, v3, 16, v2
	global_store_dwordx4 v[18:19], v[10:13], off
	s_andn2_b64 vcc, exec, s[4:5]
	s_mov_b64 s[0:1], -1
	s_cbranch_vccnz .LBB0_1184
	s_andn2_b64 vcc, exec, s[6:7]
	s_cbranch_vccnz .LBB0_1183
	s_barrier
	s_branch .LBB0_1183

;     __device__ bool next(int i, Unit& u) const { const bool ok = StaticOrder::next(i >> 2, u); u.sub = i & 3; return ok; }
; #define PG8_STAGE(bufoff, gbase, voff) do { _Pragma("unroll") for (int _i = 0; _i < 2; ++_i) \
;         __builtin_amdgcn_global_load_lds((const unsigned*)((const char*)(gbase) + (voff)[_i]), (PG8_LAS unsigned*)(lds + (bufoff) + ldsw + _i * 8192), 16, 0, 0); } while (0)
; #define PG8_BAR __builtin_amdgcn_s_barrier()
; template <class Epi, class Sched, class Gemm, bool ALIGN_EPI = false, bool SP2 = false>
; __device__ __forceinline__ void gemm_phase(PG8_LAS unsigned char* lds, const Gemm g, const Sched& S, const Epi& E) {
;     ...
;     f32x4 acc[2][2][4][2];
; #pragma unroll
;     for (int a = 0; a < 2; ++a)
; #pragma unroll
;         for (int b = 0; b < 2; ++b)
; #pragma unroll
;             for (int m = 0; m < 4; ++m)
; #pragma unroll
;                 for (int n = 0; n < 2; ++n) acc[a][b][m][n] = (f32x4){0.f, 0.f, 0.f, 0.f};
;     bf16x8 At[4][2], B0[2][2], B1[2][2];
;     const char* cA = (const char*)g.A + (size_t)cur.pm * tstepA + (size_t)cur.sub * g.a_sub; const char* cB = (const char*)g.Bt + (size_t)cur.pn * tstepB + (size_t)cur.sub * g.b_sub;
;     S.a_ready(cur);
;     if constexpr (SP2) {
;         PG8_STAGE(PG8_SB(0, 0), cB, voffB); PG8_STAGE(PG8_SB(0, 1), cB + hB1, voffB1); PG8_STAGE(PG8_SA(0, 0), cA, voffA); PG8_STAGE(PG8_SA(0, 1), cA + hstepA, voffA);
;         if (wr == 1) PG8_BAR;
;         PG8_WAIT_V(2); PG8_BAR;
;         PG8_STAGE(PG8_SB(1, 0), cB + kstep, voffB); PG8_STAGE(PG8_SA(1, 0), cA + kstep, voffA); PG8_STAGE(PG8_SB(1, 1), cB + hB1 + kstep, voffB1);
;         PG8_WAIT_V(6); PG8_BAR;
;     } else {
;         PG8_STAGE(PG8_SB(0, 0), cB, voffB); PG8_STAGE(PG8_SA(0, 0), cA, voffA); PG8_STAGE(PG8_SB(0, 1), cB + hB1, voffB1); PG8_STAGE(PG8_SA(0, 1), cA + hstepA, voffA);
;         if (wr == 1) PG8_BAR;
;         PG8_WAIT_V(4); PG8_BAR;
;         PG8_STAGE(PG8_SB(1, 0), cB + kstep, voffB); PG8_STAGE(PG8_SA(1, 0), cA + kstep, voffA); PG8_STAGE(PG8_SB(1, 1), cB + hB1 + kstep, voffB1);
;         PG8_WAIT_V(6); PG8_BAR;
;     }
;     for (;;) {
;         const bool has_next = S.next(ui + 1, nxt);
;         const char* nA = has_next ? (const char*)g.A + (size_t)nxt.pm * tstepA + (size_t)nxt.sub * g.a_sub : cA; const char* nB = has_next ? (const char*)g.Bt + (size_t)nxt.pn * tstepB + (size_t)nxt.sub * g.b_sub : cB;
.LBB0_1369:
	s_ashr_i32 s39, s38, 31
	s_lshl_b64 s[6:7], s[38:39], 19
	s_add_u32 s40, s49, s6
	s_addc_u32 s41, s50, s7
	s_and_b64 s[6:7], s[4:5], exec
	s_cselect_b32 s9, s41, s3
	s_cselect_b32 s33, s40, s2
	s_ashr_i32 s37, s36, 31
	s_lshl_b64 s[6:7], s[36:37], 19
	s_add_u32 s42, s47, s6
	s_addc_u32 s43, s48, s7
	s_and_b64 s[6:7], s[4:5], exec
	s_cselect_b32 s37, s43, s1
	s_cselect_b32 s39, s42, s0
	s_add_u32 s45, s0, 0x100
	s_addc_u32 s71, s1, 0
	s_add_u32 s0, s2, 0x40080
	v_mov_b32_e32 v18, 0
	s_addc_u32 s1, s3, 0
	s_mov_b32 s72, -2
	v_mov_b32_e32 v19, v18
	v_mov_b64_e32 v[20:21], 0
	v_mov_b64_e32 v[22:23], 0
	v_mov_b64_e32 v[24:25], 0
	v_mov_b64_e32 v[34:35], 0
	v_mov_b64_e32 v[36:37], 0
	v_mov_b64_e32 v[38:39], 0
	v_mov_b64_e32 v[40:41], 0
	v_mov_b64_e32 v[50:51], 0
	v_mov_b64_e32 v[52:53], 0
	v_mov_b64_e32 v[54:55], 0
	v_mov_b64_e32 v[56:57], 0
	v_mov_b64_e32 v[66:67], 0
	v_mov_b64_e32 v[68:69], 0
	v_mov_b64_e32 v[70:71], 0
	v_mov_b64_e32 v[72:73], 0
	v_mov_b64_e32 v[26:27], 0
	v_mov_b64_e32 v[28:29], 0
	v_mov_b64_e32 v[30:31], 0
	v_mov_b64_e32 v[32:33], 0
	v_mov_b64_e32 v[42:43], 0
	v_mov_b64_e32 v[44:45], 0
	v_mov_b64_e32 v[46:47], 0
	v_mov_b64_e32 v[48:49], 0
	v_mov_b64_e32 v[58:59], 0
	v_mov_b64_e32 v[60:61], 0
	v_mov_b64_e32 v[62:63], 0
	v_mov_b64_e32 v[64:65], 0
	v_mov_b64_e32 v[74:75], 0
	v_mov_b64_e32 v[76:77], 0
	v_mov_b64_e32 v[78:79], 0
	v_mov_b64_e32 v[80:81], 0
	v_mov_b64_e32 v[126:127], 0
	v_mov_b64_e32 v[128:129], 0
	v_mov_b64_e32 v[134:135], 0
	v_mov_b64_e32 v[136:137], 0
	v_mov_b64_e32 v[114:115], 0
	v_mov_b64_e32 v[116:117], 0
	v_mov_b64_e32 v[118:119], 0
	v_mov_b64_e32 v[120:121], 0
	v_mov_b64_e32 v[98:99], 0
	v_mov_b64_e32 v[100:101], 0
	v_mov_b64_e32 v[102:103], 0
	v_mov_b64_e32 v[104:105], 0
	v_mov_b64_e32 v[82:83], 0
	v_mov_b64_e32 v[84:85], 0
	v_mov_b64_e32 v[86:87], 0
	v_mov_b64_e32 v[88:89], 0
	v_mov_b64_e32 v[138:139], 0
	v_mov_b64_e32 v[140:141], 0
	v_mov_b64_e32 v[142:143], 0
	v_mov_b64_e32 v[144:145], 0
	v_mov_b64_e32 v[122:123], 0
	v_mov_b64_e32 v[124:125], 0
	v_mov_b64_e32 v[130:131], 0
	v_mov_b64_e32 v[132:133], 0
	v_mov_b64_e32 v[106:107], 0
	v_mov_b64_e32 v[108:109], 0
	v_mov_b64_e32 v[110:111], 0
	v_mov_b64_e32 v[112:113], 0
	v_mov_b64_e32 v[90:91], 0
	v_mov_b64_e32 v[92:93], 0
	v_mov_b64_e32 v[94:95], 0
	v_mov_b64_e32 v[96:97], 0
	s_nop 0

; __device__ __forceinline__ void attn_phase_mfma(const Ctx& c, unsigned char* lds_raw, bool do_store) {
;     ...
;     ATT_PREFETCH(u);
;     for (;;) {
;         ATT_TABLES(u);
;         asm volatile("" ::: "memory");
;         const AttnU A = attn_decode(u);
;     ...
;         const int iq = i0 + 32 * wave + rq, posq = r + d * iq;
;         const size_t tokq = (size_t)b * SEQ + posq;
;         bf16_t* qrow = c.Z + tokq * DIN + ZQ + hh * 64;
;         bf16x8 qf[4];
;         {
;             const u32x4 q0 = qn[0], q1 = qn[1], q2 = qn[2], q3 = qn[3];
;             const h16x8 cav = tq[0], cbv = tq[1], sav = tq[2], sbv = tq[3];
;             const float sc = 0.125f * 1.44269504f;
;             u32x4 o0, o1, o2, o3;
;     #pragma unroll
;             for (int e = 0; e < 4; ++e) {
;                 const float ca_0 = (float)cav[2 * e], ca_1 = (float)cav[2 * e + 1], sa_0 = (float)sav[2 * e], sa_1 = (float)sav[2 * e + 1];
;                 const float cb_0 = (float)cbv[2 * e], cb_1 = (float)cbv[2 * e + 1], sb_0 = (float)sbv[2 * e], sb_1 = (float)sbv[2 * e + 1];
;                 const float a0 = bflo(q0[e]), a1 = bfhi(q0[e]), b0 = bflo(q2[e]), b1 = bfhi(q2[e]);
;                 const float e0 = bflo(q1[e]), e1 = bfhi(q1[e]), f0 = bflo(q3[e]), f1 = bfhi(q3[e]);
;                 o0[e] = pk2((a0 * ca_0 - b0 * sa_0) * sc, (a1 * ca_1 - b1 * sa_1) * sc);
;                 o2[e] = pk2((b0 * ca_0 + a0 * sa_0) * sc, (b1 * ca_1 + a1 * sa_1) * sc);
;                 o1[e] = pk2((e0 * cb_0 - f0 * sb_0) * sc, (e1 * cb_1 - f1 * sb_1) * sc);
;                 o3[e] = pk2((f0 * cb_0 + e0 * sb_0) * sc, (f1 * cb_1 + e1 * sb_1) * sc);
;             }
;             qf[0] = __builtin_bit_cast(bf16x8, o0); qf[1] = __builtin_bit_cast(bf16x8, o1); qf[2] = __builtin_bit_cast(bf16x8, o2); qf[3] = __builtin_bit_cast(bf16x8, o3);
;         }
; #pragma unroll
;         for (int i = 0; i < 3; ++i) {
;             const int id = t + 512 * i, row = id >> 2, dc = id & 3;
;             const h16x8 kcv = tkc[i], ksv = tks[i];
;             u32x4 olo, ohi;
; #pragma unroll
;             for (int e = 0; e < 4; ++e) {
;                 const float l0 = bflo(ka[i][e]), l1 = bfhi(ka[i][e]), h0 = bflo(kb2[i][e]), h1 = bfhi(kb2[i][e]);
;                 const float cc0 = (float)kcv[2 * e], cc1 = (float)kcv[2 * e + 1], ss0 = (float)ksv[2 * e], ss1 = (float)ksv[2 * e + 1];
.LBB0_1719:
	s_mul_hi_i32 s0, s33, 0x2aaaaaab
	s_lshr_b32 s1, s0, 31
	s_ashr_i32 s0, s0, 5
	s_add_i32 s0, s0, s1
	s_mul_i32 s1, s0, 0xffffff40
	s_add_i32 s1, s33, s1
	s_ashr_i32 s88, s1, 6
	s_lshl_b32 s96, s88, 1
	s_lshr_b32 s3, 16, s96
	s_and_b32 s2, s1, 15
	s_sub_i32 s9, 4, s96
	s_add_i32 s3, s3, -1
	s_lshr_b32 s10, s2, s9
	s_and_b32 s2, s3, s2
	s_lshl_b32 s9, s2, 8
	s_sub_i32 s89, s9, 64
	v_add_u32_e32 v18, s9, v180
	v_add_u32_e32 v34, s89, v1
	v_lshlrev_b32_e32 v18, s96, v18
	v_lshlrev_b32_e32 v34, s96, v34
	v_add_u32_e32 v58, s10, v18
	v_add_u32_e32 v34, s10, v34
	v_lshlrev_b32_e32 v18, 6, v58
	v_med3_i32 v34, v34, 0, v221
	v_ashrrev_i32_e32 v19, 31, v18
	v_lshlrev_b32_e32 v34, 7, v34
	v_mov_b32_e32 v35, v106
	v_lshl_add_u64 v[18:19], v[18:19], 1, v[170:171]
	v_lshl_add_u64 v[34:35], v[172:173], 0, v[34:35]
	global_load_dwordx4 v[30:33], v[18:19], off
	global_load_dwordx4 v[22:25], v[18:19], off offset:32
	global_load_dwordx4 v[26:29], v[18:19], off offset:64
	s_nop 0
	global_load_dwordx4 v[18:21], v[18:19], off offset:96
	s_nop 0
	global_load_dwordx4 v[54:57], v[34:35], off
	global_load_dwordx4 v[50:53], v[34:35], off offset:64
	v_add_u32_e32 v34, s89, v176
	v_lshlrev_b32_e32 v34, s96, v34
	v_add_u32_e32 v34, s10, v34
	v_med3_i32 v34, v34, 0, v221
	v_lshlrev_b32_e32 v34, 7, v34
	v_mov_b32_e32 v35, v106
	v_lshl_add_u64 v[34:35], v[172:173], 0, v[34:35]
	global_load_dwordx4 v[46:49], v[34:35], off
	global_load_dwordx4 v[42:45], v[34:35], off offset:64
	v_add_u32_e32 v34, s89, v178
	v_lshlrev_b32_e32 v34, s96, v34
	v_add_u32_e32 v34, s10, v34
	v_med3_i32 v34, v34, 0, v221
	v_lshlrev_b32_e32 v34, 7, v34
	v_mov_b32_e32 v35, v106
	v_lshl_add_u64 v[34:35], v[172:173], 0, v[34:35]
	global_load_dwordx4 v[38:41], v[34:35], off
	s_nop 0
	global_load_dwordx4 v[34:37], v[34:35], off offset:64
	v_lshlrev_b32_e32 v62, 16, v86
	v_and_b32_e32 v63, 0xffff0000, v86
	v_lshlrev_b32_e32 v60, 16, v90
	v_and_b32_e32 v61, 0xffff0000, v90
	v_readlane_b32 s2, v255, 12
	s_add_i32 s33, s33, s2
	s_cmpk_gt_i32 s33, 0x5ff
	v_perm_b32 v250, v94, v82, s6
	v_perm_b32 v251, v94, v82, s7
	v_add_u32_e32 v252, 0xc000, v181
	ds_write2_b32 v252, v250, v251 offset1:194
	v_perm_b32 v250, v95, v83, s6
	v_perm_b32 v251, v95, v83, s7
	v_add_u32_e32 v252, 0xc600, v181
	ds_write2_b32 v252, v250, v251 offset0:4 offset1:198
	v_perm_b32 v250, v96, v84, s6
	v_perm_b32 v251, v96, v84, s7
	v_add_u32_e32 v252, 0xcc00, v181
	ds_write2_b32 v252, v250, v251 offset0:8 offset1:202
	v_perm_b32 v250, v97, v85, s6
	v_perm_b32 v251, v97, v85, s7
	v_add_u32_e32 v252, 0xd200, v181
	ds_write2_b32 v252, v250, v251 offset0:12 offset1:206
	v_perm_b32 v250, v114, v110, s6
	v_perm_b32 v251, v114, v110, s7
	v_add_u32_e32 v252, 0xc800, v182
	ds_write2_b32 v252, v250, v251 offset1:194
	v_perm_b32 v250, v115, v111, s6
	v_perm_b32 v251, v115, v111, s7
	v_add_u32_e32 v252, 0xce00, v182
	ds_write2_b32 v252, v250, v251 offset0:4 offset1:198
	v_perm_b32 v250, v116, v112, s6
	v_perm_b32 v251, v116, v112, s7
	v_add_u32_e32 v252, 0xd400, v182
	ds_write2_b32 v252, v250, v251 offset0:8 offset1:202
	v_perm_b32 v250, v117, v113, s6
	v_perm_b32 v251, v117, v113, s7
	v_add_u32_e32 v252, 0xda00, v182
	ds_write2_b32 v252, v250, v251 offset0:12 offset1:206
	v_perm_b32 v250, v146, v126, s6
	v_perm_b32 v251, v146, v126, s7
	v_add_u32_e32 v252, 0xd000, v183
	ds_write2_b32 v252, v250, v251 offset1:194
	v_perm_b32 v250, v147, v127, s6
	v_perm_b32 v251, v147, v127, s7
	v_add_u32_e32 v252, 0xd600, v183
	ds_write2_b32 v252, v250, v251 offset0:4 offset1:198
	v_perm_b32 v250, v148, v128, s6
	v_perm_b32 v251, v148, v128, s7
	v_add_u32_e32 v252, 0xdc00, v183
	ds_write2_b32 v252, v250, v251 offset0:8 offset1:202
	v_perm_b32 v250, v149, v129, s6
	v_perm_b32 v251, v149, v129, s7
	v_add_u32_e32 v252, 0xe200, v183
	ds_write2_b32 v252, v250, v251 offset0:12 offset1:206
	s_waitcnt vmcnt(5)
	v_cvt_f32_f16_e32 v64, v54
	s_waitcnt vmcnt(4)
	v_cvt_f32_f16_e32 v66, v50
	v_cvt_f32_f16_sdwa v67, v50 dst_sel:DWORD dst_unused:UNUSED_PAD src0_sel:WORD_1
	v_cvt_f32_f16_sdwa v65, v54 dst_sel:DWORD dst_unused:UNUSED_PAD src0_sel:WORD_1
	v_pk_mul_f32 v[68:69], v[62:63], v[66:67]
	s_nop 0
	v_pk_fma_f32 v[68:69], v[60:61], v[64:65], v[68:69] neg_lo:[0,0,1] neg_hi:[0,0,1]
	v_pk_mul_f32 v[60:61], v[60:61], v[66:67]
	v_cvt_f32_f16_e32 v66, v51
	v_cvt_f32_f16_sdwa v67, v51 dst_sel:DWORD dst_unused:UNUSED_PAD src0_sel:WORD_1
	v_pk_fma_f32 v[60:61], v[62:63], v[64:65], v[60:61]
	v_cvt_f32_f16_e32 v64, v55
	v_cvt_f32_f16_sdwa v65, v55 dst_sel:DWORD dst_unused:UNUSED_PAD src0_sel:WORD_1
	v_lshlrev_b32_e32 v62, 16, v87
	v_and_b32_e32 v63, 0xffff0000, v87
	v_cvt_pk_bf16_f32 v50, v68, v69
	v_cvt_pk_bf16_f32 v54, v60, v61
	v_lshlrev_b32_e32 v60, 16, v91
	v_and_b32_e32 v61, 0xffff0000, v91
	v_pk_mul_f32 v[68:69], v[62:63], v[66:67]
	s_nop 0
	v_pk_fma_f32 v[68:69], v[60:61], v[64:65], v[68:69] neg_lo:[0,0,1] neg_hi:[0,0,1]
	v_pk_mul_f32 v[60:61], v[60:61], v[66:67]
	v_cvt_f32_f16_e32 v66, v52
	v_cvt_f32_f16_sdwa v67, v52 dst_sel:DWORD dst_unused:UNUSED_PAD src0_sel:WORD_1
	v_pk_fma_f32 v[60:61], v[62:63], v[64:65], v[60:61]
	v_cvt_f32_f16_e32 v64, v56
	v_cvt_f32_f16_sdwa v65, v56 dst_sel:DWORD dst_unused:UNUSED_PAD src0_sel:WORD_1
	v_lshlrev_b32_e32 v62, 16, v88
	v_and_b32_e32 v63, 0xffff0000, v88
	v_cvt_pk_bf16_f32 v51, v68, v69
	v_cvt_pk_bf16_f32 v55, v60, v61
	v_lshlrev_b32_e32 v60, 16, v92
	v_and_b32_e32 v61, 0xffff0000, v92
	v_pk_mul_f32 v[68:69], v[62:63], v[66:67]
	s_nop 0
	v_pk_fma_f32 v[68:69], v[60:61], v[64:65], v[68:69] neg_lo:[0,0,1] neg_hi:[0,0,1]
	v_pk_mul_f32 v[60:61], v[60:61], v[66:67]
	v_cvt_f32_f16_e32 v66, v53
	v_cvt_f32_f16_sdwa v67, v53 dst_sel:DWORD dst_unused:UNUSED_PAD src0_sel:WORD_1
	v_pk_fma_f32 v[60:61], v[62:63], v[64:65], v[60:61]
	v_cvt_f32_f16_e32 v64, v57
	v_cvt_f32_f16_sdwa v65, v57 dst_sel:DWORD dst_unused:UNUSED_PAD src0_sel:WORD_1
	v_lshlrev_b32_e32 v62, 16, v89
	v_and_b32_e32 v63, 0xffff0000, v89
	v_cvt_pk_bf16_f32 v52, v68, v69
	v_cvt_pk_bf16_f32 v56, v60, v61
	v_lshlrev_b32_e32 v60, 16, v93
	v_and_b32_e32 v61, 0xffff0000, v93
	v_pk_mul_f32 v[68:69], v[62:63], v[66:67]
	s_nop 0
	v_pk_fma_f32 v[68:69], v[60:61], v[64:65], v[68:69] neg_lo:[0,0,1] neg_hi:[0,0,1]
	v_pk_mul_f32 v[60:61], v[60:61], v[66:67]
	v_cvt_pk_bf16_f32 v53, v68, v69
	v_pk_fma_f32 v[60:61], v[62:63], v[64:65], v[60:61]
	s_nop 0
	v_cvt_pk_bf16_f32 v57, v60, v61
	ds_write_b128 v210, v[50:53]
	ds_write_b128 v211, v[54:57]
	s_waitcnt vmcnt(2)
; __device__ __forceinline__ float bflo(unsigned w) { return __uint_as_float(w << 16); }
; __device__ __forceinline__ float bfhi(unsigned w) { return __uint_as_float(w & 0xffff0000u); }
; __device__ __forceinline__ unsigned pk2(float lo, float hi) { const f32x2n v = {lo, hi}; return __builtin_bit_cast(unsigned, __builtin_convertvector(v, bf16x2n)); }
; #define LASP __attribute__((address_space(3)))
; __device__ __forceinline__ void attn_phase_mfma(const Ctx& c, unsigned char* lds_raw, bool do_store) {
;     ...
; #pragma unroll
;         for (int i = 0; i < 3; ++i) {
;             const int id = t + 512 * i, row = id >> 2, dc = id & 3;
;             const h16x8 kcv = tkc[i], ksv = tks[i];
;             u32x4 olo, ohi;
; #pragma unroll
;             for (int e = 0; e < 4; ++e) {
;                 const float l0 = bflo(ka[i][e]), l1 = bfhi(ka[i][e]), h0 = bflo(kb2[i][e]), h1 = bfhi(kb2[i][e]);
;                 const float cc0 = (float)kcv[2 * e], cc1 = (float)kcv[2 * e + 1], ss0 = (float)ksv[2 * e], ss1 = (float)ksv[2 * e + 1];
;                 olo[e] = pk2(l0 * cc0 - h0 * ss0, l1 * cc1 - h1 * ss1);
;                 ohi[e] = pk2(h0 * cc0 + l0 * ss0, h1 * cc1 + l1 * ss1);
;             }
;             *(LASP u32x4*)(Kt + row * 128 + ((dc ^ (row & 7)) << 4)) = olo;
;             *(LASP u32x4*)(Kt + row * 128 + (((4 + dc) ^ (row & 7)) << 4)) = ohi;
;             const int rp = id % 192, dc8 = id / 192;
; #pragma unroll
;             for (int e = 0; e < 4; ++e) {
;                 Vt[(8 * dc8 + 2 * e) * 194 + rp] = __builtin_amdgcn_perm(vb[i][e], va[i][e], 0x05040100u);
;                 Vt[(8 * dc8 + 2 * e + 1) * 194 + rp] = __builtin_amdgcn_perm(vb[i][e], va[i][e], 0x07060302u);
;             }
;         }
;         __syncthreads();
	v_cvt_f32_f16_e32 v56, v42
	v_cvt_f32_f16_sdwa v57, v42 dst_sel:DWORD dst_unused:UNUSED_PAD src0_sel:WORD_1
	v_cvt_f32_f16_e32 v54, v46
	v_cvt_f32_f16_sdwa v55, v46 dst_sel:DWORD dst_unused:UNUSED_PAD src0_sel:WORD_1
	v_lshlrev_b32_e32 v52, 16, v98
	v_and_b32_e32 v53, 0xffff0000, v98
	v_lshlrev_b32_e32 v50, 16, v102
	v_and_b32_e32 v51, 0xffff0000, v102
	v_pk_mul_f32 v[60:61], v[52:53], v[56:57]
	s_nop 0
	v_pk_fma_f32 v[60:61], v[50:51], v[54:55], v[60:61] neg_lo:[0,0,1] neg_hi:[0,0,1]
	v_pk_mul_f32 v[50:51], v[50:51], v[56:57]
	v_cvt_f32_f16_e32 v56, v43
	v_cvt_f32_f16_sdwa v57, v43 dst_sel:DWORD dst_unused:UNUSED_PAD src0_sel:WORD_1
	v_pk_fma_f32 v[50:51], v[52:53], v[54:55], v[50:51]
	v_cvt_f32_f16_e32 v54, v47
	v_cvt_f32_f16_sdwa v55, v47 dst_sel:DWORD dst_unused:UNUSED_PAD src0_sel:WORD_1
	v_lshlrev_b32_e32 v52, 16, v99
	v_and_b32_e32 v53, 0xffff0000, v99
	v_cvt_pk_bf16_f32 v42, v60, v61
	v_cvt_pk_bf16_f32 v46, v50, v51
	v_lshlrev_b32_e32 v50, 16, v103
	v_and_b32_e32 v51, 0xffff0000, v103
	v_pk_mul_f32 v[60:61], v[52:53], v[56:57]
	s_nop 0
	v_pk_fma_f32 v[60:61], v[50:51], v[54:55], v[60:61] neg_lo:[0,0,1] neg_hi:[0,0,1]
	v_pk_mul_f32 v[50:51], v[50:51], v[56:57]
	v_cvt_f32_f16_e32 v56, v44
	v_cvt_f32_f16_sdwa v57, v44 dst_sel:DWORD dst_unused:UNUSED_PAD src0_sel:WORD_1
	v_pk_fma_f32 v[50:51], v[52:53], v[54:55], v[50:51]
	v_cvt_f32_f16_e32 v54, v48
	v_cvt_f32_f16_sdwa v55, v48 dst_sel:DWORD dst_unused:UNUSED_PAD src0_sel:WORD_1
	v_lshlrev_b32_e32 v52, 16, v100
	v_and_b32_e32 v53, 0xffff0000, v100
	v_cvt_pk_bf16_f32 v43, v60, v61
	v_cvt_pk_bf16_f32 v47, v50, v51
	v_lshlrev_b32_e32 v50, 16, v104
	v_and_b32_e32 v51, 0xffff0000, v104
	v_pk_mul_f32 v[60:61], v[52:53], v[56:57]
	s_nop 0
	v_pk_fma_f32 v[60:61], v[50:51], v[54:55], v[60:61] neg_lo:[0,0,1] neg_hi:[0,0,1]
	v_pk_mul_f32 v[50:51], v[50:51], v[56:57]
	v_cvt_f32_f16_e32 v56, v45
	v_cvt_f32_f16_sdwa v57, v45 dst_sel:DWORD dst_unused:UNUSED_PAD src0_sel:WORD_1
	v_pk_fma_f32 v[50:51], v[52:53], v[54:55], v[50:51]
	v_cvt_f32_f16_e32 v54, v49
	v_cvt_f32_f16_sdwa v55, v49 dst_sel:DWORD dst_unused:UNUSED_PAD src0_sel:WORD_1
	v_lshlrev_b32_e32 v52, 16, v101
	v_and_b32_e32 v53, 0xffff0000, v101
	v_cvt_pk_bf16_f32 v44, v60, v61
	v_cvt_pk_bf16_f32 v48, v50, v51
	v_lshlrev_b32_e32 v50, 16, v105
	v_and_b32_e32 v51, 0xffff0000, v105
	v_pk_mul_f32 v[60:61], v[52:53], v[56:57]
	s_nop 0
	v_pk_fma_f32 v[60:61], v[50:51], v[54:55], v[60:61] neg_lo:[0,0,1] neg_hi:[0,0,1]
	v_pk_mul_f32 v[50:51], v[50:51], v[56:57]
	v_cvt_pk_bf16_f32 v45, v60, v61
	v_pk_fma_f32 v[50:51], v[52:53], v[54:55], v[50:51]
	s_nop 0
	v_cvt_pk_bf16_f32 v49, v50, v51
	ds_write_b128 v212, v[42:45]
	ds_write_b128 v213, v[46:49]
	s_waitcnt vmcnt(0)
	v_cvt_f32_f16_e32 v48, v34
	v_cvt_f32_f16_sdwa v49, v34 dst_sel:DWORD dst_unused:UNUSED_PAD src0_sel:WORD_1
	v_cvt_f32_f16_e32 v46, v38
	v_cvt_f32_f16_sdwa v47, v38 dst_sel:DWORD dst_unused:UNUSED_PAD src0_sel:WORD_1
	v_lshlrev_b32_e32 v44, 16, v118
	v_and_b32_e32 v45, 0xffff0000, v118
	v_lshlrev_b32_e32 v42, 16, v122
	v_and_b32_e32 v43, 0xffff0000, v122
	v_pk_mul_f32 v[50:51], v[44:45], v[48:49]
	s_nop 0
	v_pk_fma_f32 v[50:51], v[42:43], v[46:47], v[50:51] neg_lo:[0,0,1] neg_hi:[0,0,1]
	v_pk_mul_f32 v[42:43], v[42:43], v[48:49]
	v_cvt_f32_f16_e32 v48, v35
	v_cvt_f32_f16_sdwa v49, v35 dst_sel:DWORD dst_unused:UNUSED_PAD src0_sel:WORD_1
	v_pk_fma_f32 v[42:43], v[44:45], v[46:47], v[42:43]
	v_cvt_f32_f16_e32 v46, v39
	v_cvt_f32_f16_sdwa v47, v39 dst_sel:DWORD dst_unused:UNUSED_PAD src0_sel:WORD_1
	v_lshlrev_b32_e32 v44, 16, v119
	v_and_b32_e32 v45, 0xffff0000, v119
	v_cvt_pk_bf16_f32 v34, v50, v51
	v_cvt_pk_bf16_f32 v38, v42, v43
	v_lshlrev_b32_e32 v42, 16, v123
	v_and_b32_e32 v43, 0xffff0000, v123
	v_pk_mul_f32 v[50:51], v[44:45], v[48:49]
	s_nop 0
	v_pk_fma_f32 v[50:51], v[42:43], v[46:47], v[50:51] neg_lo:[0,0,1] neg_hi:[0,0,1]
	v_pk_mul_f32 v[42:43], v[42:43], v[48:49]
	v_cvt_f32_f16_e32 v48, v36
	v_cvt_f32_f16_sdwa v49, v36 dst_sel:DWORD dst_unused:UNUSED_PAD src0_sel:WORD_1
	v_pk_fma_f32 v[42:43], v[44:45], v[46:47], v[42:43]
	v_cvt_f32_f16_e32 v46, v40
	v_cvt_f32_f16_sdwa v47, v40 dst_sel:DWORD dst_unused:UNUSED_PAD src0_sel:WORD_1
	v_lshlrev_b32_e32 v44, 16, v120
	v_and_b32_e32 v45, 0xffff0000, v120
	v_cvt_pk_bf16_f32 v35, v50, v51
	v_cvt_pk_bf16_f32 v39, v42, v43
	v_lshlrev_b32_e32 v42, 16, v124
	v_and_b32_e32 v43, 0xffff0000, v124
	v_pk_mul_f32 v[50:51], v[44:45], v[48:49]
	s_nop 0
	v_pk_fma_f32 v[50:51], v[42:43], v[46:47], v[50:51] neg_lo:[0,0,1] neg_hi:[0,0,1]
	v_pk_mul_f32 v[42:43], v[42:43], v[48:49]
	v_cvt_f32_f16_e32 v48, v37
	v_cvt_f32_f16_sdwa v49, v37 dst_sel:DWORD dst_unused:UNUSED_PAD src0_sel:WORD_1
	v_pk_fma_f32 v[42:43], v[44:45], v[46:47], v[42:43]
	v_cvt_f32_f16_e32 v46, v41
	v_cvt_f32_f16_sdwa v47, v41 dst_sel:DWORD dst_unused:UNUSED_PAD src0_sel:WORD_1
	v_lshlrev_b32_e32 v44, 16, v121
	v_and_b32_e32 v45, 0xffff0000, v121
	v_cvt_pk_bf16_f32 v36, v50, v51
	v_cvt_pk_bf16_f32 v40, v42, v43
	v_lshlrev_b32_e32 v42, 16, v125
	v_and_b32_e32 v43, 0xffff0000, v125
	v_pk_mul_f32 v[50:51], v[44:45], v[48:49]
	s_nop 0
	v_pk_fma_f32 v[50:51], v[42:43], v[46:47], v[50:51] neg_lo:[0,0,1] neg_hi:[0,0,1]
	v_pk_mul_f32 v[42:43], v[42:43], v[48:49]
	v_cvt_pk_bf16_f32 v37, v50, v51
	v_pk_fma_f32 v[42:43], v[44:45], v[46:47], v[42:43]
	s_nop 0
	v_cvt_pk_bf16_f32 v41, v42, v43
	ds_write_b128 v214, v[34:37]
	ds_write_b128 v215, v[38:41]
	s_waitcnt lgkmcnt(0)
	s_barrier
; __device__ __forceinline__ void attn_phase_mfma(const Ctx& c, unsigned char* lds_raw, bool do_store) {
;     ...
;         const int un = u + G;
;         if (un < NAT) ATT_PREFETCH(un);
	s_cbranch_scc1 .LBB0_1739
	s_mul_hi_i32 s2, s33, 0x2aaaaaab
	s_lshr_b32 s3, s2, 31
	s_ashr_i32 s2, s2, 5
	s_add_i32 s2, s2, s3
	s_mul_i32 s3, s2, 0xffffff40
	s_add_i32 s3, s33, s3
	s_ashr_i32 s11, s3, 6
	s_lshl_b32 s10, s11, 1
	s_lshr_b32 s13, 16, s10
	s_and_b32 s3, s3, 15
	s_sub_i32 s12, 4, s10
	s_add_i32 s13, s13, -1
	s_lshr_b32 s12, s3, s12
	s_and_b32 s3, s13, s3
	s_lshl_b32 s13, s3, 8
	s_ashr_i32 s3, s2, 31
	v_add_u32_e32 v34, s13, v180
	s_lshl_b64 s[94:95], s[2:3], 12
	v_lshlrev_b32_e32 v34, s10, v34
	s_or_b32 s90, s94, s12
	s_mov_b32 s91, s95
	v_ashrrev_i32_e32 v35, 31, v34
	v_lshl_add_u64 v[34:35], s[90:91], 0, v[34:35]
	v_mov_b64_e32 v[36:37], s[92:93]
	v_mad_u64_u32 v[36:37], s[2:3], v34, s8, v[36:37]
	s_lshl_b32 s2, s11, 8
	s_and_b32 s3, s4, 0xc0
	s_or_b32 s2, s2, s3
	v_mad_i32_i24 v37, v35, s8, v37
	s_ashr_i32 s3, s2, 31
	v_lshl_add_u64 v[34:35], s[2:3], 1, v[36:37]
	v_mov_b32_e32 v169, v106
	v_lshl_add_u64 v[34:35], v[34:35], 0, v[168:169]
	global_load_dwordx4 v[142:145], v[34:35], off offset:1536
	global_load_dwordx4 v[138:141], v[34:35], off offset:1568
	global_load_dwordx4 v[134:137], v[34:35], off offset:1600
	global_load_dwordx4 v[130:133], v[34:35], off offset:1632
	s_sub_i32 s13, s13, 64
	s_lshr_b32 s11, 0x1000, s10
	v_add_u32_e32 v34, s13, v1
	v_mov_b32_e32 v84, v106
	v_mov_b32_e32 v85, v106
	v_cmp_lt_i32_e32 vcc, -1, v34
	v_cmp_gt_i32_e64 s[74:75], s11, v34
	v_mov_b32_e32 v82, v106
	v_mov_b32_e32 v83, v106
	v_mov_b64_e32 v[88:89], v[84:85]
	v_mov_b64_e32 v[92:93], v[84:85]
	s_and_b64 vcc, vcc, s[74:75]
	v_mov_b64_e32 v[86:87], v[82:83]
	v_mov_b64_e32 v[90:91], v[82:83]
	s_and_saveexec_b64 s[74:75], vcc
	s_cbranch_execz .LBB0_1722
	v_lshlrev_b32_e32 v34, s10, v34
	v_add_u32_e32 v34, s12, v34
	v_mov_b32_e32 v35, v106
	v_lshl_add_u64 v[34:35], s[94:95], 0, v[34:35]
	v_mov_b64_e32 v[36:37], s[92:93]
	v_mad_u64_u32 v[36:37], vcc, v34, s8, v[36:37]
	v_mad_i32_i24 v37, v35, s8, v37
	v_lshl_add_u64 v[34:35], s[2:3], 1, v[36:37]
	v_mov_b32_e32 v159, v106
	v_lshl_add_u64 v[34:35], v[34:35], 0, v[158:159]
	global_load_dwordx4 v[90:93], v[34:35], off offset:3072
	global_load_dwordx4 v[86:89], v[34:35], off offset:3136

; template <class Epi, class Sched, class Gemm, bool ALIGN_EPI = false, bool SP2 = false>
; __device__ __forceinline__ void gemm_phase(PG8_LAS unsigned char* lds, const Gemm g, const Sched& S, const Epi& E) {
;     ...
; #pragma unroll
;     for (int a = 0; a < 2; ++a)
; #pragma unroll
;         for (int b = 0; b < 2; ++b)
; #pragma unroll
;             for (int m = 0; m < 4; ++m)
; #pragma unroll
;                 for (int n = 0; n < 2; ++n) acc[a][b][m][n] = (f32x4){0.f, 0.f, 0.f, 0.f};
;     bf16x8 At[4][2], B0[2][2], B1[2][2];
;     const char* cA = (const char*)g.A + (size_t)cur.pm * tstepA + (size_t)cur.sub * g.a_sub; const char* cB = (const char*)g.Bt + (size_t)cur.pn * tstepB + (size_t)cur.sub * g.b_sub;
;     S.a_ready(cur);
;     if constexpr (SP2) {
;         PG8_STAGE(PG8_SB(0, 0), cB, voffB); PG8_STAGE(PG8_SB(0, 1), cB + hB1, voffB1); PG8_STAGE(PG8_SA(0, 0), cA, voffA); PG8_STAGE(PG8_SA(0, 1), cA + hstepA, voffA);
;         if (wr == 1) PG8_BAR;
;         PG8_WAIT_V(2); PG8_BAR;
;         PG8_STAGE(PG8_SB(1, 0), cB + kstep, voffB); PG8_STAGE(PG8_SA(1, 0), cA + kstep, voffA); PG8_STAGE(PG8_SB(1, 1), cB + hB1 + kstep, voffB1);
;         PG8_WAIT_V(6); PG8_BAR;
;     } else {
;         PG8_STAGE(PG8_SB(0, 0), cB, voffB); PG8_STAGE(PG8_SA(0, 0), cA, voffA); PG8_STAGE(PG8_SB(0, 1), cB + hB1, voffB1); PG8_STAGE(PG8_SA(0, 1), cA + hstepA, voffA);
;         if (wr == 1) PG8_BAR;
;         PG8_WAIT_V(4); PG8_BAR;
;         PG8_STAGE(PG8_SB(1, 0), cB + kstep, voffB); PG8_STAGE(PG8_SA(1, 0), cA + kstep, voffA); PG8_STAGE(PG8_SB(1, 1), cB + hB1 + kstep, voffB1);
;         PG8_WAIT_V(6); PG8_BAR;
;     }
;     for (;;) {
;         const bool has_next = S.next(ui + 1, nxt);
;         const char* nA = has_next ? (const char*)g.A + (size_t)nxt.pm * tstepA + (size_t)nxt.sub * g.a_sub : cA; const char* nB = has_next ? (const char*)g.Bt + (size_t)nxt.pn * tstepB + (size_t)nxt.sub * g.b_sub : cB;
;         for (int t = 0; t < nt; t += 2) {
;             const bool last = (t == nt - 2);
;             const char* a1 = cA + (size_t)(t + 1) * kstep;
;             const char* a2 = last ? nA : cA + (size_t)(t + 2) * kstep; const char* b2 = last ? nB : cB + (size_t)(t + 2) * kstep;
;             const char* a3 = a2 + kstep; const char* b3 = b2 + kstep;
;             if (last && has_next) S.a_ready(nxt);
;             if constexpr (SP2) {
.LBB0_2551:
	s_ashr_i32 s31, s30, 31
	s_lshl_b64 s[34:35], s[30:31], 18
	s_add_u32 s34, s44, s34
	s_addc_u32 s35, s45, s35
	s_and_b64 s[36:37], s[4:5], exec
	s_cselect_b32 s31, s35, s3
	s_cselect_b32 s60, s34, s2
	s_ashr_i32 s29, s28, 31
	s_lshl_b64 s[36:37], s[28:29], 18
	s_add_u32 s36, s33, s36
	s_addc_u32 s37, s42, s37
	s_and_b64 s[40:41], s[4:5], exec
	s_cselect_b32 s29, s37, s1
	s_cselect_b32 s61, s36, s0
	s_add_u32 s62, s0, 0x100
	s_addc_u32 s63, s1, 0
	s_add_u32 s0, s2, 0x20080
	v_mov_b32_e32 v2, 0
	s_addc_u32 s1, s3, 0
	s_mov_b32 s64, -2
	v_mov_b32_e32 v3, v2
	v_mov_b32_e32 v4, v2
	v_mov_b32_e32 v5, v2
	v_mov_b32_e32 v6, v2
	v_mov_b32_e32 v7, v2
	v_mov_b32_e32 v8, v2
	v_mov_b32_e32 v9, v2
	s_waitcnt vmcnt(0)
	v_mov_b64_e32 v[18:19], 0
	v_mov_b64_e32 v[20:21], 0
	v_mov_b64_e32 v[22:23], 0
	v_mov_b64_e32 v[24:25], 0
	v_mov_b64_e32 v[34:35], 0
	v_mov_b64_e32 v[36:37], 0
	v_mov_b64_e32 v[38:39], 0
	v_mov_b64_e32 v[40:41], 0
	v_mov_b64_e32 v[50:51], 0
	v_mov_b64_e32 v[52:53], 0
	v_mov_b64_e32 v[54:55], 0
	v_mov_b64_e32 v[56:57], 0
	v_mov_b64_e32 v[10:11], 0
	v_mov_b64_e32 v[12:13], 0
	v_mov_b64_e32 v[14:15], 0
	v_mov_b64_e32 v[16:17], 0
	v_mov_b64_e32 v[26:27], 0
	v_mov_b64_e32 v[28:29], 0
	v_mov_b64_e32 v[30:31], 0
	v_mov_b64_e32 v[32:33], 0
	v_mov_b64_e32 v[42:43], 0
	v_mov_b64_e32 v[44:45], 0
	v_mov_b64_e32 v[46:47], 0
	v_mov_b64_e32 v[48:49], 0
	v_mov_b64_e32 v[58:59], 0
	v_mov_b64_e32 v[60:61], 0
	v_mov_b64_e32 v[62:63], 0
	v_mov_b64_e32 v[64:65], 0
	v_mov_b64_e32 v[66:67], 0
	v_mov_b64_e32 v[68:69], 0
	v_mov_b64_e32 v[70:71], 0
	v_mov_b64_e32 v[72:73], 0
	v_mov_b64_e32 v[82:83], 0
	v_mov_b64_e32 v[84:85], 0
	v_mov_b64_e32 v[86:87], 0
	v_mov_b64_e32 v[88:89], 0
	v_mov_b64_e32 v[98:99], 0
	v_mov_b64_e32 v[100:101], 0
	v_mov_b64_e32 v[102:103], 0
	v_mov_b64_e32 v[104:105], 0
	v_mov_b64_e32 v[114:115], 0
	v_mov_b64_e32 v[116:117], 0
	v_mov_b64_e32 v[118:119], 0
	v_mov_b64_e32 v[120:121], 0
	v_mov_b64_e32 v[74:75], 0
	v_mov_b64_e32 v[76:77], 0
	v_mov_b64_e32 v[78:79], 0
	v_mov_b64_e32 v[80:81], 0
	v_mov_b64_e32 v[90:91], 0
	v_mov_b64_e32 v[92:93], 0
	v_mov_b64_e32 v[94:95], 0
	v_mov_b64_e32 v[96:97], 0
	v_mov_b64_e32 v[106:107], 0
	v_mov_b64_e32 v[108:109], 0
	v_mov_b64_e32 v[110:111], 0
	v_mov_b64_e32 v[112:113], 0
	v_mov_b64_e32 v[122:123], 0
	v_mov_b64_e32 v[124:125], 0
	v_mov_b64_e32 v[126:127], 0
	v_mov_b64_e32 v[128:129], 0
.LBB0_2552:
	ds_read_b128 v[172:175], v183
	ds_read_b128 v[188:191], v183 offset:1024
	ds_read_b128 v[192:195], v183 offset:2048
	ds_read_b128 v[196:199], v183 offset:3072
	ds_read_b128 v[134:137], v185
	ds_read_b128 v[138:141], v185 offset:1024
	ds_read_b128 v[142:145], v185 offset:2048
	ds_read_b128 v[130:133], v185 offset:3072
	s_add_u32 s2, s0, 0xfffe0080
	s_addc_u32 s3, s1, -1
	s_cmp_eq_u32 s64, 4
	s_cselect_b32 s3, s31, s3
	s_cselect_b32 s2, s60, s2
	s_cselect_b32 s41, s29, s63
	s_cselect_b32 s40, s61, s62
	v_lshl_add_u64 v[160:161], s[0:1], 0, v[158:159]
	s_add_i32 m0, s39, 0xc000
	ds_read_b128 v[164:167], v187
	ds_read_b128 v[168:171], v187 offset:1024
	ds_read_b128 v[200:203], v187 offset:2048
	ds_read_b128 v[204:207], v187 offset:3072
	ds_read_b128 v[208:211], v187 offset:4096
	ds_read_b128 v[212:215], v187 offset:5120
	ds_read_b128 v[216:219], v187 offset:6144
	ds_read_b128 v[220:223], v187 offset:7168
	global_load_lds_dwordx4 v[160:161], off
	v_lshl_add_u64 v[160:161], s[0:1], 0, v[156:157]
	s_add_i32 m0, s39, 0xe000
	s_nop 0
	global_load_lds_dwordx4 v[160:161], off
	s_waitcnt vmcnt(8)
	s_waitcnt lgkmcnt(0)
	s_barrier
	s_setprio 1
	s_waitcnt lgkmcnt(0)
	v_mfma_i32_16x16x64_i8 v[224:227], v[172:175], v[164:167], v[126:129]
	v_mfma_i32_16x16x64_i8 v[126:129], v[188:191], v[168:171], v[224:227]
	v_mfma_i32_16x16x64_i8 v[228:231], v[192:195], v[164:167], v[122:125]
	v_mfma_i32_16x16x64_i8 v[232:235], v[172:175], v[200:203], v[110:113]
	v_mfma_i32_16x16x64_i8 v[236:239], v[192:195], v[200:203], v[106:109]
	v_mfma_i32_16x16x64_i8 v[240:243], v[172:175], v[208:211], v[94:97]
	v_mfma_i32_16x16x64_i8 v[244:247], v[192:195], v[208:211], v[90:93]
	v_mfma_i32_16x16x64_i8 v[224:227], v[172:175], v[216:219], v[78:81]
	v_mfma_i32_16x16x64_i8 v[74:77], v[192:195], v[216:219], v[74:77]
	v_mfma_i32_16x16x64_i8 v[122:125], v[196:199], v[168:171], v[228:231]
	v_mfma_i32_16x16x64_i8 v[110:113], v[188:191], v[204:207], v[232:235]
	v_mfma_i32_16x16x64_i8 v[106:109], v[196:199], v[204:207], v[236:239]
	v_mfma_i32_16x16x64_i8 v[94:97], v[188:191], v[212:215], v[240:243]
	v_mfma_i32_16x16x64_i8 v[90:93], v[196:199], v[212:215], v[244:247]
	v_mfma_i32_16x16x64_i8 v[78:81], v[188:191], v[220:223], v[224:227]
	v_mfma_i32_16x16x64_i8 v[74:77], v[196:199], v[220:223], v[74:77]
	s_setprio 0
	s_setprio 1
	v_mfma_i32_16x16x64_i8 v[224:227], v[134:137], v[164:167], v[118:121]
	v_mfma_i32_16x16x64_i8 v[118:121], v[138:141], v[168:171], v[224:227]
	v_mfma_i32_16x16x64_i8 v[228:231], v[142:145], v[164:167], v[114:117]
	v_mfma_i32_16x16x64_i8 v[232:235], v[134:137], v[200:203], v[102:105]
	v_mfma_i32_16x16x64_i8 v[236:239], v[142:145], v[200:203], v[98:101]
	v_mfma_i32_16x16x64_i8 v[240:243], v[134:137], v[208:211], v[86:89]
	v_mfma_i32_16x16x64_i8 v[244:247], v[142:145], v[208:211], v[82:85]
	v_mfma_i32_16x16x64_i8 v[164:167], v[134:137], v[216:219], v[70:73]
	v_mfma_i32_16x16x64_i8 v[66:69], v[142:145], v[216:219], v[66:69]
	v_mfma_i32_16x16x64_i8 v[114:117], v[130:133], v[168:171], v[228:231]
	v_mfma_i32_16x16x64_i8 v[102:105], v[138:141], v[204:207], v[232:235]
	v_mfma_i32_16x16x64_i8 v[98:101], v[130:133], v[204:207], v[236:239]
	v_mfma_i32_16x16x64_i8 v[86:89], v[138:141], v[212:215], v[240:243]
	v_mfma_i32_16x16x64_i8 v[82:85], v[130:133], v[212:215], v[244:247]
	v_mfma_i32_16x16x64_i8 v[70:73], v[138:141], v[220:223], v[164:167]
	v_mfma_i32_16x16x64_i8 v[66:69], v[130:133], v[220:223], v[66:69]
	s_setprio 0
	s_barrier
; #define PG8_STAGE(bufoff, gbase, voff) do { _Pragma("unroll") for (int _i = 0; _i < 2; ++_i) \
;         __builtin_amdgcn_global_load_lds((const unsigned*)((const char*)(gbase) + (voff)[_i]), (PG8_LAS unsigned*)(lds + (bufoff) + ldsw + _i * 8192), 16, 0, 0); } while (0)
; #define PG8_LDA(dst, b, h) do { _Pragma("unroll") for (int m = 0; m < 4; ++m) _Pragma("unroll") for (int k = 0; k < 2; ++k) dst[m][k] = *(const PG8_LAS bf16x8*)(lds + PG8_SA(b, h) + aoff + m * 2048 + k * 1024); } while (0)
; #define PG8_LDB(dst, b, h) do { _Pragma("unroll") for (int n = 0; n < 2; ++n) _Pragma("unroll") for (int k = 0; k < 2; ++k) dst[n][k] = *(const PG8_LAS bf16x8*)(lds + PG8_SB(b, h) + boff + n * 2048 + k * 1024); } while (0)
; #define PG8_MMA(ai, bj, At, Bt) do { __builtin_amdgcn_s_setprio(1); _Pragma("unroll") for (int m = 0; m < 4; ++m) _Pragma("unroll") for (int n = 0; n < 2; ++n) _Pragma("unroll") for (int k = 0; k < 2; ++k) \
;         acc[ai][bj][m][n] = Gemm::i8 ? ::mfma16i8_g(Bt[n][k], At[m][k], acc[ai][bj][m][n]) : ::mfma16_g(Bt[n][k], At[m][k], acc[ai][bj][m][n]); __builtin_amdgcn_s_setprio(0); } while (0)
; #define PG8_WAIT_V(n) asm volatile("s_waitcnt vmcnt(" #n ")" ::: "memory")
; #define PG8_BAR __builtin_amdgcn_s_barrier()
; template <class Epi, class Sched, class Gemm, bool ALIGN_EPI = false, bool SP2 = false>
; __device__ __forceinline__ void gemm_phase(PG8_LAS unsigned char* lds, const Gemm g, const Sched& S, const Epi& E) {
;     ...
;             if constexpr (SP2) {
;             PG8_LDB(B0, 0, 0); PG8_LDB(B1, 0, 1); PG8_SCHED; PG8_LDA(At, 0, 0); PG8_STAGE(PG8_SA(1, 1), a1 + hstepA, voffA);
;             PG8_WAIT_V(8); PG8_WAIT_L(0); PG8_BAR; PG8_MMA(0, 0, At, B0); PG8_MMA(0, 1, At, B1); PG8_BAR; PG8_SCHED;
;             PG8_LDA(At, 0, 1); PG8_STAGE(PG8_SB(0, 0), b2, voffB); PG8_STAGE(PG8_SB(0, 1), b2 + hB1, voffB1); PG8_STAGE(PG8_SA(0, 0), a2, voffA);
;             PG8_WAIT_V(8); PG8_WAIT_L(0); PG8_BAR; PG8_MMA(1, 0, At, B0); PG8_MMA(1, 1, At, B1); PG8_BAR; PG8_SCHED;
;             PG8_LDB(B0, 1, 0); PG8_LDB(B1, 1, 1); PG8_SCHED; PG8_LDA(At, 1, 0); PG8_STAGE(PG8_SA(0, 1), a2 + hstepA, voffA);
;             PG8_WAIT_V(8); PG8_WAIT_L(0); PG8_BAR; PG8_MMA(0, 0, At, B0); PG8_MMA(0, 1, At, B1); PG8_BAR; PG8_SCHED;
;             PG8_LDA(At, 1, 1); PG8_STAGE(PG8_SB(1, 0), b3, voffB); PG8_STAGE(PG8_SB(1, 1), b3 + hB1, voffB1); PG8_STAGE(PG8_SA(1, 0), a3, voffA);
	s_add_i32 s65, s55, s43
	v_lshl_add_u64 v[164:165], s[40:41], 0, v[148:149]
	s_mov_b32 m0, s65
	ds_read_b128 v[200:203], v187 offset:16384
	ds_read_b128 v[204:207], v187 offset:17408
	ds_read_b128 v[208:211], v187 offset:18432
	ds_read_b128 v[212:215], v187 offset:19456
	ds_read_b128 v[216:219], v187 offset:20480
	ds_read_b128 v[220:223], v187 offset:21504
	ds_read_b128 v[224:227], v187 offset:22528
	ds_read_b128 v[228:231], v187 offset:23552
	global_load_lds_dwordx4 v[164:165], off
	s_add_i32 m0, s65, 0x2000
	s_add_u32 s66, s40, 0x2000
	v_lshl_add_u64 v[166:167], s[40:41], 0, v[152:153]
	s_addc_u32 s67, s41, 0
	s_add_i32 s65, s56, s43
	global_load_lds_dwordx4 v[166:167], off
	v_lshl_add_u64 v[160:161], s[66:67], 0, v[148:149]
	s_mov_b32 m0, s65
	v_lshl_add_u64 v[168:169], s[2:3], 0, v[146:147]
	global_load_lds_dwordx4 v[160:161], off
	v_lshl_add_u64 v[160:161], s[66:67], 0, v[152:153]
	s_add_i32 m0, s65, 0x2000
	v_lshl_add_u64 v[170:171], s[2:3], 0, v[150:151]
	global_load_lds_dwordx4 v[160:161], off
	s_mov_b32 m0, s39
	s_nop 0
	global_load_lds_dwordx4 v[168:169], off
	s_mov_b32 m0, s46
	s_nop 0
	global_load_lds_dwordx4 v[170:171], off
	s_waitcnt vmcnt(8)
	s_waitcnt lgkmcnt(0)
	s_barrier
	s_setprio 1
	s_waitcnt lgkmcnt(0)
	v_mfma_i32_16x16x64_i8 v[232:235], v[172:175], v[200:203], v[62:65]
	v_mfma_i32_16x16x64_i8 v[62:65], v[188:191], v[204:207], v[232:235]
	v_mfma_i32_16x16x64_i8 v[236:239], v[192:195], v[200:203], v[58:61]
	v_mfma_i32_16x16x64_i8 v[240:243], v[172:175], v[208:211], v[46:49]
	v_mfma_i32_16x16x64_i8 v[244:247], v[192:195], v[208:211], v[42:45]
	v_mfma_i32_16x16x64_i8 v[248:251], v[172:175], v[216:219], v[30:33]
	v_mfma_i32_16x16x64_i8 v[160:163], v[192:195], v[216:219], v[26:29]
	v_mfma_i32_16x16x64_i8 v[232:235], v[172:175], v[224:227], v[14:17]
	v_mfma_i32_16x16x64_i8 v[10:13], v[192:195], v[224:227], v[10:13]
	v_mfma_i32_16x16x64_i8 v[58:61], v[196:199], v[204:207], v[236:239]
	v_mfma_i32_16x16x64_i8 v[46:49], v[188:191], v[212:215], v[240:243]
	v_mfma_i32_16x16x64_i8 v[42:45], v[196:199], v[212:215], v[244:247]
	v_mfma_i32_16x16x64_i8 v[30:33], v[188:191], v[220:223], v[248:251]
	v_mfma_i32_16x16x64_i8 v[26:29], v[196:199], v[220:223], v[160:163]
	v_mfma_i32_16x16x64_i8 v[14:17], v[188:191], v[228:231], v[232:235]
	v_mfma_i32_16x16x64_i8 v[10:13], v[196:199], v[228:231], v[10:13]
	s_setprio 0
	s_setprio 1
	v_mfma_i32_16x16x64_i8 v[160:163], v[134:137], v[200:203], v[54:57]
	v_mfma_i32_16x16x64_i8 v[54:57], v[138:141], v[204:207], v[160:163]
	v_mfma_i32_16x16x64_i8 v[172:175], v[142:145], v[200:203], v[50:53]
	v_mfma_i32_16x16x64_i8 v[188:191], v[134:137], v[208:211], v[38:41]
	v_mfma_i32_16x16x64_i8 v[192:195], v[142:145], v[208:211], v[34:37]
	v_mfma_i32_16x16x64_i8 v[196:199], v[134:137], v[216:219], v[22:25]
	v_mfma_i32_16x16x64_i8 v[232:235], v[142:145], v[216:219], v[18:21]
	v_mfma_i32_16x16x64_i8 v[160:163], v[134:137], v[224:227], v[6:9]
	v_mfma_i32_16x16x64_i8 v[2:5], v[142:145], v[224:227], v[2:5]
	v_mfma_i32_16x16x64_i8 v[50:53], v[130:133], v[204:207], v[172:175]
	v_mfma_i32_16x16x64_i8 v[38:41], v[138:141], v[212:215], v[188:191]
	v_mfma_i32_16x16x64_i8 v[34:37], v[130:133], v[212:215], v[192:195]
	v_mfma_i32_16x16x64_i8 v[22:25], v[138:141], v[220:223], v[196:199]
	v_mfma_i32_16x16x64_i8 v[18:21], v[130:133], v[220:223], v[232:235]
	v_mfma_i32_16x16x64_i8 v[6:9], v[138:141], v[228:231], v[160:163]
	v_mfma_i32_16x16x64_i8 v[2:5], v[130:133], v[228:231], v[2:5]
	s_setprio 0
	s_barrier
	s_add_i32 s65, 0, 0x18000
	s_add_i32 s66, 0, 0x1c000
	v_add_u32_e32 v130, s65, v181
	v_add_u32_e32 v131, s66, v181
	ds_read_b128 v[160:163], v130
	ds_read_b128 v[172:175], v130 offset:1024
	ds_read_b128 v[188:191], v130 offset:2048
	ds_read_b128 v[192:195], v130 offset:3072
	ds_read_b128 v[134:137], v131
	ds_read_b128 v[138:141], v131 offset:1024
	ds_read_b128 v[142:145], v131 offset:2048
	ds_read_b128 v[130:133], v131 offset:3072
	s_add_u32 s2, s2, 0x20000
	s_addc_u32 s3, s3, 0
	s_mov_b32 m0, s47
	v_lshl_add_u64 v[176:177], s[2:3], 0, v[146:147]
	ds_read_b128 v[196:199], v187 offset:32768
	ds_read_b128 v[200:203], v187 offset:33792
	ds_read_b128 v[204:207], v187 offset:34816
	ds_read_b128 v[208:211], v187 offset:35840
	ds_read_b128 v[212:215], v187 offset:36864
	ds_read_b128 v[216:219], v187 offset:37888
	ds_read_b128 v[220:223], v187 offset:38912
	ds_read_b128 v[224:227], v187 offset:39936
	global_load_lds_dwordx4 v[176:177], off
	v_lshl_add_u64 v[176:177], s[2:3], 0, v[150:151]
	s_mov_b32 m0, s48
	s_nop 0
	global_load_lds_dwordx4 v[176:177], off
	s_waitcnt vmcnt(8)
	s_waitcnt lgkmcnt(0)
	s_barrier
; #define PG8_STAGE(bufoff, gbase, voff) do { _Pragma("unroll") for (int _i = 0; _i < 2; ++_i) \
;         __builtin_amdgcn_global_load_lds((const unsigned*)((const char*)(gbase) + (voff)[_i]), (PG8_LAS unsigned*)(lds + (bufoff) + ldsw + _i * 8192), 16, 0, 0); } while (0)
; #define PG8_LDA(dst, b, h) do { _Pragma("unroll") for (int m = 0; m < 4; ++m) _Pragma("unroll") for (int k = 0; k < 2; ++k) dst[m][k] = *(const PG8_LAS bf16x8*)(lds + PG8_SA(b, h) + aoff + m * 2048 + k * 1024); } while (0)
; #define PG8_LDB(dst, b, h) do { _Pragma("unroll") for (int n = 0; n < 2; ++n) _Pragma("unroll") for (int k = 0; k < 2; ++k) dst[n][k] = *(const PG8_LAS bf16x8*)(lds + PG8_SB(b, h) + boff + n * 2048 + k * 1024); } while (0)
; #define PG8_MMA(ai, bj, At, Bt) do { __builtin_amdgcn_s_setprio(1); _Pragma("unroll") for (int m = 0; m < 4; ++m) _Pragma("unroll") for (int n = 0; n < 2; ++n) _Pragma("unroll") for (int k = 0; k < 2; ++k) \
;         acc[ai][bj][m][n] = Gemm::i8 ? ::mfma16i8_g(Bt[n][k], At[m][k], acc[ai][bj][m][n]) : ::mfma16_g(Bt[n][k], At[m][k], acc[ai][bj][m][n]); __builtin_amdgcn_s_setprio(0); } while (0)
; #define PG8_WAIT_V(n) asm volatile("s_waitcnt vmcnt(" #n ")" ::: "memory")
; #define PG8_WAIT_L(n) asm volatile("s_waitcnt lgkmcnt(" #n ")" ::: "memory")
; template <class Epi, class Sched, class Gemm, bool ALIGN_EPI = false, bool SP2 = false>
; __device__ __forceinline__ void gemm_phase(PG8_LAS unsigned char* lds, const Gemm g, const Sched& S, const Epi& E) {
;     ...
;             PG8_LDA(At, 0, 1); PG8_STAGE(PG8_SB(0, 0), b2, voffB); PG8_STAGE(PG8_SB(0, 1), b2 + hB1, voffB1); PG8_STAGE(PG8_SA(0, 0), a2, voffA);
;             PG8_WAIT_V(8); PG8_WAIT_L(0); PG8_BAR; PG8_MMA(1, 0, At, B0); PG8_MMA(1, 1, At, B1); PG8_BAR; PG8_SCHED;
;             PG8_LDB(B0, 1, 0); PG8_LDB(B1, 1, 1); PG8_SCHED; PG8_LDA(At, 1, 0); PG8_STAGE(PG8_SA(0, 1), a2 + hstepA, voffA);
;             PG8_WAIT_V(8); PG8_WAIT_L(0); PG8_BAR; PG8_MMA(0, 0, At, B0); PG8_MMA(0, 1, At, B1); PG8_BAR; PG8_SCHED;
;             PG8_LDA(At, 1, 1); PG8_STAGE(PG8_SB(1, 0), b3, voffB); PG8_STAGE(PG8_SB(1, 1), b3 + hB1, voffB1); PG8_STAGE(PG8_SA(1, 0), a3, voffA);
;             PG8_WAIT_V(8);
;             if constexpr (epi_pre<Epi>::value) { if (last) E.pre(pre, cur, wr, wc, lane); }
;             PG8_WAIT_L(0); PG8_BAR; PG8_MMA(1, 0, At, B0); PG8_MMA(1, 1, At, B1); PG8_BAR; PG8_SCHED;
	s_setprio 1
	s_waitcnt lgkmcnt(0)
	v_mfma_i32_16x16x64_i8 v[228:231], v[160:163], v[196:199], v[126:129]
	v_mfma_i32_16x16x64_i8 v[126:129], v[172:175], v[200:203], v[228:231]
	v_mfma_i32_16x16x64_i8 v[232:235], v[188:191], v[196:199], v[122:125]
	v_mfma_i32_16x16x64_i8 v[236:239], v[160:163], v[204:207], v[110:113]
	v_mfma_i32_16x16x64_i8 v[240:243], v[188:191], v[204:207], v[106:109]
	v_mfma_i32_16x16x64_i8 v[244:247], v[160:163], v[212:215], v[94:97]
	v_mfma_i32_16x16x64_i8 v[248:251], v[188:191], v[212:215], v[90:93]
	v_mfma_i32_16x16x64_i8 v[228:231], v[160:163], v[220:223], v[78:81]
	v_mfma_i32_16x16x64_i8 v[74:77], v[188:191], v[220:223], v[74:77]
	v_mfma_i32_16x16x64_i8 v[122:125], v[192:195], v[200:203], v[232:235]
	v_mfma_i32_16x16x64_i8 v[110:113], v[172:175], v[208:211], v[236:239]
	v_mfma_i32_16x16x64_i8 v[106:109], v[192:195], v[208:211], v[240:243]
	v_mfma_i32_16x16x64_i8 v[94:97], v[172:175], v[216:219], v[244:247]
	v_mfma_i32_16x16x64_i8 v[90:93], v[192:195], v[216:219], v[248:251]
	v_mfma_i32_16x16x64_i8 v[78:81], v[172:175], v[224:227], v[228:231]
	v_mfma_i32_16x16x64_i8 v[74:77], v[192:195], v[224:227], v[74:77]
	s_setprio 0
	s_setprio 1
	v_mfma_i32_16x16x64_i8 v[228:231], v[134:137], v[196:199], v[118:121]
	v_mfma_i32_16x16x64_i8 v[118:121], v[138:141], v[200:203], v[228:231]
	v_mfma_i32_16x16x64_i8 v[232:235], v[142:145], v[196:199], v[114:117]
	v_mfma_i32_16x16x64_i8 v[236:239], v[134:137], v[204:207], v[102:105]
	v_mfma_i32_16x16x64_i8 v[240:243], v[142:145], v[204:207], v[98:101]
	v_mfma_i32_16x16x64_i8 v[244:247], v[134:137], v[212:215], v[86:89]
	v_mfma_i32_16x16x64_i8 v[248:251], v[142:145], v[212:215], v[82:85]
	v_mfma_i32_16x16x64_i8 v[196:199], v[134:137], v[220:223], v[70:73]
	v_mfma_i32_16x16x64_i8 v[66:69], v[142:145], v[220:223], v[66:69]
	v_mfma_i32_16x16x64_i8 v[114:117], v[130:133], v[200:203], v[232:235]
	v_mfma_i32_16x16x64_i8 v[102:105], v[138:141], v[208:211], v[236:239]
	v_mfma_i32_16x16x64_i8 v[98:101], v[130:133], v[208:211], v[240:243]
	v_mfma_i32_16x16x64_i8 v[86:89], v[138:141], v[216:219], v[244:247]
	v_mfma_i32_16x16x64_i8 v[82:85], v[130:133], v[216:219], v[248:251]
	v_mfma_i32_16x16x64_i8 v[70:73], v[138:141], v[224:227], v[196:199]
	v_mfma_i32_16x16x64_i8 v[66:69], v[130:133], v[224:227], v[66:69]
	s_setprio 0
	s_barrier
	s_add_i32 s2, s65, s43
	v_lshl_add_u64 v[164:165], v[164:165], 0, s[18:19]
	s_mov_b32 m0, s2
	ds_read_b128 v[196:199], v187 offset:49152
	ds_read_b128 v[200:203], v187 offset:50176
	ds_read_b128 v[204:207], v187 offset:51200
	ds_read_b128 v[208:211], v187 offset:52224
	ds_read_b128 v[212:215], v187 offset:53248
	ds_read_b128 v[216:219], v187 offset:54272
	ds_read_b128 v[220:223], v187 offset:55296
	ds_read_b128 v[224:227], v187 offset:56320
	global_load_lds_dwordx4 v[164:165], off
	s_add_i32 m0, s2, 0x2000
	s_add_u32 s2, s40, 0x2080
	v_lshl_add_u64 v[164:165], v[166:167], 0, s[18:19]
	s_addc_u32 s3, s41, 0
	s_add_i32 s40, s66, s43
	global_load_lds_dwordx4 v[164:165], off
	v_lshl_add_u64 v[164:165], s[2:3], 0, v[148:149]
	s_mov_b32 m0, s40
	s_nop 0
	global_load_lds_dwordx4 v[164:165], off
	v_lshl_add_u64 v[164:165], s[2:3], 0, v[152:153]
	s_add_i32 m0, s40, 0x2000
	s_nop 0
	global_load_lds_dwordx4 v[164:165], off
	v_lshl_add_u64 v[164:165], v[168:169], 0, s[18:19]
	s_mov_b32 m0, s51
	s_nop 0
	global_load_lds_dwordx4 v[164:165], off
	v_lshl_add_u64 v[164:165], v[170:171], 0, s[18:19]
	s_mov_b32 m0, s52
	s_nop 0
	global_load_lds_dwordx4 v[164:165], off
	s_waitcnt vmcnt(8)
	s_waitcnt lgkmcnt(0)
	s_barrier
	s_setprio 1
	s_waitcnt lgkmcnt(0)
	v_mfma_i32_16x16x64_i8 v[164:167], v[160:163], v[196:199], v[62:65]
	v_mfma_i32_16x16x64_i8 v[62:65], v[172:175], v[200:203], v[164:167]
	v_mfma_i32_16x16x64_i8 v[168:171], v[188:191], v[196:199], v[58:61]
	v_mfma_i32_16x16x64_i8 v[228:231], v[160:163], v[204:207], v[46:49]
	v_mfma_i32_16x16x64_i8 v[232:235], v[188:191], v[204:207], v[42:45]
	v_mfma_i32_16x16x64_i8 v[236:239], v[160:163], v[212:215], v[30:33]
	v_mfma_i32_16x16x64_i8 v[240:243], v[188:191], v[212:215], v[26:29]
	v_mfma_i32_16x16x64_i8 v[164:167], v[160:163], v[220:223], v[14:17]
	v_mfma_i32_16x16x64_i8 v[10:13], v[188:191], v[220:223], v[10:13]
	v_mfma_i32_16x16x64_i8 v[58:61], v[192:195], v[200:203], v[168:171]
	v_mfma_i32_16x16x64_i8 v[46:49], v[172:175], v[208:211], v[228:231]
	v_mfma_i32_16x16x64_i8 v[42:45], v[192:195], v[208:211], v[232:235]
	v_mfma_i32_16x16x64_i8 v[30:33], v[172:175], v[216:219], v[236:239]
	v_mfma_i32_16x16x64_i8 v[26:29], v[192:195], v[216:219], v[240:243]
	v_mfma_i32_16x16x64_i8 v[14:17], v[172:175], v[224:227], v[164:167]
	v_mfma_i32_16x16x64_i8 v[10:13], v[192:195], v[224:227], v[10:13]
	s_setprio 0
	s_setprio 1
	v_mfma_i32_16x16x64_i8 v[160:163], v[134:137], v[196:199], v[54:57]
	v_mfma_i32_16x16x64_i8 v[54:57], v[138:141], v[200:203], v[160:163]
	v_mfma_i32_16x16x64_i8 v[164:167], v[142:145], v[196:199], v[50:53]
	v_mfma_i32_16x16x64_i8 v[168:171], v[134:137], v[204:207], v[38:41]
	v_mfma_i32_16x16x64_i8 v[172:175], v[142:145], v[204:207], v[34:37]
	v_mfma_i32_16x16x64_i8 v[188:191], v[134:137], v[212:215], v[22:25]
	v_mfma_i32_16x16x64_i8 v[192:195], v[142:145], v[212:215], v[18:21]
	v_mfma_i32_16x16x64_i8 v[160:163], v[134:137], v[220:223], v[6:9]
	v_mfma_i32_16x16x64_i8 v[2:5], v[142:145], v[220:223], v[2:5]
	v_mfma_i32_16x16x64_i8 v[50:53], v[130:133], v[200:203], v[164:167]
	v_mfma_i32_16x16x64_i8 v[38:41], v[138:141], v[208:211], v[168:171]
	v_mfma_i32_16x16x64_i8 v[34:37], v[130:133], v[208:211], v[172:175]
	v_mfma_i32_16x16x64_i8 v[22:25], v[138:141], v[216:219], v[188:191]
	v_mfma_i32_16x16x64_i8 v[18:21], v[130:133], v[216:219], v[192:195]
	v_mfma_i32_16x16x64_i8 v[6:9], v[138:141], v[224:227], v[160:163]
	v_mfma_i32_16x16x64_i8 v[2:5], v[130:133], v[224:227], v[2:5]
	s_setprio 0
	s_barrier
; #define PG8_BAR __builtin_amdgcn_s_barrier()
;     __device__ __forceinline__ void operator()(const f32x4 (&acc)[2][2][4][2], const Unit& u, int wr, int wc, int fr, int fq) const {
;         asm volatile("" : "+v"(fr), "+v"(fq));
;         const int row0 = u.pm * BM + wr * 64 + fr, col0 = u.pn * BM + wc * 64 + 16 * fq;
;         const int gn = u.pn >> 2, gbase = (gn < 3) ? 3072 + 1024 * gn : 0;
;         f32x4 bv[2][2];
; #pragma unroll
;         for (int bj = 0; bj < 2; ++bj)
; #pragma unroll
;             for (int n = 0; n < 2; ++n) bv[bj][n] = *(const f32x4*)(bias + col0 + 8 * bj + 4 * n) * -1.44269504f;
;         f32x4 wv[2][2];
; #pragma unroll
;         for (int bj = 0; bj < 2; ++bj)
; #pragma unroll
;             for (int n = 0; n < 2; ++n) wv[bj][n] = *(const f32x4*)(SW + col0 + 8 * bj + 4 * n) * -1.44269504f;
;         float rsv[8];
; #pragma unroll
;         for (int i = 0; i < 8; ++i) rsv[i] = SH[row0 + (i >> 2) * HALF + (i & 3) * 16];
; template <class Epi, class Sched, class Gemm, bool ALIGN_EPI = false, bool SP2 = false>
; __device__ __forceinline__ void gemm_phase(PG8_LAS unsigned char* lds, const Gemm g, const Sched& S, const Epi& E) {
;     ...
;         if constexpr (ALIGN_EPI) { if (wr == 0) PG8_BAR; }
	s_add_i32 s64, s64, 2
	s_add_u32 s62, s62, 0x100
	s_addc_u32 s63, s63, 0
	s_add_u32 s0, s0, 0x100
	s_addc_u32 s1, s1, 0
	s_cmp_gt_u32 s64, 5
	s_cbranch_scc0 .LBB0_2552
	s_lshl_b32 s0, s59, 8
	v_mov_b32_e32 v154, v1
	v_mov_b32_e32 v130, v179
	s_or_b32 s0, s0, s53
	v_cvt_f32_i32_e32 v212, v122
	v_lshl_add_u32 v144, v130, 4, s0
	s_lshl_b32 s0, s38, 8
	v_ashrrev_i32_e32 v145, 31, v144
	s_add_i32 s0, s0, s50
	v_lshlrev_b64 v[142:143], 2, v[144:145]
	v_add_u32_e32 v164, s0, v154
	v_lshl_add_u64 v[160:161], s[14:15], 0, v[142:143]
	v_ashrrev_i32_e32 v165, 31, v164
	global_load_dwordx4 v[130:133], v[160:161], off
	global_load_dwordx4 v[134:137], v[160:161], off offset:16
	global_load_dwordx4 v[138:141], v[160:161], off offset:32
	s_nop 0
	global_load_dwordx4 v[160:163], v[160:161], off offset:48
	v_lshl_add_u64 v[142:143], s[16:17], 0, v[142:143]
	v_lshl_add_u64 v[170:171], v[164:165], 2, s[12:13]
	global_load_dwordx4 v[166:169], v[142:143], off
	global_load_dwordx4 v[194:197], v[142:143], off offset:16
	global_load_dwordx4 v[198:201], v[142:143], off offset:32
	global_load_dwordx4 v[202:205], v[142:143], off offset:48
	global_load_dword v206, v[170:171], off
	global_load_dword v188, v[170:171], off offset:64
	global_load_dword v186, v[170:171], off offset:128
	global_load_dword v184, v[170:171], off offset:192
	global_load_dword v182, v[170:171], off offset:512
	global_load_dword v180, v[170:171], off offset:576
	global_load_dword v178, v[170:171], off offset:640
	global_load_dword v122, v[170:171], off offset:704
	s_ashr_i32 s0, s59, 2
	s_lshl_b32 s1, s0, 10
	v_mov_b64_e32 v[142:143], s[10:11]
	s_add_i32 s2, s1, 0xc00
	v_cvt_f32_i32_e32 v209, v127
	v_cvt_f32_i32_e32 v208, v126
	v_cvt_f32_i32_e32 v215, v125
	v_cvt_f32_i32_e32 v214, v124
	s_cmp_lt_i32 s0, 3
	v_mad_i64_i32 v[124:125], s[0:1], v164, s57, v[142:143]
	s_cselect_b32 s0, s2, 0
	v_cvt_f32_i32_e32 v211, v129
	v_cvt_f32_i32_e32 v210, v128
	s_ashr_i32 s1, s0, 31
	v_cvt_f32_i32_e32 v115, v115
	v_cvt_f32_i32_e32 v114, v114
	v_cvt_f32_i32_e32 v99, v99
	v_cvt_f32_i32_e32 v98, v98
	v_cvt_f32_i32_e32 v83, v83
	v_cvt_f32_i32_e32 v82, v82
	v_cvt_f32_i32_e32 v67, v67
	v_cvt_f32_i32_e32 v66, v66
	v_cvt_f32_i32_e32 v51, v51
	v_cvt_f32_i32_e32 v50, v50
	v_cvt_f32_i32_e32 v35, v35
	v_cvt_f32_i32_e32 v34, v34
	v_cvt_f32_i32_e32 v19, v19
	v_cvt_f32_i32_e32 v18, v18
	v_and_b32_e32 v154, 0x3f0, v144
	v_lshl_add_u64 v[124:125], v[124:125], 0, s[0:1]
	v_cvt_f32_i32_e32 v117, v117
	v_cvt_f32_i32_e32 v116, v116
	v_cvt_f32_i32_e32 v111, v111
	v_cvt_f32_i32_e32 v110, v110
	v_cvt_f32_i32_e32 v101, v101
	v_cvt_f32_i32_e32 v100, v100
	v_cvt_f32_i32_e32 v95, v95
	v_cvt_f32_i32_e32 v94, v94
	v_cvt_f32_i32_e32 v85, v85
	v_cvt_f32_i32_e32 v84, v84
	v_cvt_f32_i32_e32 v79, v79
	v_cvt_f32_i32_e32 v78, v78
	v_cvt_f32_i32_e32 v69, v69
	v_cvt_f32_i32_e32 v68, v68
	v_cvt_f32_i32_e32 v63, v63
	v_cvt_f32_i32_e32 v62, v62
	v_cvt_f32_i32_e32 v53, v53
	v_cvt_f32_i32_e32 v52, v52
	v_cvt_f32_i32_e32 v47, v47
	v_cvt_f32_i32_e32 v46, v46
	v_cvt_f32_i32_e32 v37, v37
	v_cvt_f32_i32_e32 v36, v36
	v_cvt_f32_i32_e32 v31, v31
	v_cvt_f32_i32_e32 v30, v30
	v_cvt_f32_i32_e32 v21, v21
	v_cvt_f32_i32_e32 v20, v20
	v_cvt_f32_i32_e32 v15, v15
	v_cvt_f32_i32_e32 v14, v14
	v_add_u32_e32 v207, 32, v164
	v_lshl_add_u64 v[216:217], v[124:125], 0, v[154:155]
	v_add_u32_e32 v189, 0xa0, v164
	v_cvt_f32_i32_e32 v213, v123
	v_add_u32_e32 v123, 0xb0, v164
	v_cvt_f32_i32_e32 v119, v119
	v_cvt_f32_i32_e32 v118, v118
	v_cvt_f32_i32_e32 v109, v109
	v_cvt_f32_i32_e32 v108, v108
	v_cvt_f32_i32_e32 v103, v103
	v_cvt_f32_i32_e32 v102, v102
	v_cvt_f32_i32_e32 v93, v93
	v_cvt_f32_i32_e32 v121, v121
	v_cvt_f32_i32_e32 v120, v120
	v_cvt_f32_i32_e32 v113, v113
	v_cvt_f32_i32_e32 v112, v112
	v_cvt_f32_i32_e32 v107, v107
	v_cvt_f32_i32_e32 v106, v106
	v_cvt_f32_i32_e32 v105, v105
	v_cvt_f32_i32_e32 v104, v104
	v_cvt_f32_i32_e32 v92, v92
	v_cvt_f32_i32_e32 v87, v87
	v_cvt_f32_i32_e32 v86, v86
	v_cvt_f32_i32_e32 v97, v97
	v_cvt_f32_i32_e32 v96, v96
	v_cvt_f32_i32_e32 v91, v91
	v_cvt_f32_i32_e32 v90, v90
	v_cvt_f32_i32_e32 v89, v89
	v_cvt_f32_i32_e32 v88, v88
	v_cvt_f32_i32_e32 v77, v77
	v_cvt_f32_i32_e32 v76, v76
	v_cvt_f32_i32_e32 v71, v71
	v_cvt_f32_i32_e32 v70, v70
	v_cvt_f32_i32_e32 v81, v81
	v_cvt_f32_i32_e32 v80, v80
	v_cvt_f32_i32_e32 v75, v75
	v_cvt_f32_i32_e32 v74, v74
	v_cvt_f32_i32_e32 v73, v73
	v_cvt_f32_i32_e32 v72, v72
	v_cvt_f32_i32_e32 v61, v61
	v_cvt_f32_i32_e32 v60, v60
	v_cvt_f32_i32_e32 v55, v55
	v_cvt_f32_i32_e32 v54, v54
	v_cvt_f32_i32_e32 v65, v65
	v_cvt_f32_i32_e32 v64, v64
	v_cvt_f32_i32_e32 v59, v59
	v_cvt_f32_i32_e32 v58, v58
	v_cvt_f32_i32_e32 v57, v57
	v_cvt_f32_i32_e32 v56, v56
	v_cvt_f32_i32_e32 v45, v45
	v_cvt_f32_i32_e32 v44, v44
	v_cvt_f32_i32_e32 v39, v39
	v_cvt_f32_i32_e32 v38, v38
	v_cvt_f32_i32_e32 v49, v49
	v_cvt_f32_i32_e32 v48, v48
	v_cvt_f32_i32_e32 v43, v43
	v_cvt_f32_i32_e32 v42, v42
	v_cvt_f32_i32_e32 v41, v41
	v_cvt_f32_i32_e32 v40, v40
	v_cvt_f32_i32_e32 v29, v29
	v_cvt_f32_i32_e32 v28, v28
	v_cvt_f32_i32_e32 v23, v23
	v_cvt_f32_i32_e32 v22, v22
	v_cvt_f32_i32_e32 v33, v33
	v_cvt_f32_i32_e32 v32, v32
	v_cvt_f32_i32_e32 v27, v27
	v_cvt_f32_i32_e32 v26, v26
	v_cvt_f32_i32_e32 v25, v25
	v_cvt_f32_i32_e32 v24, v24
	v_cvt_f32_i32_e32 v7, v7
	v_cvt_f32_i32_e32 v6, v6
	v_cvt_f32_i32_e32 v3, v3
	v_cvt_f32_i32_e32 v2, v2
	v_cvt_f32_i32_e32 v17, v17
	v_cvt_f32_i32_e32 v16, v16
	v_cvt_f32_i32_e32 v11, v11
	v_cvt_f32_i32_e32 v13, v13
	v_cvt_f32_i32_e32 v12, v12
	v_cvt_f32_i32_e32 v10, v10
	v_cvt_f32_i32_e32 v9, v9
	v_cvt_f32_i32_e32 v8, v8
	v_cvt_f32_i32_e32 v5, v5
	v_cvt_f32_i32_e32 v4, v4
	s_and_b64 vcc, exec, s[20:21]
	s_cbranch_vccz .LBB0_2555
	s_barrier

;     __device__ bool next(int i, Unit& u) const { const bool ok = StaticOrder::next(i >> 2, u); u.sub = i & 3; return ok; }
; template <class Epi, class Sched, class Gemm, bool ALIGN_EPI = false, bool SP2 = false>
; __device__ __forceinline__ void gemm_phase(PG8_LAS unsigned char* lds, const Gemm g, const Sched& S, const Epi& E) {
;     ...
;         const bool has_next = S.next(ui + 1, nxt);
;         const char* nA = has_next ? (const char*)g.A + (size_t)nxt.pm * tstepA + (size_t)nxt.sub * g.a_sub : cA; const char* nB = has_next ? (const char*)g.Bt + (size_t)nxt.pn * tstepB + (size_t)nxt.sub * g.b_sub : cB;
;     ...
;         if constexpr (!epi_chain<Epi>::value) {
; #pragma unroll
;         for (int a = 0; a < 2; ++a)
; #pragma unroll
;             for (int b = 0; b < 2; ++b)
; #pragma unroll
;                 for (int m = 0; m < 4; ++m)
; #pragma unroll
;                     for (int n = 0; n < 2; ++n) acc[a][b][m][n] = (f32x4){0.f, 0.f, 0.f, 0.f};
;         }
;         cur = nxt; cA = nA; cB = nB; ++ui;
.LBB0_2729:
	s_ashr_i32 s39, s38, 31
	s_lshl_b64 s[40:41], s[38:39], 19
	s_add_u32 s40, s50, s40
	s_addc_u32 s41, s51, s41
	s_and_b64 s[42:43], s[0:1], exec
	s_cselect_b32 s5, s41, s47
	s_cselect_b32 s39, s40, s46
	s_ashr_i32 s37, s36, 31
	s_lshl_b64 s[42:43], s[36:37], 19
	s_add_u32 s42, s52, s42
	s_addc_u32 s43, s53, s43
	s_and_b64 s[48:49], s[0:1], exec
	s_cselect_b32 s37, s43, s3
	s_cselect_b32 s45, s42, s2
	s_add_u32 s75, s2, 0x100
	s_addc_u32 s76, s3, 0
	s_add_u32 s46, s46, 0x40080
	v_mov_b32_e32 v0, 0
	s_addc_u32 s47, s47, 0
	s_mov_b32 s77, -2
	v_mov_b32_e32 v1, v0
	v_mov_b64_e32 v[2:3], 0
	v_mov_b64_e32 v[4:5], 0
	v_mov_b64_e32 v[6:7], 0
	v_mov_b64_e32 v[16:17], 0
	v_mov_b64_e32 v[18:19], 0
	v_mov_b64_e32 v[20:21], 0
	v_mov_b64_e32 v[22:23], 0
	v_mov_b64_e32 v[32:33], 0
	v_mov_b64_e32 v[34:35], 0
	v_mov_b64_e32 v[36:37], 0
	v_mov_b64_e32 v[38:39], 0
	v_mov_b64_e32 v[48:49], 0
	v_mov_b64_e32 v[50:51], 0
	v_mov_b64_e32 v[52:53], 0
	v_mov_b64_e32 v[54:55], 0
	v_mov_b64_e32 v[8:9], 0
	v_mov_b64_e32 v[10:11], 0
	v_mov_b64_e32 v[12:13], 0
	v_mov_b64_e32 v[14:15], 0
	v_mov_b64_e32 v[24:25], 0
	v_mov_b64_e32 v[26:27], 0
	v_mov_b64_e32 v[28:29], 0
	v_mov_b64_e32 v[30:31], 0
	v_mov_b64_e32 v[40:41], 0
	v_mov_b64_e32 v[42:43], 0
	v_mov_b64_e32 v[44:45], 0
	v_mov_b64_e32 v[46:47], 0
	v_mov_b64_e32 v[56:57], 0
	v_mov_b64_e32 v[58:59], 0
	v_mov_b64_e32 v[60:61], 0
	v_mov_b64_e32 v[62:63], 0
	v_mov_b64_e32 v[64:65], 0
	v_mov_b64_e32 v[66:67], 0
	v_mov_b64_e32 v[68:69], 0
	v_mov_b64_e32 v[70:71], 0
	v_mov_b64_e32 v[80:81], 0
	v_mov_b64_e32 v[82:83], 0
	v_mov_b64_e32 v[84:85], 0
	v_mov_b64_e32 v[86:87], 0
	v_mov_b64_e32 v[96:97], 0
	v_mov_b64_e32 v[98:99], 0
	v_mov_b64_e32 v[100:101], 0
	v_mov_b64_e32 v[102:103], 0
	v_mov_b64_e32 v[112:113], 0
	v_mov_b64_e32 v[114:115], 0
	v_mov_b64_e32 v[116:117], 0
	v_mov_b64_e32 v[118:119], 0
	v_mov_b64_e32 v[72:73], 0
	v_mov_b64_e32 v[74:75], 0
	v_mov_b64_e32 v[76:77], 0
	v_mov_b64_e32 v[78:79], 0
	v_mov_b64_e32 v[88:89], 0
	v_mov_b64_e32 v[90:91], 0
	v_mov_b64_e32 v[92:93], 0
	v_mov_b64_e32 v[94:95], 0
	v_mov_b64_e32 v[104:105], 0
	v_mov_b64_e32 v[106:107], 0
	v_mov_b64_e32 v[108:109], 0
	v_mov_b64_e32 v[110:111], 0
	v_mov_b64_e32 v[120:121], 0
	v_mov_b64_e32 v[122:123], 0
	v_mov_b64_e32 v[124:125], 0
	v_mov_b64_e32 v[126:127], 0
	s_nop 0
